# combo2: B0 reads early + lgkmcnt(0) and setprio 1 before the pre-MFMA barrier + setprio 0 and prep after the post-MFMA barrier
# speedup vs baseline: 1.0256x; 1.0154x over previous
; #define PG8_STAGE(bufoff, gbase, voff) do { _Pragma("unroll") for (int _i = 0; _i < 2; ++_i) \
;     __builtin_amdgcn_global_load_lds((const unsigned*)((const char*)(gbase) + (voff)[_i]), (LAS unsigned*)(lds + (bufoff) + ldsw + _i * 8192), 16, 0, 0); } while (0)
; #define PG8_LDA(dst, b, h) do { _Pragma("unroll") for (int m = 0; m < 4; ++m) _Pragma("unroll") for (int k = 0; k < 2; ++k) dst[m][k] = *(const LAS bf16x8*)(lds + PG8_SA(b, h) + aoff + m * 2048 + k * 1024); } while (0)
; #define PG8_LDB(dst, b, h) do { _Pragma("unroll") for (int n = 0; n < 2; ++n) _Pragma("unroll") for (int k = 0; k < 2; ++k) dst[n][k] = *(const LAS bf16x8*)(lds + PG8_SB(b, h) + boff + n * 2048 + k * 1024); } while (0)
; #define PG8_MMA(ai, bj, At, Bt) do { __builtin_amdgcn_s_setprio(1); _Pragma("unroll") for (int m = 0; m < 4; ++m) _Pragma("unroll") for (int n = 0; n < 2; ++n) _Pragma("unroll") for (int k = 0; k < 2; ++k) \
;     acc[ai][bj][m][n] = __builtin_amdgcn_mfma_f32_16x16x32_bf16(Bt[n][k], At[m][k], acc[ai][bj][m][n], 0, 0, 0); __builtin_amdgcn_s_setprio(0); } while (0)
; #define PG8_WAIT_L(n) asm volatile("s_waitcnt lgkmcnt(" #n ")" ::: "memory")
; #define PG8_BAR __builtin_amdgcn_s_barrier()
; #define PG8_SCHED __builtin_amdgcn_sched_barrier(0)
; template <class Epi, class Sched = StaticOrder>
; DI void gemm_phase(LAS unsigned char* lds, const Gemm g, const Sched& S, const Epi& E) {
;     ...
;     for (int t = 0; t < nt; t += 2) {
;       const bool last = (t == nt - 2);
;       const char* a1 = cA + (size_t)(t + 1) * kstep;
;       const char* a2 = last ? nA : cA + (size_t)(t + 2) * kstep; const char* b2 = last ? nB : cB + (size_t)(t + 2) * kstep;
;       const char* a3 = a2 + kstep; const char* b3 = b2 + kstep;
;       PG8_LDB(B0, 0, 0); PG8_SCHED; PG8_LDA(At, 0, 0); PG8_STAGE(PG8_SA(1, 1), a1 + hstep, voffA);
;       PG8_WAIT_L(8); PG8_BAR; PG8_WAIT_L(0); PG8_MMA(0, 0, At, B0); PG8_BAR; PG8_SCHED;
;       PG8_LDB(B1, 0, 1); PG8_STAGE(PG8_SB(0, 0), b2, voffB);
;       PG8_BAR; PG8_WAIT_L(0); PG8_MMA(0, 1, At, B1); PG8_BAR;
;       PG8_LDA(At, 0, 1); PG8_STAGE(PG8_SA(0, 0), a2, voffA);
;       PG8_BAR; PG8_WAIT_L(0); PG8_MMA(1, 0, At, B0); PG8_BAR; PG8_SCHED;
.LBB0_346:
	s_add_u32 s8, s6, 0xfff80080
	s_addc_u32 s9, s7, -1
	s_cmp_eq_u32 s52, 28
	s_cselect_b32 s11, s31, s9
	s_cselect_b32 s10, s42, s8
	s_cselect_b32 s9, s29, s45
	s_cselect_b32 s8, s43, s44
	v_lshl_add_u64 v[202:203], s[6:7], 0, v[146:147]
	s_add_i32 m0, s48, 0xc000
	ds_read_b128 v[162:165], v174
	ds_read_b128 v[166:169], v174 offset:1024
	ds_read_b128 v[178:181], v174 offset:2048
	ds_read_b128 v[182:185], v174 offset:3072
	ds_read_b128 v[186:189], v174 offset:4096
	ds_read_b128 v[190:193], v174 offset:5120
	ds_read_b128 v[194:197], v174 offset:6144
	ds_read_b128 v[198:201], v174 offset:7168
	global_load_lds_dwordx4 v[202:203], off
	v_lshl_add_u64 v[202:203], s[6:7], 0, v[148:149]
	s_add_i32 m0, s48, 0xe000
	s_nop 0
	global_load_lds_dwordx4 v[202:203], off
	s_waitcnt lgkmcnt(0)
	s_setprio 1
	s_barrier
	v_mfma_f32_16x16x32_bf16 v[124:127], v[128:131], v[162:165], v[124:127]
	v_mfma_f32_16x16x32_bf16 v[120:123], v[154:157], v[162:165], v[120:123]
	v_mfma_f32_16x16x32_bf16 v[108:111], v[128:131], v[178:181], v[108:111]
	v_mfma_f32_16x16x32_bf16 v[104:107], v[154:157], v[178:181], v[104:107]
	v_mfma_f32_16x16x32_bf16 v[100:103], v[128:131], v[186:189], v[100:103]
	v_mfma_f32_16x16x32_bf16 v[92:95], v[154:157], v[186:189], v[92:95]
	v_mfma_f32_16x16x32_bf16 v[84:87], v[128:131], v[194:197], v[84:87]
	v_mfma_f32_16x16x32_bf16 v[76:79], v[154:157], v[194:197], v[76:79]
	v_mfma_f32_16x16x32_bf16 v[124:127], v[132:135], v[166:169], v[124:127]
	v_mfma_f32_16x16x32_bf16 v[120:123], v[158:161], v[166:169], v[120:123]
	v_mfma_f32_16x16x32_bf16 v[108:111], v[132:135], v[182:185], v[108:111]
	v_mfma_f32_16x16x32_bf16 v[104:107], v[158:161], v[182:185], v[104:107]
	v_mfma_f32_16x16x32_bf16 v[100:103], v[132:135], v[190:193], v[100:103]
	v_mfma_f32_16x16x32_bf16 v[92:95], v[158:161], v[190:193], v[92:95]
	v_mfma_f32_16x16x32_bf16 v[84:87], v[132:135], v[198:201], v[84:87]
	v_mfma_f32_16x16x32_bf16 v[76:79], v[158:161], v[198:201], v[76:79]
	s_barrier
	s_setprio 0
	s_add_i32 s53, s65, s41
	v_lshl_add_u64 v[220:221], s[8:9], 0, v[140:141]
	s_mov_b32 m0, s53
	ds_read_b128 v[202:205], v175
	ds_read_b128 v[206:209], v175 offset:1024
	ds_read_b128 v[212:215], v175 offset:2048
	ds_read_b128 v[216:219], v175 offset:3072
	global_load_lds_dwordx4 v[220:221], off
	v_lshl_add_u64 v[222:223], s[8:9], 0, v[136:137]
	s_add_i32 m0, s53, 0x2000
	s_nop 0
	global_load_lds_dwordx4 v[222:223], off
	s_waitcnt lgkmcnt(0)
	s_setprio 1
	s_barrier
	v_mfma_f32_16x16x32_bf16 v[116:119], v[202:205], v[162:165], v[116:119]
	v_mfma_f32_16x16x32_bf16 v[112:115], v[212:215], v[162:165], v[112:115]
	v_mfma_f32_16x16x32_bf16 v[96:99], v[202:205], v[178:181], v[96:99]
	v_mfma_f32_16x16x32_bf16 v[88:91], v[212:215], v[178:181], v[88:91]
	v_mfma_f32_16x16x32_bf16 v[80:83], v[202:205], v[186:189], v[80:83]
	v_mfma_f32_16x16x32_bf16 v[72:75], v[212:215], v[186:189], v[72:75]
	v_mfma_f32_16x16x32_bf16 v[68:71], v[202:205], v[194:197], v[68:71]
	v_mfma_f32_16x16x32_bf16 v[64:67], v[212:215], v[194:197], v[64:67]
	v_mfma_f32_16x16x32_bf16 v[116:119], v[206:209], v[166:169], v[116:119]
	v_mfma_f32_16x16x32_bf16 v[112:115], v[216:219], v[166:169], v[112:115]
	v_mfma_f32_16x16x32_bf16 v[96:99], v[206:209], v[182:185], v[96:99]
	v_mfma_f32_16x16x32_bf16 v[88:91], v[216:219], v[182:185], v[88:91]
	v_mfma_f32_16x16x32_bf16 v[80:83], v[206:209], v[190:193], v[80:83]
	v_mfma_f32_16x16x32_bf16 v[72:75], v[216:219], v[190:193], v[72:75]
	v_mfma_f32_16x16x32_bf16 v[68:71], v[206:209], v[198:201], v[68:71]
	v_mfma_f32_16x16x32_bf16 v[64:67], v[216:219], v[198:201], v[64:67]
	s_barrier
	s_setprio 0
	s_mov_b32 m0, s48
	v_lshl_add_u64 v[224:225], s[10:11], 0, v[142:143]
	ds_read_b128 v[162:165], v174 offset:16384
	ds_read_b128 v[166:169], v174 offset:17408
	ds_read_b128 v[178:181], v174 offset:18432
	ds_read_b128 v[182:185], v174 offset:19456
	ds_read_b128 v[186:189], v174 offset:20480
	ds_read_b128 v[190:193], v174 offset:21504
	ds_read_b128 v[194:197], v174 offset:22528
	ds_read_b128 v[198:201], v174 offset:23552
	global_load_lds_dwordx4 v[224:225], off
	v_lshl_add_u64 v[226:227], s[10:11], 0, v[138:139]
	s_mov_b32 m0, s49
	s_nop 0
	global_load_lds_dwordx4 v[226:227], off
	s_waitcnt vmcnt(10)
	s_waitcnt lgkmcnt(0)
	s_setprio 1
	s_barrier
	v_mfma_f32_16x16x32_bf16 v[60:63], v[128:131], v[162:165], v[60:63]
	v_mfma_f32_16x16x32_bf16 v[56:59], v[154:157], v[162:165], v[56:59]
	v_mfma_f32_16x16x32_bf16 v[52:55], v[128:131], v[178:181], v[52:55]
	v_mfma_f32_16x16x32_bf16 v[44:47], v[154:157], v[178:181], v[44:47]
	v_mfma_f32_16x16x32_bf16 v[36:39], v[128:131], v[186:189], v[36:39]
	v_mfma_f32_16x16x32_bf16 v[28:31], v[154:157], v[186:189], v[28:31]
	v_mfma_f32_16x16x32_bf16 v[20:23], v[128:131], v[194:197], v[20:23]
	v_mfma_f32_16x16x32_bf16 v[12:15], v[154:157], v[194:197], v[12:15]
	v_mfma_f32_16x16x32_bf16 v[60:63], v[132:135], v[166:169], v[60:63]
	v_mfma_f32_16x16x32_bf16 v[56:59], v[158:161], v[166:169], v[56:59]
	v_mfma_f32_16x16x32_bf16 v[52:55], v[132:135], v[182:185], v[52:55]
	v_mfma_f32_16x16x32_bf16 v[44:47], v[158:161], v[182:185], v[44:47]
	v_mfma_f32_16x16x32_bf16 v[36:39], v[132:135], v[190:193], v[36:39]
	v_mfma_f32_16x16x32_bf16 v[28:31], v[158:161], v[190:193], v[28:31]
	v_mfma_f32_16x16x32_bf16 v[20:23], v[132:135], v[198:201], v[20:23]
	v_mfma_f32_16x16x32_bf16 v[12:15], v[158:161], v[198:201], v[12:15]
	s_barrier
; #define PG8_STAGE(bufoff, gbase, voff) do { _Pragma("unroll") for (int _i = 0; _i < 2; ++_i) \
;     __builtin_amdgcn_global_load_lds((const unsigned*)((const char*)(gbase) + (voff)[_i]), (LAS unsigned*)(lds + (bufoff) + ldsw + _i * 8192), 16, 0, 0); } while (0)
; #define PG8_LDA(dst, b, h) do { _Pragma("unroll") for (int m = 0; m < 4; ++m) _Pragma("unroll") for (int k = 0; k < 2; ++k) dst[m][k] = *(const LAS bf16x8*)(lds + PG8_SA(b, h) + aoff + m * 2048 + k * 1024); } while (0)
; #define PG8_LDB(dst, b, h) do { _Pragma("unroll") for (int n = 0; n < 2; ++n) _Pragma("unroll") for (int k = 0; k < 2; ++k) dst[n][k] = *(const LAS bf16x8*)(lds + PG8_SB(b, h) + boff + n * 2048 + k * 1024); } while (0)
; #define PG8_MMA(ai, bj, At, Bt) do { __builtin_amdgcn_s_setprio(1); _Pragma("unroll") for (int m = 0; m < 4; ++m) _Pragma("unroll") for (int n = 0; n < 2; ++n) _Pragma("unroll") for (int k = 0; k < 2; ++k) \
;     acc[ai][bj][m][n] = __builtin_amdgcn_mfma_f32_16x16x32_bf16(Bt[n][k], At[m][k], acc[ai][bj][m][n], 0, 0, 0); __builtin_amdgcn_s_setprio(0); } while (0)
; #define PG8_WAIT_V(n) asm volatile("s_waitcnt vmcnt(" #n ")" ::: "memory")
; #define PG8_WAIT_L(n) asm volatile("s_waitcnt lgkmcnt(" #n ")" ::: "memory")
; #define PG8_BAR __builtin_amdgcn_s_barrier()
; #define PG8_SCHED __builtin_amdgcn_sched_barrier(0)
; template <class Epi, class Sched = StaticOrder>
; DI void gemm_phase(LAS unsigned char* lds, const Gemm g, const Sched& S, const Epi& E) {
;     ...
;       PG8_STAGE(PG8_SB(0, 1), b2 + hstep, voffB);
;       PG8_WAIT_V(6); PG8_BAR; PG8_MMA(1, 1, At, B1); PG8_BAR;
;       PG8_LDB(B0, 1, 0); PG8_SCHED; PG8_LDA(At, 1, 0); PG8_STAGE(PG8_SA(0, 1), a2 + hstep, voffA);
;       PG8_WAIT_L(8); PG8_BAR; PG8_WAIT_L(0); PG8_MMA(0, 0, At, B0); PG8_BAR; PG8_SCHED;
;       PG8_LDB(B1, 1, 1); PG8_STAGE(PG8_SB(1, 0), b3, voffB);
;       PG8_BAR; PG8_WAIT_L(0); PG8_MMA(0, 1, At, B1); PG8_BAR;
;       PG8_LDA(At, 1, 1); PG8_STAGE(PG8_SA(1, 0), a3, voffA);
;       PG8_BAR; PG8_WAIT_L(0); PG8_MMA(1, 0, At, B0); PG8_BAR; PG8_SCHED;
	s_setprio 0
	s_add_u32 s54, s8, 0x80000
	s_addc_u32 s55, s9, 0
	s_add_i32 s53, s72, s41
	v_lshl_add_u64 v[128:129], s[54:55], 0, v[140:141]
	s_mov_b32 m0, s53
	s_nop 0
	global_load_lds_dwordx4 v[128:129], off
	v_lshl_add_u64 v[128:129], s[54:55], 0, v[136:137]
	s_add_i32 m0, s53, 0x2000
	s_nop 0
	global_load_lds_dwordx4 v[128:129], off
	s_add_i32 s53, 0, 0x18000
	v_add_u32_e32 v158, s53, v171
	ds_read_b128 v[128:131], v158
	ds_read_b128 v[132:135], v158 offset:1024
	ds_read_b128 v[154:157], v158 offset:2048
	ds_read_b128 v[158:161], v158 offset:3072
	s_waitcnt vmcnt(6)
	s_setprio 1
	s_barrier
	v_mfma_f32_16x16x32_bf16 v[48:51], v[202:205], v[162:165], v[48:51]
	v_mfma_f32_16x16x32_bf16 v[40:43], v[212:215], v[162:165], v[40:43]
	v_mfma_f32_16x16x32_bf16 v[32:35], v[202:205], v[178:181], v[32:35]
	v_mfma_f32_16x16x32_bf16 v[24:27], v[212:215], v[178:181], v[24:27]
	v_mfma_f32_16x16x32_bf16 v[16:19], v[202:205], v[186:189], v[16:19]
	v_mfma_f32_16x16x32_bf16 v[8:11], v[212:215], v[186:189], v[8:11]
	v_mfma_f32_16x16x32_bf16 v[4:7], v[202:205], v[194:197], v[4:7]
	v_mfma_f32_16x16x32_bf16 v[0:3], v[212:215], v[194:197], v[0:3]
	v_mfma_f32_16x16x32_bf16 v[48:51], v[206:209], v[166:169], v[48:51]
	v_mfma_f32_16x16x32_bf16 v[40:43], v[216:219], v[166:169], v[40:43]
	v_mfma_f32_16x16x32_bf16 v[32:35], v[206:209], v[182:185], v[32:35]
	v_mfma_f32_16x16x32_bf16 v[24:27], v[216:219], v[182:185], v[24:27]
	v_mfma_f32_16x16x32_bf16 v[16:19], v[206:209], v[190:193], v[16:19]
	v_mfma_f32_16x16x32_bf16 v[8:11], v[216:219], v[190:193], v[8:11]
	v_mfma_f32_16x16x32_bf16 v[4:7], v[206:209], v[198:201], v[4:7]
	v_mfma_f32_16x16x32_bf16 v[0:3], v[216:219], v[198:201], v[0:3]
	s_barrier
	s_setprio 0
	s_add_u32 s10, s10, 0x80000
	s_addc_u32 s11, s11, 0
	s_mov_b32 m0, s50
	v_lshl_add_u64 v[202:203], s[10:11], 0, v[142:143]
	ds_read_b128 v[162:165], v174 offset:32768
	ds_read_b128 v[166:169], v174 offset:33792
	ds_read_b128 v[178:181], v174 offset:34816
	ds_read_b128 v[182:185], v174 offset:35840
	ds_read_b128 v[186:189], v174 offset:36864
	ds_read_b128 v[190:193], v174 offset:37888
	ds_read_b128 v[194:197], v174 offset:38912
	ds_read_b128 v[198:201], v174 offset:39936
	global_load_lds_dwordx4 v[202:203], off
	v_lshl_add_u64 v[202:203], s[10:11], 0, v[138:139]
	s_mov_b32 m0, s51
	s_nop 0
	global_load_lds_dwordx4 v[202:203], off
	s_waitcnt lgkmcnt(0)
	s_setprio 1
	s_barrier
	v_mfma_f32_16x16x32_bf16 v[124:127], v[128:131], v[162:165], v[124:127]
	v_mfma_f32_16x16x32_bf16 v[120:123], v[154:157], v[162:165], v[120:123]
	v_mfma_f32_16x16x32_bf16 v[108:111], v[128:131], v[178:181], v[108:111]
	v_mfma_f32_16x16x32_bf16 v[104:107], v[154:157], v[178:181], v[104:107]
	v_mfma_f32_16x16x32_bf16 v[100:103], v[128:131], v[186:189], v[100:103]
	v_mfma_f32_16x16x32_bf16 v[92:95], v[154:157], v[186:189], v[92:95]
	v_mfma_f32_16x16x32_bf16 v[84:87], v[128:131], v[194:197], v[84:87]
	v_mfma_f32_16x16x32_bf16 v[76:79], v[154:157], v[194:197], v[76:79]
	v_mfma_f32_16x16x32_bf16 v[124:127], v[132:135], v[166:169], v[124:127]
	v_mfma_f32_16x16x32_bf16 v[120:123], v[158:161], v[166:169], v[120:123]
	v_mfma_f32_16x16x32_bf16 v[108:111], v[132:135], v[182:185], v[108:111]
	v_mfma_f32_16x16x32_bf16 v[104:107], v[158:161], v[182:185], v[104:107]
	v_mfma_f32_16x16x32_bf16 v[100:103], v[132:135], v[190:193], v[100:103]
	v_mfma_f32_16x16x32_bf16 v[92:95], v[158:161], v[190:193], v[92:95]
	v_mfma_f32_16x16x32_bf16 v[84:87], v[132:135], v[198:201], v[84:87]
	v_mfma_f32_16x16x32_bf16 v[76:79], v[158:161], v[198:201], v[76:79]
	s_barrier
	s_setprio 0
	s_add_i32 s10, 0, 0x1c000
	s_add_i32 s11, s53, s41
	v_add_u32_e32 v177, s10, v171
	v_lshl_add_u64 v[220:221], v[220:221], 0, s[22:23]
	s_mov_b32 m0, s11
	ds_read_b128 v[202:205], v177
	ds_read_b128 v[206:209], v177 offset:1024
	ds_read_b128 v[212:215], v177 offset:2048
	ds_read_b128 v[216:219], v177 offset:3072
	global_load_lds_dwordx4 v[220:221], off
	v_lshl_add_u64 v[220:221], v[222:223], 0, s[22:23]
	s_add_i32 m0, s11, 0x2000
	s_nop 0
	global_load_lds_dwordx4 v[220:221], off
	s_waitcnt lgkmcnt(0)
	s_setprio 1
	s_barrier
	v_mfma_f32_16x16x32_bf16 v[116:119], v[202:205], v[162:165], v[116:119]
	v_mfma_f32_16x16x32_bf16 v[112:115], v[212:215], v[162:165], v[112:115]
	v_mfma_f32_16x16x32_bf16 v[96:99], v[202:205], v[178:181], v[96:99]
	v_mfma_f32_16x16x32_bf16 v[88:91], v[212:215], v[178:181], v[88:91]
	v_mfma_f32_16x16x32_bf16 v[80:83], v[202:205], v[186:189], v[80:83]
	v_mfma_f32_16x16x32_bf16 v[72:75], v[212:215], v[186:189], v[72:75]
	v_mfma_f32_16x16x32_bf16 v[68:71], v[202:205], v[194:197], v[68:71]
	v_mfma_f32_16x16x32_bf16 v[64:67], v[212:215], v[194:197], v[64:67]
	v_mfma_f32_16x16x32_bf16 v[116:119], v[206:209], v[166:169], v[116:119]
	v_mfma_f32_16x16x32_bf16 v[112:115], v[216:219], v[166:169], v[112:115]
	v_mfma_f32_16x16x32_bf16 v[96:99], v[206:209], v[182:185], v[96:99]
	v_mfma_f32_16x16x32_bf16 v[88:91], v[216:219], v[182:185], v[88:91]
	v_mfma_f32_16x16x32_bf16 v[80:83], v[206:209], v[190:193], v[80:83]
	v_mfma_f32_16x16x32_bf16 v[72:75], v[216:219], v[190:193], v[72:75]
	v_mfma_f32_16x16x32_bf16 v[68:71], v[206:209], v[198:201], v[68:71]
	v_mfma_f32_16x16x32_bf16 v[64:67], v[216:219], v[198:201], v[64:67]
	s_barrier
	s_setprio 0
	s_mov_b32 m0, s56
	v_lshl_add_u64 v[220:221], v[224:225], 0, s[22:23]
	ds_read_b128 v[162:165], v174 offset:49152
	ds_read_b128 v[166:169], v174 offset:50176
	ds_read_b128 v[178:181], v174 offset:51200
	ds_read_b128 v[182:185], v174 offset:52224
	ds_read_b128 v[186:189], v174 offset:53248
	ds_read_b128 v[190:193], v174 offset:54272
	ds_read_b128 v[194:197], v174 offset:55296
	ds_read_b128 v[198:201], v174 offset:56320
	global_load_lds_dwordx4 v[220:221], off
	v_lshl_add_u64 v[220:221], v[226:227], 0, s[22:23]
	s_mov_b32 m0, s57
	s_nop 0
	global_load_lds_dwordx4 v[220:221], off
	s_waitcnt vmcnt(10)
	s_waitcnt lgkmcnt(0)
	s_setprio 1
	s_barrier
; #define PG8_STAGE(bufoff, gbase, voff) do { _Pragma("unroll") for (int _i = 0; _i < 2; ++_i) \
;     __builtin_amdgcn_global_load_lds((const unsigned*)((const char*)(gbase) + (voff)[_i]), (LAS unsigned*)(lds + (bufoff) + ldsw + _i * 8192), 16, 0, 0); } while (0)
; #define PG8_MMA(ai, bj, At, Bt) do { __builtin_amdgcn_s_setprio(1); _Pragma("unroll") for (int m = 0; m < 4; ++m) _Pragma("unroll") for (int n = 0; n < 2; ++n) _Pragma("unroll") for (int k = 0; k < 2; ++k) \
;     acc[ai][bj][m][n] = __builtin_amdgcn_mfma_f32_16x16x32_bf16(Bt[n][k], At[m][k], acc[ai][bj][m][n], 0, 0, 0); __builtin_amdgcn_s_setprio(0); } while (0)
; #define PG8_WAIT_V(n) asm volatile("s_waitcnt vmcnt(" #n ")" ::: "memory")
; #define PG8_WAIT_L(n) asm volatile("s_waitcnt lgkmcnt(" #n ")" ::: "memory")
; #define PG8_BAR __builtin_amdgcn_s_barrier()
; #define PG8_SCHED __builtin_amdgcn_sched_barrier(0)
; DI float row_rstd(const float* ssq, int row, int fq) {
;   const f32x4 a = *(const f32x4*)(ssq + (size_t)row * 32 + fq * 8), b = *(const f32x4*)(ssq + (size_t)row * 32 + fq * 8 + 4);
;   float sm = ((a[0] + a[1]) + (a[2] + a[3])) + ((b[0] + b[1]) + (b[2] + b[3]));
;   sm += __shfl_xor(sm, 16); sm += __shfl_xor(sm, 32);
;   return rsqrtf(sm * (1.0f / 2048.f) + 1e-6f);
; }
; template <class Epi, class Sched = StaticOrder>
; DI void gemm_phase(LAS unsigned char* lds, const Gemm g, const Sched& S, const Epi& E) {
;     ...
;       PG8_BAR; PG8_WAIT_L(0); PG8_MMA(1, 0, At, B0); PG8_BAR; PG8_SCHED;
;       PG8_STAGE(PG8_SB(1, 1), b3 + hstep, voffB);
;       PG8_WAIT_V(6); PG8_BAR; PG8_MMA(1, 1, At, B1); PG8_BAR;
;     }
	v_mfma_f32_16x16x32_bf16 v[60:63], v[128:131], v[162:165], v[60:63]
	v_mfma_f32_16x16x32_bf16 v[56:59], v[154:157], v[162:165], v[56:59]
	v_mfma_f32_16x16x32_bf16 v[52:55], v[128:131], v[178:181], v[52:55]
	v_mfma_f32_16x16x32_bf16 v[44:47], v[154:157], v[178:181], v[44:47]
	v_mfma_f32_16x16x32_bf16 v[36:39], v[128:131], v[186:189], v[36:39]
	v_mfma_f32_16x16x32_bf16 v[28:31], v[154:157], v[186:189], v[28:31]
	v_mfma_f32_16x16x32_bf16 v[20:23], v[128:131], v[194:197], v[20:23]
	v_mfma_f32_16x16x32_bf16 v[12:15], v[154:157], v[194:197], v[12:15]
	v_mfma_f32_16x16x32_bf16 v[60:63], v[132:135], v[166:169], v[60:63]
	v_mfma_f32_16x16x32_bf16 v[56:59], v[158:161], v[166:169], v[56:59]
	v_mfma_f32_16x16x32_bf16 v[52:55], v[132:135], v[182:185], v[52:55]
	v_mfma_f32_16x16x32_bf16 v[44:47], v[158:161], v[182:185], v[44:47]
	v_mfma_f32_16x16x32_bf16 v[36:39], v[132:135], v[190:193], v[36:39]
	v_mfma_f32_16x16x32_bf16 v[28:31], v[158:161], v[190:193], v[28:31]
	v_mfma_f32_16x16x32_bf16 v[20:23], v[132:135], v[198:201], v[20:23]
	v_mfma_f32_16x16x32_bf16 v[12:15], v[158:161], v[198:201], v[12:15]
	s_barrier
	s_setprio 0
	s_add_u32 s8, s8, 0x80080
	s_addc_u32 s9, s9, 0
	s_add_i32 s10, s10, s41
	v_lshl_add_u64 v[128:129], s[8:9], 0, v[140:141]
	s_mov_b32 m0, s10
	s_nop 0
	global_load_lds_dwordx4 v[128:129], off
	v_lshl_add_u64 v[128:129], s[8:9], 0, v[136:137]
	s_add_i32 m0, s10, 0x2000
	s_nop 0
	global_load_lds_dwordx4 v[128:129], off
	ds_read_b128 v[128:131], v173
	ds_read_b128 v[132:135], v173 offset:1024
	ds_read_b128 v[154:157], v173 offset:2048
	ds_read_b128 v[158:161], v173 offset:3072
	s_waitcnt vmcnt(6)
	s_setprio 1
	s_barrier
	v_mfma_f32_16x16x32_bf16 v[48:51], v[202:205], v[162:165], v[48:51]
	v_mfma_f32_16x16x32_bf16 v[40:43], v[212:215], v[162:165], v[40:43]
	v_mfma_f32_16x16x32_bf16 v[32:35], v[202:205], v[178:181], v[32:35]
	v_mfma_f32_16x16x32_bf16 v[24:27], v[212:215], v[178:181], v[24:27]
	v_mfma_f32_16x16x32_bf16 v[16:19], v[202:205], v[186:189], v[16:19]
	v_mfma_f32_16x16x32_bf16 v[8:11], v[212:215], v[186:189], v[8:11]
	v_mfma_f32_16x16x32_bf16 v[4:7], v[202:205], v[194:197], v[4:7]
	v_mfma_f32_16x16x32_bf16 v[0:3], v[212:215], v[194:197], v[0:3]
	v_mfma_f32_16x16x32_bf16 v[48:51], v[206:209], v[166:169], v[48:51]
	v_mfma_f32_16x16x32_bf16 v[40:43], v[216:219], v[166:169], v[40:43]
	v_mfma_f32_16x16x32_bf16 v[32:35], v[206:209], v[182:185], v[32:35]
	v_mfma_f32_16x16x32_bf16 v[24:27], v[216:219], v[182:185], v[24:27]
	v_mfma_f32_16x16x32_bf16 v[16:19], v[206:209], v[190:193], v[16:19]
	v_mfma_f32_16x16x32_bf16 v[8:11], v[216:219], v[190:193], v[8:11]
	v_mfma_f32_16x16x32_bf16 v[4:7], v[206:209], v[198:201], v[4:7]
	v_mfma_f32_16x16x32_bf16 v[0:3], v[216:219], v[198:201], v[0:3]
	s_add_i32 s52, s52, 2
	s_add_u32 s6, s6, 0x100
	s_addc_u32 s7, s7, 0
	s_add_u32 s44, s44, 0x100
	s_addc_u32 s45, s45, 0
	s_cmp_gt_u32 s52, 29
	s_barrier
	s_setprio 0
	s_cbranch_scc0 .LBB0_346
	s_waitcnt lgkmcnt(0)
	v_lshl_add_u32 v168, s4, 8, v170
	v_ashrrev_i32_e32 v169, 31, v168
	v_or_b32_e32 v154, 16, v168
	v_lshlrev_b64 v[128:129], 7, v[168:169]
	v_ashrrev_i32_e32 v155, 31, v154
	v_lshl_add_u64 v[128:129], v[144:145], 0, v[128:129]
	v_lshlrev_b64 v[156:157], 7, v[154:155]
	global_load_dwordx4 v[132:135], v[128:129], off
	s_nop 0
	global_load_dwordx4 v[128:131], v[128:129], off offset:16
	v_lshl_add_u64 v[156:157], v[144:145], 0, v[156:157]
	global_load_dwordx4 v[178:181], v[156:157], off
	global_load_dwordx4 v[182:185], v[156:157], off offset:16
	v_or_b32_e32 v160, 32, v168
	v_ashrrev_i32_e32 v161, 31, v160
	v_lshlrev_b64 v[156:157], 7, v[160:161]
	v_lshl_add_u64 v[156:157], v[144:145], 0, v[156:157]
	global_load_dwordx4 v[186:189], v[156:157], off
	global_load_dwordx4 v[190:193], v[156:157], off offset:16
	v_or_b32_e32 v156, 48, v168
	v_ashrrev_i32_e32 v157, 31, v156
	v_lshlrev_b64 v[158:159], 7, v[156:157]
	v_lshl_add_u64 v[158:159], v[144:145], 0, v[158:159]
	global_load_dwordx4 v[194:197], v[158:159], off
	global_load_dwordx4 v[198:201], v[158:159], off offset:16
	v_add_u32_e32 v164, 0x80, v168
	v_ashrrev_i32_e32 v165, 31, v164
	v_lshlrev_b64 v[158:159], 7, v[164:165]
	v_lshl_add_u64 v[158:159], v[144:145], 0, v[158:159]
	global_load_dwordx4 v[202:205], v[158:159], off
	global_load_dwordx4 v[206:209], v[158:159], off offset:16
	v_add_u32_e32 v158, 0x90, v168
	v_ashrrev_i32_e32 v159, 31, v158
	v_lshlrev_b64 v[162:163], 7, v[158:159]
	v_lshl_add_u64 v[162:163], v[144:145], 0, v[162:163]
	global_load_dwordx4 v[212:215], v[162:163], off
	global_load_dwordx4 v[216:219], v[162:163], off offset:16
	v_add_u32_e32 v166, 0xa0, v168
	v_ashrrev_i32_e32 v167, 31, v166
	v_lshlrev_b64 v[162:163], 7, v[166:167]
	v_lshl_add_u64 v[162:163], v[144:145], 0, v[162:163]
	global_load_dwordx4 v[220:223], v[162:163], off
	global_load_dwordx4 v[224:227], v[162:163], off offset:16
	v_add_u32_e32 v162, 0xb0, v168
	v_ashrrev_i32_e32 v163, 31, v162
	v_lshlrev_b64 v[228:229], 7, v[162:163]
	v_lshl_add_u64 v[232:233], v[144:145], 0, v[228:229]
	global_load_dwordx4 v[228:231], v[232:233], off
	s_nop 0
	global_load_dwordx4 v[232:235], v[232:233], off offset:16
	s_waitcnt vmcnt(0)
; DI unsigned pack2(float lo, float hi) { f32x2 v = {lo, hi}; bf16v2 r = __builtin_convertvector(v, bf16v2); return __builtin_bit_cast(unsigned, r); }
; DI float row_rstd(const float* ssq, int row, int fq) {
;   const f32x4 a = *(const f32x4*)(ssq + (size_t)row * 32 + fq * 8), b = *(const f32x4*)(ssq + (size_t)row * 32 + fq * 8 + 4);
;   float sm = ((a[0] + a[1]) + (a[2] + a[3])) + ((b[0] + b[1]) + (b[2] + b[3]));
;   sm += __shfl_xor(sm, 16); sm += __shfl_xor(sm, 32);
;   return rsqrtf(sm * (1.0f / 2048.f) + 1e-6f);
; }
;   DI void operator()(const f32x4 (&acc)[2][2][4][2], const Unit& u, int wr, int wc, int fr, int fq) const {
;     const int row0 = u.pm * BM + wr * 64 + fr, col0 = u.pn * BM + wc * 32 + 8 * fq;
;     float rsv[2][4];
; #pragma unroll
;     for (int ai = 0; ai < 2; ++ai)
; #pragma unroll
;       for (int m = 0; m < 4; ++m) rsv[ai][m] = row_rstd(ssq, row0 + ai * HALF + m * 16, fq);
; #pragma unroll
;     for (int ai = 0; ai < 2; ++ai)
; #pragma unroll
;       for (int m = 0; m < 4; ++m) {
;         const int row = row0 + ai * HALF + m * 16;
;         const float rs = rsv[ai][m];
;         bf16_t* rowp = O + (size_t)row * ldc + col0;
; #pragma unroll
;         for (int bj = 0; bj < 2; ++bj) {
;           const f32x4 v0 = acc[ai][bj][m][0] * rs, v1 = acc[ai][bj][m][1] * rs;
;           u32x4 w; w.x = pack2(v0[0], v0[1]); w.y = pack2(v0[2], v0[3]); w.z = pack2(v1[0], v1[1]); w.w = pack2(v1[2], v1[3]);
;           *(u32x4*)(rowp + bj * HALF) = w;
;         }
;       }
;   }
	v_mov_b32_e32 v236, v132
	v_mov_b32_e32 v237, v128
	v_mov_b32_e32 v128, v133
	v_mov_b32_e32 v132, v134
	v_mov_b32_e32 v133, v130
	v_mov_b32_e32 v130, v135
	v_pk_add_f32 v[130:131], v[132:133], v[130:131]
	v_mov_b32_e32 v132, v178
	v_mov_b32_e32 v133, v182
	v_mov_b32_e32 v182, v179
	v_mov_b32_e32 v134, v180
	v_mov_b32_e32 v135, v184
	v_mov_b32_e32 v184, v181
	v_pk_add_f32 v[128:129], v[236:237], v[128:129]
	v_pk_add_f32 v[132:133], v[132:133], v[182:183]
	v_pk_add_f32 v[134:135], v[134:135], v[184:185]
	v_pk_add_f32 v[128:129], v[128:129], v[130:131]
	v_pk_add_f32 v[130:131], v[132:133], v[134:135]
	v_mov_b32_e32 v133, v128
	v_mov_b32_e32 v132, v130
	v_and_b32_e32 v130, 64, v176
	v_add_u32_e32 v155, 64, v130
	v_xor_b32_e32 v130, 16, v176
	v_cmp_lt_i32_e32 vcc, v130, v155
	v_mov_b32_e32 v128, v131
	v_pk_add_f32 v[128:129], v[132:133], v[128:129]
	v_cndmask_b32_e32 v130, v176, v130, vcc
	v_lshlrev_b32_e32 v157, 2, v130
	ds_bpermute_b32 v131, v157, v129
	ds_bpermute_b32 v130, v157, v128
	v_mov_b32_e32 v178, v186
	v_mov_b32_e32 v179, v190
	v_mov_b32_e32 v190, v187
	v_mov_b32_e32 v186, v194
	s_waitcnt lgkmcnt(0)
	v_pk_add_f32 v[128:129], v[128:129], v[130:131]
	v_xor_b32_e32 v130, 32, v176
	v_cmp_lt_i32_e32 vcc, v130, v155
	v_mov_b32_e32 v187, v198
	v_mov_b32_e32 v198, v195
	v_cndmask_b32_e32 v130, v176, v130, vcc
	v_lshlrev_b32_e32 v155, 2, v130
	ds_bpermute_b32 v131, v155, v129
	ds_bpermute_b32 v130, v155, v128
	v_pk_add_f32 v[182:183], v[186:187], v[198:199]
	v_mov_b32_e32 v180, v188
	v_mov_b32_e32 v181, v192
	v_mov_b32_e32 v192, v189
	s_waitcnt lgkmcnt(0)
	v_pk_add_f32 v[128:129], v[128:129], v[130:131]
	v_mov_b64_e32 v[130:131], s[26:27]
	v_pk_fma_f32 v[128:129], v[128:129], s[24:25], v[130:131] op_sel_hi:[1,0,0]
	v_mov_b32_e32 v188, v196
	v_mul_f32_e32 v159, 0x4b800000, v129
	v_cmp_gt_f32_e32 vcc, s73, v129
	v_mov_b32_e32 v189, v200
	v_mov_b32_e32 v200, v197
	v_cndmask_b32_e32 v129, v129, v159, vcc
	v_rsq_f32_e32 v129, v129
	v_pk_add_f32 v[178:179], v[178:179], v[190:191]
	v_pk_add_f32 v[180:181], v[180:181], v[192:193]
	v_pk_add_f32 v[184:185], v[188:189], v[200:201]
	v_mul_f32_e32 v159, 0x45800000, v129
	v_cndmask_b32_e32 v198, v129, v159, vcc
	v_pk_mul_f32 v[126:127], v[126:127], v[198:199] op_sel_hi:[1,0]
	v_pk_mul_f32 v[124:125], v[124:125], v[198:199] op_sel_hi:[1,0]
	v_pk_mul_f32 v[122:123], v[122:123], v[198:199] op_sel_hi:[1,0]
	v_pk_mul_f32 v[120:121], v[120:121], v[198:199] op_sel_hi:[1,0]
	v_cvt_pk_bf16_f32 v124, v124, v125
	v_cvt_pk_bf16_f32 v125, v126, v127
	v_cvt_pk_bf16_f32 v127, v122, v123
	v_lshl_or_b32 v122, s5, 8, v172
	v_cvt_pk_bf16_f32 v126, v120, v121
	v_ashrrev_i32_e32 v123, 31, v122
	v_mov_b64_e32 v[120:121], s[2:3]
	v_mad_i64_i32 v[168:169], s[4:5], v168, s76, v[120:121]
	v_lshlrev_b64 v[122:123], 1, v[122:123]
	v_lshl_add_u64 v[168:169], v[168:169], 0, v[122:123]
	global_store_dwordx4 v[168:169], v[124:127], off
	v_mov_b32_e32 v194, v202
	v_mov_b32_e32 v195, v206
	v_pk_add_f32 v[124:125], v[178:179], v[180:181]
	v_pk_add_f32 v[126:127], v[182:183], v[184:185]
	v_mov_b32_e32 v179, v124
	v_mov_b32_e32 v178, v126
	v_mov_b32_e32 v124, v127
	v_pk_add_f32 v[124:125], v[178:179], v[124:125]
	ds_bpermute_b32 v127, v157, v125
	ds_bpermute_b32 v126, v157, v124
	v_mov_b32_e32 v206, v203
	v_mov_b32_e32 v196, v204
	v_mov_b32_e32 v197, v208
	v_mov_b32_e32 v208, v205
	v_mov_b32_e32 v202, v212
	v_mov_b32_e32 v203, v216
	v_mov_b32_e32 v216, v213
	v_mov_b32_e32 v204, v214
	v_mov_b32_e32 v205, v218
	v_mov_b32_e32 v218, v215
	v_pk_add_f32 v[186:187], v[194:195], v[206:207]
	v_pk_add_f32 v[188:189], v[196:197], v[208:209]
	v_pk_add_f32 v[190:191], v[202:203], v[216:217]
	v_pk_add_f32 v[192:193], v[204:205], v[218:219]
	v_pk_mul_f32 v[178:179], v[114:115], v[198:199] op_sel_hi:[1,0]
	s_waitcnt lgkmcnt(0)
	v_pk_add_f32 v[114:115], v[124:125], v[126:127]
	v_pk_add_f32 v[126:127], v[186:187], v[188:189]
	v_pk_add_f32 v[180:181], v[190:191], v[192:193]
	v_mov_b32_e32 v183, v126
	v_mov_b32_e32 v182, v180
	v_mov_b32_e32 v126, v181
	v_pk_add_f32 v[126:127], v[182:183], v[126:127]
	ds_bpermute_b32 v125, v155, v115
	ds_bpermute_b32 v124, v155, v114
	ds_bpermute_b32 v181, v157, v127
	ds_bpermute_b32 v180, v157, v126
	v_mul_f32_e32 v129, 0x4b800000, v128
	v_cmp_gt_f32_e32 vcc, s73, v128
	s_waitcnt lgkmcnt(2)
	v_pk_add_f32 v[114:115], v[114:115], v[124:125]
	v_mov_b32_e32 v194, v220
	s_waitcnt lgkmcnt(0)
	v_pk_add_f32 v[124:125], v[126:127], v[180:181]
	ds_bpermute_b32 v127, v155, v125
	ds_bpermute_b32 v126, v155, v124
	v_pk_fma_f32 v[114:115], v[114:115], s[24:25], v[130:131] op_sel_hi:[1,0,0]
	v_cndmask_b32_e32 v159, v128, v129, vcc
	v_mul_f32_e32 v128, 0x4b800000, v115
	v_cmp_gt_f32_e64 s[4:5], s73, v115
	v_cmp_gt_f32_e64 s[6:7], s73, v114
	v_mov_b32_e32 v195, v224
	v_cndmask_b32_e64 v161, v115, v128, s[4:5]
	v_mul_f32_e32 v115, 0x4b800000, v114
	v_mov_b32_e32 v224, v221
	v_mov_b32_e32 v196, v222
	v_mov_b32_e32 v197, v226
	v_mov_b32_e32 v226, v223
	v_cndmask_b32_e64 v163, v114, v115, s[6:7]
	s_waitcnt lgkmcnt(0)
	v_pk_add_f32 v[114:115], v[124:125], v[126:127]
	v_pk_add_f32 v[132:133], v[194:195], v[224:225]
	v_pk_add_f32 v[134:135], v[196:197], v[226:227]
	v_mov_b32_e32 v194, v228
	v_mov_b32_e32 v195, v232
	v_mov_b32_e32 v232, v229
	v_mov_b32_e32 v196, v230
	v_mov_b32_e32 v197, v234
	v_mov_b32_e32 v234, v231
	v_pk_fma_f32 v[114:115], v[114:115], s[24:25], v[130:131] op_sel_hi:[1,0,0]
	v_pk_add_f32 v[194:195], v[194:195], v[232:233]
	v_pk_add_f32 v[196:197], v[196:197], v[234:235]
	v_mul_f32_e32 v124, 0x4b800000, v115
	v_cmp_gt_f32_e64 s[8:9], s73, v115
	v_pk_add_f32 v[126:127], v[194:195], v[196:197]
	v_cmp_gt_f32_e64 s[10:11], s73, v114
	v_cndmask_b32_e64 v165, v115, v124, s[8:9]
	v_pk_add_f32 v[124:125], v[132:133], v[134:135]
	v_mov_b32_e32 v128, v126
	v_mov_b32_e32 v129, v124
	v_mov_b32_e32 v124, v127
	v_pk_add_f32 v[124:125], v[128:129], v[124:125]
	ds_bpermute_b32 v127, v157, v125
	ds_bpermute_b32 v126, v157, v124
	v_rsq_f32_e32 v128, v159
	v_mul_f32_e32 v115, 0x4b800000, v114
	v_cndmask_b32_e64 v129, v114, v115, s[10:11]
	v_pk_mul_f32 v[116:117], v[116:117], v[198:199] op_sel_hi:[1,0]
	s_waitcnt lgkmcnt(0)
; DI unsigned pack2(float lo, float hi) { f32x2 v = {lo, hi}; bf16v2 r = __builtin_convertvector(v, bf16v2); return __builtin_bit_cast(unsigned, r); }
;   DI void operator()(const f32x4 (&acc)[2][2][4][2], const Unit& u, int wr, int wc, int fr, int fq) const {
;     ...
;     for (int ai = 0; ai < 2; ++ai)
; #pragma unroll
;       for (int m = 0; m < 4; ++m) {
;         const int row = row0 + ai * HALF + m * 16;
;         const float rs = rsv[ai][m];
;         bf16_t* rowp = O + (size_t)row * ldc + col0;
; #pragma unroll
;         for (int bj = 0; bj < 2; ++bj) {
;           const f32x4 v0 = acc[ai][bj][m][0] * rs, v1 = acc[ai][bj][m][1] * rs;
;           u32x4 w; w.x = pack2(v0[0], v0[1]); w.y = pack2(v0[2], v0[3]); w.z = pack2(v1[0], v1[1]); w.w = pack2(v1[2], v1[3]);
;           *(u32x4*)(rowp + bj * HALF) = w;
;         }
;       }
;   }
	v_pk_add_f32 v[114:115], v[124:125], v[126:127]
	ds_bpermute_b32 v125, v155, v115
	ds_bpermute_b32 v124, v155, v114
	v_mul_f32_e32 v126, 0x45800000, v128
	v_rsq_f32_e32 v127, v161
	v_cndmask_b32_e32 v126, v128, v126, vcc
	v_rsq_f32_e32 v128, v163
	s_waitcnt lgkmcnt(0)
	v_pk_add_f32 v[114:115], v[114:115], v[124:125]
	v_mul_f32_e32 v124, 0x45800000, v127
	v_cndmask_b32_e64 v124, v127, v124, s[4:5]
	v_mul_f32_e32 v127, 0x45800000, v128
	v_pk_fma_f32 v[114:115], v[114:115], s[24:25], v[130:131] op_sel_hi:[1,0,0]
	v_rsq_f32_e32 v125, v165
	v_cndmask_b32_e64 v128, v128, v127, s[6:7]
	v_rsq_f32_e32 v127, v129
	v_mul_f32_e32 v129, 0x4b800000, v115
	v_cmp_gt_f32_e32 vcc, s73, v115
	v_cmp_gt_f32_e64 s[4:5], s73, v114
	v_pk_mul_f32 v[118:119], v[118:119], v[198:199] op_sel_hi:[1,0]
	v_cndmask_b32_e32 v129, v115, v129, vcc
	v_mul_f32_e32 v115, 0x4b800000, v114
	v_cndmask_b32_e64 v131, v114, v115, s[4:5]
	v_cvt_pk_bf16_f32 v114, v116, v117
	v_rsq_f32_e32 v117, v129
	v_cvt_pk_bf16_f32 v115, v118, v119
	v_rsq_f32_e32 v119, v131
	v_mul_f32_e32 v116, 0x45800000, v125
	v_pk_mul_f32 v[112:113], v[112:113], v[198:199] op_sel_hi:[1,0]
	v_cndmask_b32_e64 v118, v125, v116, s[8:9]
	v_mul_f32_e32 v116, 0x45800000, v127
	v_cndmask_b32_e64 v130, v127, v116, s[10:11]
	v_cvt_pk_bf16_f32 v116, v112, v113
	v_mul_f32_e32 v112, 0x45800000, v117
	v_cndmask_b32_e32 v132, v117, v112, vcc
	v_mul_f32_e32 v112, 0x45800000, v119
	v_cvt_pk_bf16_f32 v117, v178, v179
	v_cndmask_b32_e64 v112, v119, v112, s[4:5]
	global_store_dwordx4 v[168:169], v[114:117], off offset:256
	v_pk_mul_f32 v[110:111], v[110:111], v[126:127] op_sel_hi:[1,0]
	v_pk_mul_f32 v[108:109], v[108:109], v[126:127] op_sel_hi:[1,0]
	v_mad_i64_i32 v[114:115], s[4:5], v154, s76, v[120:121]
	v_pk_mul_f32 v[116:117], v[106:107], v[126:127] op_sel_hi:[1,0]
	v_pk_mul_f32 v[106:107], v[104:105], v[126:127] op_sel_hi:[1,0]
	v_lshl_add_u64 v[114:115], v[114:115], 0, v[122:123]
	v_cvt_pk_bf16_f32 v104, v108, v109
	v_cvt_pk_bf16_f32 v105, v110, v111
	v_cvt_pk_bf16_f32 v106, v106, v107
	v_cvt_pk_bf16_f32 v107, v116, v117
	global_store_dwordx4 v[114:115], v[104:107], off
	v_pk_mul_f32 v[98:99], v[98:99], v[126:127] op_sel_hi:[1,0]
	v_pk_mul_f32 v[96:97], v[96:97], v[126:127] op_sel_hi:[1,0]
	v_pk_mul_f32 v[104:105], v[90:91], v[126:127] op_sel_hi:[1,0]
	v_pk_mul_f32 v[90:91], v[88:89], v[126:127] op_sel_hi:[1,0]
	v_cvt_pk_bf16_f32 v88, v96, v97
	v_cvt_pk_bf16_f32 v89, v98, v99
	v_cvt_pk_bf16_f32 v90, v90, v91
	v_cvt_pk_bf16_f32 v91, v104, v105
	global_store_dwordx4 v[114:115], v[88:91], off offset:256
	v_pk_mul_f32 v[94:95], v[94:95], v[124:125] op_sel_hi:[1,0]
	v_pk_mul_f32 v[92:93], v[92:93], v[124:125] op_sel_hi:[1,0]
	v_mad_i64_i32 v[88:89], s[4:5], v160, s76, v[120:121]
	v_lshl_add_u64 v[96:97], v[88:89], 0, v[122:123]
	v_pk_mul_f32 v[90:91], v[102:103], v[124:125] op_sel_hi:[1,0]
	v_pk_mul_f32 v[88:89], v[100:101], v[124:125] op_sel_hi:[1,0]
	v_pk_mul_f32 v[82:83], v[82:83], v[124:125] op_sel_hi:[1,0]
	v_cvt_pk_bf16_f32 v88, v88, v89
	v_cvt_pk_bf16_f32 v89, v90, v91
	v_cvt_pk_bf16_f32 v90, v92, v93
	v_cvt_pk_bf16_f32 v91, v94, v95
	global_store_dwordx4 v[96:97], v[88:91], off
	v_pk_mul_f32 v[80:81], v[80:81], v[124:125] op_sel_hi:[1,0]
	v_pk_mul_f32 v[78:79], v[78:79], v[128:129] op_sel_hi:[1,0]
	v_pk_mul_f32 v[88:89], v[74:75], v[124:125] op_sel_hi:[1,0]
	v_pk_mul_f32 v[74:75], v[72:73], v[124:125] op_sel_hi:[1,0]
	v_cvt_pk_bf16_f32 v72, v80, v81
	v_cvt_pk_bf16_f32 v73, v82, v83
	v_cvt_pk_bf16_f32 v74, v74, v75
	v_cvt_pk_bf16_f32 v75, v88, v89
	global_store_dwordx4 v[96:97], v[72:75], off offset:256
	v_pk_mul_f32 v[76:77], v[76:77], v[128:129] op_sel_hi:[1,0]
	v_pk_mul_f32 v[70:71], v[70:71], v[128:129] op_sel_hi:[1,0]
	v_mad_i64_i32 v[72:73], s[4:5], v156, s76, v[120:121]
	v_lshl_add_u64 v[80:81], v[72:73], 0, v[122:123]
	v_pk_mul_f32 v[74:75], v[86:87], v[128:129] op_sel_hi:[1,0]
	v_pk_mul_f32 v[72:73], v[84:85], v[128:129] op_sel_hi:[1,0]
	v_pk_mul_f32 v[68:69], v[68:69], v[128:129] op_sel_hi:[1,0]
	v_cvt_pk_bf16_f32 v72, v72, v73
	v_cvt_pk_bf16_f32 v73, v74, v75
	v_cvt_pk_bf16_f32 v74, v76, v77
	v_cvt_pk_bf16_f32 v75, v78, v79
	global_store_dwordx4 v[80:81], v[72:75], off
	v_pk_mul_f32 v[62:63], v[62:63], v[118:119] op_sel_hi:[1,0]
; DI unsigned pack2(float lo, float hi) { f32x2 v = {lo, hi}; bf16v2 r = __builtin_convertvector(v, bf16v2); return __builtin_bit_cast(unsigned, r); }
; #define PG8_WAIT_V(n) asm volatile("s_waitcnt vmcnt(" #n ")" ::: "memory")
; #define PG8_BAR __builtin_amdgcn_s_barrier()
;   DI void operator()(const f32x4 (&acc)[2][2][4][2], const Unit& u, int wr, int wc, int fr, int fq) const {
;     ...
;     for (int ai = 0; ai < 2; ++ai)
; #pragma unroll
;       for (int m = 0; m < 4; ++m) {
;         const int row = row0 + ai * HALF + m * 16;
;         const float rs = rsv[ai][m];
;         bf16_t* rowp = O + (size_t)row * ldc + col0;
; #pragma unroll
;         for (int bj = 0; bj < 2; ++bj) {
;           const f32x4 v0 = acc[ai][bj][m][0] * rs, v1 = acc[ai][bj][m][1] * rs;
;           u32x4 w; w.x = pack2(v0[0], v0[1]); w.y = pack2(v0[2], v0[3]); w.z = pack2(v1[0], v1[1]); w.w = pack2(v1[2], v1[3]);
;           *(u32x4*)(rowp + bj * HALF) = w;
;         }
;       }
;   }
; template <class Epi, class Sched = StaticOrder>
; DI void gemm_phase(LAS unsigned char* lds, const Gemm g, const Sched& S, const Epi& E) {
;     ...
;     E(acc, cur, wr, wc, fr, fq);
;     if (!has_next) break;
; #pragma unroll
;     for (int a = 0; a < 2; ++a)
; #pragma unroll
;       for (int b = 0; b < 2; ++b)
; #pragma unroll
;         for (int m = 0; m < 4; ++m)
; #pragma unroll
;           for (int n = 0; n < 2; ++n) acc[a][b][m][n] = (f32x4){0.f, 0.f, 0.f, 0.f};
;     cur = nxt; cA = nA; cB = nB; ++ui;
;   }
;   PG8_WAIT_V(0);
;   if (wr == 0) PG8_BAR;
	v_pk_mul_f32 v[60:61], v[60:61], v[118:119] op_sel_hi:[1,0]
	v_pk_mul_f32 v[72:73], v[66:67], v[128:129] op_sel_hi:[1,0]
	v_pk_mul_f32 v[66:67], v[64:65], v[128:129] op_sel_hi:[1,0]
	v_cvt_pk_bf16_f32 v64, v68, v69
	v_cvt_pk_bf16_f32 v65, v70, v71
	v_cvt_pk_bf16_f32 v66, v66, v67
	v_cvt_pk_bf16_f32 v67, v72, v73
	global_store_dwordx4 v[80:81], v[64:67], off offset:256
	v_pk_mul_f32 v[50:51], v[50:51], v[118:119] op_sel_hi:[1,0]
	v_pk_mul_f32 v[48:49], v[48:49], v[118:119] op_sel_hi:[1,0]
	v_mad_i64_i32 v[64:65], s[4:5], v164, s76, v[120:121]
	v_pk_mul_f32 v[66:67], v[58:59], v[118:119] op_sel_hi:[1,0]
	v_pk_mul_f32 v[58:59], v[56:57], v[118:119] op_sel_hi:[1,0]
	v_lshl_add_u64 v[64:65], v[64:65], 0, v[122:123]
	v_cvt_pk_bf16_f32 v56, v60, v61
	v_cvt_pk_bf16_f32 v57, v62, v63
	v_cvt_pk_bf16_f32 v58, v58, v59
	v_cvt_pk_bf16_f32 v59, v66, v67
	global_store_dwordx4 v[64:65], v[56:59], off
	v_pk_mul_f32 v[46:47], v[46:47], v[130:131] op_sel_hi:[1,0]
	v_pk_mul_f32 v[44:45], v[44:45], v[130:131] op_sel_hi:[1,0]
	v_pk_mul_f32 v[56:57], v[42:43], v[118:119] op_sel_hi:[1,0]
	v_pk_mul_f32 v[42:43], v[40:41], v[118:119] op_sel_hi:[1,0]
	v_cvt_pk_bf16_f32 v40, v48, v49
	v_cvt_pk_bf16_f32 v41, v50, v51
	v_cvt_pk_bf16_f32 v42, v42, v43
	v_cvt_pk_bf16_f32 v43, v56, v57
	global_store_dwordx4 v[64:65], v[40:43], off offset:256
	v_pk_mul_f32 v[34:35], v[34:35], v[130:131] op_sel_hi:[1,0]
	v_pk_mul_f32 v[32:33], v[32:33], v[130:131] op_sel_hi:[1,0]
	v_mad_i64_i32 v[40:41], s[4:5], v158, s76, v[120:121]
	v_lshl_add_u64 v[48:49], v[40:41], 0, v[122:123]
	v_pk_mul_f32 v[42:43], v[54:55], v[130:131] op_sel_hi:[1,0]
	v_pk_mul_f32 v[40:41], v[52:53], v[130:131] op_sel_hi:[1,0]
	v_pk_mul_f32 v[30:31], v[30:31], v[132:133] op_sel_hi:[1,0]
	v_cvt_pk_bf16_f32 v40, v40, v41
	v_cvt_pk_bf16_f32 v41, v42, v43
	v_cvt_pk_bf16_f32 v42, v44, v45
	v_cvt_pk_bf16_f32 v43, v46, v47
	global_store_dwordx4 v[48:49], v[40:43], off
	v_pk_mul_f32 v[28:29], v[28:29], v[132:133] op_sel_hi:[1,0]
	v_pk_mul_f32 v[18:19], v[18:19], v[132:133] op_sel_hi:[1,0]
	v_pk_mul_f32 v[40:41], v[26:27], v[130:131] op_sel_hi:[1,0]
	v_pk_mul_f32 v[26:27], v[24:25], v[130:131] op_sel_hi:[1,0]
	v_cvt_pk_bf16_f32 v24, v32, v33
	v_cvt_pk_bf16_f32 v25, v34, v35
	v_cvt_pk_bf16_f32 v26, v26, v27
	v_cvt_pk_bf16_f32 v27, v40, v41
	global_store_dwordx4 v[48:49], v[24:27], off offset:256
	v_pk_mul_f32 v[16:17], v[16:17], v[132:133] op_sel_hi:[1,0]
	v_pk_mul_f32 v[14:15], v[14:15], v[112:113] op_sel_hi:[1,0]
	v_mad_i64_i32 v[24:25], s[4:5], v166, s76, v[120:121]
	v_lshl_add_u64 v[32:33], v[24:25], 0, v[122:123]
	v_pk_mul_f32 v[26:27], v[38:39], v[132:133] op_sel_hi:[1,0]
	v_pk_mul_f32 v[24:25], v[36:37], v[132:133] op_sel_hi:[1,0]
	v_pk_mul_f32 v[12:13], v[12:13], v[112:113] op_sel_hi:[1,0]
	v_cvt_pk_bf16_f32 v24, v24, v25
	v_cvt_pk_bf16_f32 v25, v26, v27
	v_cvt_pk_bf16_f32 v26, v28, v29
	v_cvt_pk_bf16_f32 v27, v30, v31
	global_store_dwordx4 v[32:33], v[24:27], off
	v_pk_mul_f32 v[6:7], v[6:7], v[112:113] op_sel_hi:[1,0]
	v_pk_mul_f32 v[4:5], v[4:5], v[112:113] op_sel_hi:[1,0]
	v_pk_mul_f32 v[24:25], v[10:11], v[132:133] op_sel_hi:[1,0]
	v_pk_mul_f32 v[10:11], v[8:9], v[132:133] op_sel_hi:[1,0]
	v_cvt_pk_bf16_f32 v8, v16, v17
	v_cvt_pk_bf16_f32 v9, v18, v19
	v_cvt_pk_bf16_f32 v10, v10, v11
	v_cvt_pk_bf16_f32 v11, v24, v25
	global_store_dwordx4 v[32:33], v[8:11], off offset:256
	s_and_b64 vcc, exec, s[0:1]
	s_mov_b64 s[8:9], s[36:37]
	v_mad_i64_i32 v[8:9], s[4:5], v162, s76, v[120:121]
	v_lshl_add_u64 v[16:17], v[8:9], 0, v[122:123]
	v_pk_mul_f32 v[10:11], v[22:23], v[112:113] op_sel_hi:[1,0]
	v_pk_mul_f32 v[8:9], v[20:21], v[112:113] op_sel_hi:[1,0]
	s_mov_b32 s5, s28
	v_cvt_pk_bf16_f32 v8, v8, v9
	v_cvt_pk_bf16_f32 v9, v10, v11
	v_cvt_pk_bf16_f32 v10, v12, v13
	v_cvt_pk_bf16_f32 v11, v14, v15
	global_store_dwordx4 v[16:17], v[8:11], off
	s_mov_b32 s4, s30
	s_mov_b64 s[6:7], s[34:35]
	v_pk_mul_f32 v[8:9], v[2:3], v[112:113] op_sel_hi:[1,0]
	v_pk_mul_f32 v[2:3], v[0:1], v[112:113] op_sel_hi:[1,0]
	v_cvt_pk_bf16_f32 v0, v4, v5
	v_cvt_pk_bf16_f32 v1, v6, v7
	v_cvt_pk_bf16_f32 v2, v2, v3
	v_cvt_pk_bf16_f32 v3, v8, v9
	global_store_dwordx4 v[16:17], v[0:3], off offset:256
	s_cbranch_vccz .LBB0_343
	s_waitcnt vmcnt(0)
	s_cmpk_gt_u32 s27, 0xff
	s_cbranch_scc1 .LBB0_350
	s_barrier

; #define PG8_STAGE(bufoff, gbase, voff) do { _Pragma("unroll") for (int _i = 0; _i < 2; ++_i) \
;     __builtin_amdgcn_global_load_lds((const unsigned*)((const char*)(gbase) + (voff)[_i]), (LAS unsigned*)(lds + (bufoff) + ldsw + _i * 8192), 16, 0, 0); } while (0)
; #define PG8_LDA(dst, b, h) do { _Pragma("unroll") for (int m = 0; m < 4; ++m) _Pragma("unroll") for (int k = 0; k < 2; ++k) dst[m][k] = *(const LAS bf16x8*)(lds + PG8_SA(b, h) + aoff + m * 2048 + k * 1024); } while (0)
; #define PG8_LDB(dst, b, h) do { _Pragma("unroll") for (int n = 0; n < 2; ++n) _Pragma("unroll") for (int k = 0; k < 2; ++k) dst[n][k] = *(const LAS bf16x8*)(lds + PG8_SB(b, h) + boff + n * 2048 + k * 1024); } while (0)
; #define PG8_MMA(ai, bj, At, Bt) do { __builtin_amdgcn_s_setprio(1); _Pragma("unroll") for (int m = 0; m < 4; ++m) _Pragma("unroll") for (int n = 0; n < 2; ++n) _Pragma("unroll") for (int k = 0; k < 2; ++k) \
;     acc[ai][bj][m][n] = __builtin_amdgcn_mfma_f32_16x16x32_bf16(Bt[n][k], At[m][k], acc[ai][bj][m][n], 0, 0, 0); __builtin_amdgcn_s_setprio(0); } while (0)
; #define PG8_WAIT_L(n) asm volatile("s_waitcnt lgkmcnt(" #n ")" ::: "memory")
; #define PG8_BAR __builtin_amdgcn_s_barrier()
; #define PG8_SCHED __builtin_amdgcn_sched_barrier(0)
; template <class Epi, class Sched = StaticOrder>
; DI void gemm_phase(LAS unsigned char* lds, const Gemm g, const Sched& S, const Epi& E) {
;     ...
;     for (int t = 0; t < nt; t += 2) {
;       const bool last = (t == nt - 2);
;       const char* a1 = cA + (size_t)(t + 1) * kstep;
;       const char* a2 = last ? nA : cA + (size_t)(t + 2) * kstep; const char* b2 = last ? nB : cB + (size_t)(t + 2) * kstep;
;       const char* a3 = a2 + kstep; const char* b3 = b2 + kstep;
;       PG8_LDB(B0, 0, 0); PG8_SCHED; PG8_LDA(At, 0, 0); PG8_STAGE(PG8_SA(1, 1), a1 + hstep, voffA);
;       PG8_WAIT_L(8); PG8_BAR; PG8_WAIT_L(0); PG8_MMA(0, 0, At, B0); PG8_BAR; PG8_SCHED;
;       PG8_LDB(B1, 0, 1); PG8_STAGE(PG8_SB(0, 0), b2, voffB);
;       PG8_BAR; PG8_WAIT_L(0); PG8_MMA(0, 1, At, B1); PG8_BAR;
;       PG8_LDA(At, 0, 1); PG8_STAGE(PG8_SA(0, 0), a2, voffA);
;       PG8_BAR; PG8_WAIT_L(0); PG8_MMA(1, 0, At, B0); PG8_BAR; PG8_SCHED;
.LBB0_728:
	s_add_u32 s24, s22, 0xfff80080
	s_addc_u32 s25, s23, -1
	s_cmp_eq_u32 s53, 28
	s_cselect_b32 s27, s17, s25
	s_cselect_b32 s26, s43, s24
	s_cselect_b32 s25, s15, s52
	s_cselect_b32 s24, s44, s45
	v_lshl_add_u64 v[192:193], s[22:23], 0, v[184:185]
	s_add_i32 m0, s37, 0xc000
	ds_read_b128 v[144:147], v208
	ds_read_b128 v[148:151], v208 offset:1024
	ds_read_b128 v[152:155], v208 offset:2048
	ds_read_b128 v[156:159], v208 offset:3072
	ds_read_b128 v[160:163], v208 offset:4096
	ds_read_b128 v[164:167], v208 offset:5120
	ds_read_b128 v[168:171], v208 offset:6144
	ds_read_b128 v[172:175], v208 offset:7168
	global_load_lds_dwordx4 v[192:193], off
	v_lshl_add_u64 v[192:193], s[22:23], 0, v[186:187]
	s_add_i32 m0, s37, 0xe000
	s_nop 0
	global_load_lds_dwordx4 v[192:193], off
	s_waitcnt lgkmcnt(0)
	s_setprio 1
	s_barrier
	v_mfma_f32_16x16x32_bf16 v[124:127], v[128:131], v[144:147], v[124:127]
	v_mfma_f32_16x16x32_bf16 v[120:123], v[136:139], v[144:147], v[120:123]
	v_mfma_f32_16x16x32_bf16 v[108:111], v[128:131], v[152:155], v[108:111]
	v_mfma_f32_16x16x32_bf16 v[104:107], v[136:139], v[152:155], v[104:107]
	v_mfma_f32_16x16x32_bf16 v[92:95], v[128:131], v[160:163], v[92:95]
	v_mfma_f32_16x16x32_bf16 v[88:91], v[136:139], v[160:163], v[88:91]
	v_mfma_f32_16x16x32_bf16 v[76:79], v[128:131], v[168:171], v[76:79]
	v_mfma_f32_16x16x32_bf16 v[72:75], v[136:139], v[168:171], v[72:75]
	v_mfma_f32_16x16x32_bf16 v[124:127], v[132:135], v[148:151], v[124:127]
	v_mfma_f32_16x16x32_bf16 v[120:123], v[140:143], v[148:151], v[120:123]
	v_mfma_f32_16x16x32_bf16 v[108:111], v[132:135], v[156:159], v[108:111]
	v_mfma_f32_16x16x32_bf16 v[104:107], v[140:143], v[156:159], v[104:107]
	v_mfma_f32_16x16x32_bf16 v[92:95], v[132:135], v[164:167], v[92:95]
	v_mfma_f32_16x16x32_bf16 v[88:91], v[140:143], v[164:167], v[88:91]
	v_mfma_f32_16x16x32_bf16 v[76:79], v[132:135], v[172:175], v[76:79]
	v_mfma_f32_16x16x32_bf16 v[72:75], v[140:143], v[172:175], v[72:75]
	s_barrier
	s_setprio 0
	s_add_i32 s54, s50, s35
	v_lshl_add_u64 v[216:217], s[24:25], 0, v[180:181]
	s_mov_b32 m0, s54
	ds_read_b128 v[192:195], v209
	ds_read_b128 v[196:199], v209 offset:1024
	ds_read_b128 v[200:203], v209 offset:2048
	ds_read_b128 v[212:215], v209 offset:3072
	global_load_lds_dwordx4 v[216:217], off
	v_lshl_add_u64 v[218:219], s[24:25], 0, v[176:177]
	s_add_i32 m0, s54, 0x2000
	s_nop 0
	global_load_lds_dwordx4 v[218:219], off
	s_waitcnt lgkmcnt(0)
	s_setprio 1
	s_barrier
	v_mfma_f32_16x16x32_bf16 v[116:119], v[192:195], v[144:147], v[116:119]
	v_mfma_f32_16x16x32_bf16 v[112:115], v[200:203], v[144:147], v[112:115]
	v_mfma_f32_16x16x32_bf16 v[100:103], v[192:195], v[152:155], v[100:103]
	v_mfma_f32_16x16x32_bf16 v[96:99], v[200:203], v[152:155], v[96:99]
	v_mfma_f32_16x16x32_bf16 v[84:87], v[192:195], v[160:163], v[84:87]
	v_mfma_f32_16x16x32_bf16 v[80:83], v[200:203], v[160:163], v[80:83]
	v_mfma_f32_16x16x32_bf16 v[68:71], v[192:195], v[168:171], v[68:71]
	v_mfma_f32_16x16x32_bf16 v[64:67], v[200:203], v[168:171], v[64:67]
	v_mfma_f32_16x16x32_bf16 v[116:119], v[196:199], v[148:151], v[116:119]
	v_mfma_f32_16x16x32_bf16 v[112:115], v[212:215], v[148:151], v[112:115]
	v_mfma_f32_16x16x32_bf16 v[100:103], v[196:199], v[156:159], v[100:103]
	v_mfma_f32_16x16x32_bf16 v[96:99], v[212:215], v[156:159], v[96:99]
	v_mfma_f32_16x16x32_bf16 v[84:87], v[196:199], v[164:167], v[84:87]
	v_mfma_f32_16x16x32_bf16 v[80:83], v[212:215], v[164:167], v[80:83]
	v_mfma_f32_16x16x32_bf16 v[68:71], v[196:199], v[172:175], v[68:71]
	v_mfma_f32_16x16x32_bf16 v[64:67], v[212:215], v[172:175], v[64:67]
	s_barrier
	s_setprio 0
	s_mov_b32 m0, s37
	v_lshl_add_u64 v[220:221], s[26:27], 0, v[182:183]
	ds_read_b128 v[144:147], v208 offset:16384
	ds_read_b128 v[148:151], v208 offset:17408
	ds_read_b128 v[152:155], v208 offset:18432
	ds_read_b128 v[156:159], v208 offset:19456
	ds_read_b128 v[160:163], v208 offset:20480
	ds_read_b128 v[164:167], v208 offset:21504
	ds_read_b128 v[168:171], v208 offset:22528
	ds_read_b128 v[172:175], v208 offset:23552
	global_load_lds_dwordx4 v[220:221], off
	v_lshl_add_u64 v[222:223], s[26:27], 0, v[178:179]
	s_mov_b32 m0, s38
	s_nop 0
	global_load_lds_dwordx4 v[222:223], off
	s_waitcnt vmcnt(10)
	s_waitcnt lgkmcnt(0)
	s_setprio 1
	s_barrier
	v_mfma_f32_16x16x32_bf16 v[60:63], v[128:131], v[144:147], v[60:63]
	v_mfma_f32_16x16x32_bf16 v[56:59], v[136:139], v[144:147], v[56:59]
	v_mfma_f32_16x16x32_bf16 v[44:47], v[128:131], v[152:155], v[44:47]
	v_mfma_f32_16x16x32_bf16 v[40:43], v[136:139], v[152:155], v[40:43]
	v_mfma_f32_16x16x32_bf16 v[28:31], v[128:131], v[160:163], v[28:31]
	v_mfma_f32_16x16x32_bf16 v[24:27], v[136:139], v[160:163], v[24:27]
	v_mfma_f32_16x16x32_bf16 v[12:15], v[128:131], v[168:171], v[12:15]
	v_mfma_f32_16x16x32_bf16 v[8:11], v[136:139], v[168:171], v[8:11]
	v_mfma_f32_16x16x32_bf16 v[60:63], v[132:135], v[148:151], v[60:63]
	v_mfma_f32_16x16x32_bf16 v[56:59], v[140:143], v[148:151], v[56:59]
	v_mfma_f32_16x16x32_bf16 v[44:47], v[132:135], v[156:159], v[44:47]
	v_mfma_f32_16x16x32_bf16 v[40:43], v[140:143], v[156:159], v[40:43]
	v_mfma_f32_16x16x32_bf16 v[28:31], v[132:135], v[164:167], v[28:31]
	v_mfma_f32_16x16x32_bf16 v[24:27], v[140:143], v[164:167], v[24:27]
	v_mfma_f32_16x16x32_bf16 v[12:15], v[132:135], v[172:175], v[12:15]
	v_mfma_f32_16x16x32_bf16 v[8:11], v[140:143], v[172:175], v[8:11]
	s_barrier
; #define PG8_STAGE(bufoff, gbase, voff) do { _Pragma("unroll") for (int _i = 0; _i < 2; ++_i) \
;     __builtin_amdgcn_global_load_lds((const unsigned*)((const char*)(gbase) + (voff)[_i]), (LAS unsigned*)(lds + (bufoff) + ldsw + _i * 8192), 16, 0, 0); } while (0)
; #define PG8_LDA(dst, b, h) do { _Pragma("unroll") for (int m = 0; m < 4; ++m) _Pragma("unroll") for (int k = 0; k < 2; ++k) dst[m][k] = *(const LAS bf16x8*)(lds + PG8_SA(b, h) + aoff + m * 2048 + k * 1024); } while (0)
; #define PG8_LDB(dst, b, h) do { _Pragma("unroll") for (int n = 0; n < 2; ++n) _Pragma("unroll") for (int k = 0; k < 2; ++k) dst[n][k] = *(const LAS bf16x8*)(lds + PG8_SB(b, h) + boff + n * 2048 + k * 1024); } while (0)
; #define PG8_MMA(ai, bj, At, Bt) do { __builtin_amdgcn_s_setprio(1); _Pragma("unroll") for (int m = 0; m < 4; ++m) _Pragma("unroll") for (int n = 0; n < 2; ++n) _Pragma("unroll") for (int k = 0; k < 2; ++k) \
;     acc[ai][bj][m][n] = __builtin_amdgcn_mfma_f32_16x16x32_bf16(Bt[n][k], At[m][k], acc[ai][bj][m][n], 0, 0, 0); __builtin_amdgcn_s_setprio(0); } while (0)
; #define PG8_WAIT_V(n) asm volatile("s_waitcnt vmcnt(" #n ")" ::: "memory")
; #define PG8_WAIT_L(n) asm volatile("s_waitcnt lgkmcnt(" #n ")" ::: "memory")
; #define PG8_BAR __builtin_amdgcn_s_barrier()
; #define PG8_SCHED __builtin_amdgcn_sched_barrier(0)
; template <class Epi, class Sched = StaticOrder>
; DI void gemm_phase(LAS unsigned char* lds, const Gemm g, const Sched& S, const Epi& E) {
;     ...
;       PG8_STAGE(PG8_SB(0, 1), b2 + hstep, voffB);
;       PG8_WAIT_V(6); PG8_BAR; PG8_MMA(1, 1, At, B1); PG8_BAR;
;       PG8_LDB(B0, 1, 0); PG8_SCHED; PG8_LDA(At, 1, 0); PG8_STAGE(PG8_SA(0, 1), a2 + hstep, voffA);
;       PG8_WAIT_L(8); PG8_BAR; PG8_WAIT_L(0); PG8_MMA(0, 0, At, B0); PG8_BAR; PG8_SCHED;
;       PG8_LDB(B1, 1, 1); PG8_STAGE(PG8_SB(1, 0), b3, voffB);
;       PG8_BAR; PG8_WAIT_L(0); PG8_MMA(0, 1, At, B1); PG8_BAR;
;       PG8_LDA(At, 1, 1); PG8_STAGE(PG8_SA(1, 0), a3, voffA);
;       PG8_BAR; PG8_WAIT_L(0); PG8_MMA(1, 0, At, B0); PG8_BAR; PG8_SCHED;
	s_setprio 0
	s_add_u32 s54, s24, 0x80000
	s_addc_u32 s55, s25, 0
	s_add_i32 s57, s51, s35
	v_lshl_add_u64 v[128:129], s[54:55], 0, v[180:181]
	s_mov_b32 m0, s57
	s_nop 0
	global_load_lds_dwordx4 v[128:129], off
	v_lshl_add_u64 v[128:129], s[54:55], 0, v[176:177]
	s_add_i32 m0, s57, 0x2000
	s_nop 0
	global_load_lds_dwordx4 v[128:129], off
	s_add_i32 s54, 0, 0x18000
	v_add_u32_e32 v140, s54, v205
	ds_read_b128 v[128:131], v140
	ds_read_b128 v[132:135], v140 offset:1024
	ds_read_b128 v[136:139], v140 offset:2048
	ds_read_b128 v[140:143], v140 offset:3072
	s_waitcnt vmcnt(6)
	s_setprio 1
	s_barrier
	v_mfma_f32_16x16x32_bf16 v[52:55], v[192:195], v[144:147], v[52:55]
	v_mfma_f32_16x16x32_bf16 v[48:51], v[200:203], v[144:147], v[48:51]
	v_mfma_f32_16x16x32_bf16 v[36:39], v[192:195], v[152:155], v[36:39]
	v_mfma_f32_16x16x32_bf16 v[32:35], v[200:203], v[152:155], v[32:35]
	v_mfma_f32_16x16x32_bf16 v[20:23], v[192:195], v[160:163], v[20:23]
	v_mfma_f32_16x16x32_bf16 v[16:19], v[200:203], v[160:163], v[16:19]
	v_mfma_f32_16x16x32_bf16 v[4:7], v[192:195], v[168:171], v[4:7]
	v_mfma_f32_16x16x32_bf16 v[0:3], v[200:203], v[168:171], v[0:3]
	v_mfma_f32_16x16x32_bf16 v[52:55], v[196:199], v[148:151], v[52:55]
	v_mfma_f32_16x16x32_bf16 v[48:51], v[212:215], v[148:151], v[48:51]
	v_mfma_f32_16x16x32_bf16 v[36:39], v[196:199], v[156:159], v[36:39]
	v_mfma_f32_16x16x32_bf16 v[32:35], v[212:215], v[156:159], v[32:35]
	v_mfma_f32_16x16x32_bf16 v[20:23], v[196:199], v[164:167], v[20:23]
	v_mfma_f32_16x16x32_bf16 v[16:19], v[212:215], v[164:167], v[16:19]
	v_mfma_f32_16x16x32_bf16 v[4:7], v[196:199], v[172:175], v[4:7]
	v_mfma_f32_16x16x32_bf16 v[0:3], v[212:215], v[172:175], v[0:3]
	s_barrier
	s_setprio 0
	s_add_u32 s26, s26, 0x80000
	s_addc_u32 s27, s27, 0
	s_mov_b32 m0, s39
	v_lshl_add_u64 v[192:193], s[26:27], 0, v[182:183]
	ds_read_b128 v[144:147], v208 offset:32768
	ds_read_b128 v[148:151], v208 offset:33792
	ds_read_b128 v[152:155], v208 offset:34816
	ds_read_b128 v[156:159], v208 offset:35840
	ds_read_b128 v[160:163], v208 offset:36864
	ds_read_b128 v[164:167], v208 offset:37888
	ds_read_b128 v[168:171], v208 offset:38912
	ds_read_b128 v[172:175], v208 offset:39936
	global_load_lds_dwordx4 v[192:193], off
	v_lshl_add_u64 v[192:193], s[26:27], 0, v[178:179]
	s_mov_b32 m0, s40
	s_nop 0
	global_load_lds_dwordx4 v[192:193], off
	s_waitcnt lgkmcnt(0)
	s_setprio 1
	s_barrier
	v_mfma_f32_16x16x32_bf16 v[124:127], v[128:131], v[144:147], v[124:127]
	v_mfma_f32_16x16x32_bf16 v[120:123], v[136:139], v[144:147], v[120:123]
	v_mfma_f32_16x16x32_bf16 v[108:111], v[128:131], v[152:155], v[108:111]
	v_mfma_f32_16x16x32_bf16 v[104:107], v[136:139], v[152:155], v[104:107]
	v_mfma_f32_16x16x32_bf16 v[92:95], v[128:131], v[160:163], v[92:95]
	v_mfma_f32_16x16x32_bf16 v[88:91], v[136:139], v[160:163], v[88:91]
	v_mfma_f32_16x16x32_bf16 v[76:79], v[128:131], v[168:171], v[76:79]
	v_mfma_f32_16x16x32_bf16 v[72:75], v[136:139], v[168:171], v[72:75]
	v_mfma_f32_16x16x32_bf16 v[124:127], v[132:135], v[148:151], v[124:127]
	v_mfma_f32_16x16x32_bf16 v[120:123], v[140:143], v[148:151], v[120:123]
	v_mfma_f32_16x16x32_bf16 v[108:111], v[132:135], v[156:159], v[108:111]
	v_mfma_f32_16x16x32_bf16 v[104:107], v[140:143], v[156:159], v[104:107]
	v_mfma_f32_16x16x32_bf16 v[92:95], v[132:135], v[164:167], v[92:95]
	v_mfma_f32_16x16x32_bf16 v[88:91], v[140:143], v[164:167], v[88:91]
	v_mfma_f32_16x16x32_bf16 v[76:79], v[132:135], v[172:175], v[76:79]
	v_mfma_f32_16x16x32_bf16 v[72:75], v[140:143], v[172:175], v[72:75]
	s_barrier
	s_setprio 0
	s_add_i32 s26, 0, 0x1c000
	s_add_i32 s27, s54, s35
	v_add_u32_e32 v212, s26, v205
	v_lshl_add_u64 v[216:217], v[216:217], 0, s[10:11]
	s_mov_b32 m0, s27
	ds_read_b128 v[192:195], v212
	ds_read_b128 v[196:199], v212 offset:1024
	ds_read_b128 v[200:203], v212 offset:2048
	ds_read_b128 v[212:215], v212 offset:3072
	global_load_lds_dwordx4 v[216:217], off
	v_lshl_add_u64 v[216:217], v[218:219], 0, s[10:11]
	s_add_i32 m0, s27, 0x2000
	s_nop 0
	global_load_lds_dwordx4 v[216:217], off
	s_waitcnt lgkmcnt(0)
	s_setprio 1
	s_barrier
	v_mfma_f32_16x16x32_bf16 v[116:119], v[192:195], v[144:147], v[116:119]
	v_mfma_f32_16x16x32_bf16 v[112:115], v[200:203], v[144:147], v[112:115]
	v_mfma_f32_16x16x32_bf16 v[100:103], v[192:195], v[152:155], v[100:103]
	v_mfma_f32_16x16x32_bf16 v[96:99], v[200:203], v[152:155], v[96:99]
	v_mfma_f32_16x16x32_bf16 v[84:87], v[192:195], v[160:163], v[84:87]
	v_mfma_f32_16x16x32_bf16 v[80:83], v[200:203], v[160:163], v[80:83]
	v_mfma_f32_16x16x32_bf16 v[68:71], v[192:195], v[168:171], v[68:71]
	v_mfma_f32_16x16x32_bf16 v[64:67], v[200:203], v[168:171], v[64:67]
	v_mfma_f32_16x16x32_bf16 v[116:119], v[196:199], v[148:151], v[116:119]
	v_mfma_f32_16x16x32_bf16 v[112:115], v[212:215], v[148:151], v[112:115]
	v_mfma_f32_16x16x32_bf16 v[100:103], v[196:199], v[156:159], v[100:103]
	v_mfma_f32_16x16x32_bf16 v[96:99], v[212:215], v[156:159], v[96:99]
	v_mfma_f32_16x16x32_bf16 v[84:87], v[196:199], v[164:167], v[84:87]
	v_mfma_f32_16x16x32_bf16 v[80:83], v[212:215], v[164:167], v[80:83]
	v_mfma_f32_16x16x32_bf16 v[68:71], v[196:199], v[172:175], v[68:71]
	v_mfma_f32_16x16x32_bf16 v[64:67], v[212:215], v[172:175], v[64:67]
	s_barrier
	s_setprio 0
	s_mov_b32 m0, s46
	v_lshl_add_u64 v[216:217], v[220:221], 0, s[10:11]
	ds_read_b128 v[144:147], v208 offset:49152
	ds_read_b128 v[148:151], v208 offset:50176
	ds_read_b128 v[152:155], v208 offset:51200
	ds_read_b128 v[156:159], v208 offset:52224
	ds_read_b128 v[160:163], v208 offset:53248
	ds_read_b128 v[164:167], v208 offset:54272
	ds_read_b128 v[168:171], v208 offset:55296
	ds_read_b128 v[172:175], v208 offset:56320
	global_load_lds_dwordx4 v[216:217], off
	v_lshl_add_u64 v[216:217], v[222:223], 0, s[10:11]
	s_mov_b32 m0, s47
	s_nop 0
	global_load_lds_dwordx4 v[216:217], off
	s_waitcnt vmcnt(10)
	s_waitcnt lgkmcnt(0)
	s_setprio 1
	s_barrier
; #define PG8_STAGE(bufoff, gbase, voff) do { _Pragma("unroll") for (int _i = 0; _i < 2; ++_i) \
;     __builtin_amdgcn_global_load_lds((const unsigned*)((const char*)(gbase) + (voff)[_i]), (LAS unsigned*)(lds + (bufoff) + ldsw + _i * 8192), 16, 0, 0); } while (0)
; #define PG8_MMA(ai, bj, At, Bt) do { __builtin_amdgcn_s_setprio(1); _Pragma("unroll") for (int m = 0; m < 4; ++m) _Pragma("unroll") for (int n = 0; n < 2; ++n) _Pragma("unroll") for (int k = 0; k < 2; ++k) \
;     acc[ai][bj][m][n] = __builtin_amdgcn_mfma_f32_16x16x32_bf16(Bt[n][k], At[m][k], acc[ai][bj][m][n], 0, 0, 0); __builtin_amdgcn_s_setprio(0); } while (0)
; #define PG8_WAIT_V(n) asm volatile("s_waitcnt vmcnt(" #n ")" ::: "memory")
; #define PG8_WAIT_L(n) asm volatile("s_waitcnt lgkmcnt(" #n ")" ::: "memory")
; #define PG8_BAR __builtin_amdgcn_s_barrier()
; #define PG8_SCHED __builtin_amdgcn_sched_barrier(0)
; template <class Epi, class Sched = StaticOrder>
; DI void gemm_phase(LAS unsigned char* lds, const Gemm g, const Sched& S, const Epi& E) {
;     ...
;       PG8_BAR; PG8_WAIT_L(0); PG8_MMA(1, 0, At, B0); PG8_BAR; PG8_SCHED;
;       PG8_STAGE(PG8_SB(1, 1), b3 + hstep, voffB);
;       PG8_WAIT_V(6); PG8_BAR; PG8_MMA(1, 1, At, B1); PG8_BAR;
;     }
	v_mfma_f32_16x16x32_bf16 v[60:63], v[128:131], v[144:147], v[60:63]
	v_mfma_f32_16x16x32_bf16 v[56:59], v[136:139], v[144:147], v[56:59]
	v_mfma_f32_16x16x32_bf16 v[44:47], v[128:131], v[152:155], v[44:47]
	v_mfma_f32_16x16x32_bf16 v[40:43], v[136:139], v[152:155], v[40:43]
	v_mfma_f32_16x16x32_bf16 v[28:31], v[128:131], v[160:163], v[28:31]
	v_mfma_f32_16x16x32_bf16 v[24:27], v[136:139], v[160:163], v[24:27]
	v_mfma_f32_16x16x32_bf16 v[12:15], v[128:131], v[168:171], v[12:15]
	v_mfma_f32_16x16x32_bf16 v[8:11], v[136:139], v[168:171], v[8:11]
	v_mfma_f32_16x16x32_bf16 v[60:63], v[132:135], v[148:151], v[60:63]
	v_mfma_f32_16x16x32_bf16 v[56:59], v[140:143], v[148:151], v[56:59]
	v_mfma_f32_16x16x32_bf16 v[44:47], v[132:135], v[156:159], v[44:47]
	v_mfma_f32_16x16x32_bf16 v[40:43], v[140:143], v[156:159], v[40:43]
	v_mfma_f32_16x16x32_bf16 v[28:31], v[132:135], v[164:167], v[28:31]
	v_mfma_f32_16x16x32_bf16 v[24:27], v[140:143], v[164:167], v[24:27]
	v_mfma_f32_16x16x32_bf16 v[12:15], v[132:135], v[172:175], v[12:15]
	v_mfma_f32_16x16x32_bf16 v[8:11], v[140:143], v[172:175], v[8:11]
	s_barrier
	s_setprio 0
	s_add_u32 s24, s24, 0x80080
	s_addc_u32 s25, s25, 0
	s_add_i32 s26, s26, s35
	v_lshl_add_u64 v[128:129], s[24:25], 0, v[180:181]
	s_mov_b32 m0, s26
	s_nop 0
	global_load_lds_dwordx4 v[128:129], off
	v_lshl_add_u64 v[128:129], s[24:25], 0, v[176:177]
	s_add_i32 m0, s26, 0x2000
	s_nop 0
	global_load_lds_dwordx4 v[128:129], off
	ds_read_b128 v[128:131], v207
	ds_read_b128 v[132:135], v207 offset:1024
	ds_read_b128 v[136:139], v207 offset:2048
	ds_read_b128 v[140:143], v207 offset:3072
	s_waitcnt vmcnt(6)
	s_setprio 1
	s_barrier
	v_mfma_f32_16x16x32_bf16 v[52:55], v[192:195], v[144:147], v[52:55]
	v_mfma_f32_16x16x32_bf16 v[48:51], v[200:203], v[144:147], v[48:51]
	v_mfma_f32_16x16x32_bf16 v[36:39], v[192:195], v[152:155], v[36:39]
	v_mfma_f32_16x16x32_bf16 v[32:35], v[200:203], v[152:155], v[32:35]
	v_mfma_f32_16x16x32_bf16 v[20:23], v[192:195], v[160:163], v[20:23]
	v_mfma_f32_16x16x32_bf16 v[16:19], v[200:203], v[160:163], v[16:19]
	v_mfma_f32_16x16x32_bf16 v[4:7], v[192:195], v[168:171], v[4:7]
	v_mfma_f32_16x16x32_bf16 v[0:3], v[200:203], v[168:171], v[0:3]
	v_mfma_f32_16x16x32_bf16 v[52:55], v[196:199], v[148:151], v[52:55]
	v_mfma_f32_16x16x32_bf16 v[48:51], v[212:215], v[148:151], v[48:51]
	v_mfma_f32_16x16x32_bf16 v[36:39], v[196:199], v[156:159], v[36:39]
	v_mfma_f32_16x16x32_bf16 v[32:35], v[212:215], v[156:159], v[32:35]
	v_mfma_f32_16x16x32_bf16 v[20:23], v[196:199], v[164:167], v[20:23]
	v_mfma_f32_16x16x32_bf16 v[16:19], v[212:215], v[164:167], v[16:19]
	v_mfma_f32_16x16x32_bf16 v[4:7], v[196:199], v[172:175], v[4:7]
	v_mfma_f32_16x16x32_bf16 v[0:3], v[212:215], v[172:175], v[0:3]
	s_add_i32 s53, s53, 2
	s_add_u32 s22, s22, 0x100
	s_addc_u32 s23, s23, 0
	s_add_u32 s45, s45, 0x100
	s_addc_u32 s52, s52, 0
	s_cmp_gt_u32 s53, 29
	s_barrier
	s_setprio 0
	s_cbranch_scc0 .LBB0_728
; DI unsigned pack2(float lo, float hi) { f32x2 v = {lo, hi}; bf16v2 r = __builtin_convertvector(v, bf16v2); return __builtin_bit_cast(unsigned, r); }
;   DI void operator()(const f32x4 (&acc)[2][2][4][2], const Unit& u, int wr, int wc, int fr, int fq) const {
;     const int row0 = u.pm * BM + wr * 64 + fr, col0 = u.pn * BM + wc * 32 + 8 * fq;
; #pragma unroll
;     for (int ai = 0; ai < 2; ++ai) {
;       f32x4 bv[4][2][2];
; #pragma unroll
;       for (int m = 0; m < 4; ++m)
; #pragma unroll
;         for (int bj = 0; bj < 2; ++bj) {
;           const float* bp = base + (size_t)(row0 + ai * HALF + m * 16) * 2048 + col0 + bj * HALF;
;           bv[m][bj][0] = *(const f32x4*)bp; bv[m][bj][1] = *(const f32x4*)(bp + 4);
;         }
; #pragma unroll
;       for (int m = 0; m < 4; ++m) {
;         const int row = row0 + ai * HALF + m * 16;
;         const size_t off = (size_t)row * 2048 + col0;
;         float ss = 0.f;
; #pragma unroll
;         for (int bj = 0; bj < 2; ++bj) {
;           const f32x4 v0 = acc[ai][bj][m][0] + bv[m][bj][0], v1 = acc[ai][bj][m][1] + bv[m][bj][1];
;           *(f32x4*)(C + off + bj * HALF) = v0; *(f32x4*)(C + off + bj * HALF + 4) = v1;
;           if (xb) {
;             u32x4 w; w.x = pack2(v0[0], v0[1]); w.y = pack2(v0[2], v0[3]); w.z = pack2(v1[0], v1[1]); w.w = pack2(v1[2], v1[3]);
;             *(u32x4*)(xb + off + bj * HALF) = w;
;             ss += v0[0] * v0[0] + v0[1] * v0[1] + v0[2] * v0[2] + v0[3] * v0[3] + v1[0] * v1[0] + v1[1] * v1[1] + v1[2] * v1[2] + v1[3] * v1[3];
;           }
;         }
;         if (xb) {
;           ss += __shfl_xor(ss, 16); ss += __shfl_xor(ss, 32);
;           if (fq == 0) ssq[(size_t)row * 32 + u.pn * 4 + wc] = ss;
;         }
	s_waitcnt lgkmcnt(0)
	v_lshl_add_u32 v196, s12, 8, v204
	v_lshl_or_b32 v192, s42, 8, v206
	v_ashrrev_i32_e32 v193, 31, v192
	v_ashrrev_i32_e32 v197, 31, v196
	v_lshl_add_u64 v[194:195], v[192:193], 2, s[60:61]
	v_lshlrev_b64 v[128:129], 13, v[196:197]
	v_lshl_add_u64 v[128:129], v[194:195], 0, v[128:129]
	global_load_dwordx4 v[214:217], v[128:129], off
	global_load_dwordx4 v[218:221], v[128:129], off offset:16
	global_load_dwordx4 v[222:225], v[128:129], off offset:512
	global_load_dwordx4 v[226:229], v[128:129], off offset:528
	v_or_b32_e32 v202, 16, v196
	v_or_b32_e32 v200, 32, v196
	v_or_b32_e32 v198, 48, v196
	v_ashrrev_i32_e32 v203, 31, v202
	v_ashrrev_i32_e32 v201, 31, v200
	v_ashrrev_i32_e32 v199, 31, v198
	v_lshlrev_b64 v[128:129], 13, v[202:203]
	v_lshlrev_b64 v[130:131], 13, v[200:201]
	v_lshlrev_b64 v[132:133], 13, v[198:199]
	v_lshl_add_u64 v[128:129], v[194:195], 0, v[128:129]
	v_lshl_add_u64 v[130:131], v[194:195], 0, v[130:131]
	v_lshl_add_u64 v[132:133], v[194:195], 0, v[132:133]
	global_load_dwordx4 v[168:171], v[128:129], off offset:16
	global_load_dwordx4 v[172:175], v[128:129], off
	global_load_dwordx4 v[160:163], v[128:129], off offset:528
	global_load_dwordx4 v[164:167], v[128:129], off offset:512
	global_load_dwordx4 v[152:155], v[130:131], off offset:16
	global_load_dwordx4 v[156:159], v[130:131], off
	global_load_dwordx4 v[144:147], v[130:131], off offset:528
	global_load_dwordx4 v[148:151], v[130:131], off offset:512
	global_load_dwordx4 v[136:139], v[132:133], off offset:16
	global_load_dwordx4 v[140:143], v[132:133], off
	s_nop 0
	global_load_dwordx4 v[128:131], v[132:133], off offset:528
	s_nop 0
	global_load_dwordx4 v[132:135], v[132:133], off offset:512
	v_and_b32_e32 v212, 64, v211
	v_xor_b32_e32 v230, 16, v211
	v_add_u32_e32 v232, 64, v212
	v_xor_b32_e32 v231, 32, v211
	v_cmp_lt_i32_e32 vcc, v230, v232
	v_lshlrev_b64 v[212:213], 11, v[196:197]
	v_readlane_b32 s64, v243, 3
	v_cndmask_b32_e32 v233, v211, v230, vcc
	v_cmp_lt_i32_e32 vcc, v231, v232
	v_readlane_b32 s78, v243, 17
	v_readlane_b32 s79, v243, 18
	v_cndmask_b32_e32 v234, v211, v231, vcc
	v_lshl_add_u64 v[230:231], v[212:213], 0, v[192:193]
	v_lshlrev_b32_e32 v212, 2, v233
	v_lshl_add_u64 v[232:233], v[230:231], 2, s[78:79]
	v_lshl_add_u64 v[230:231], v[230:231], 1, s[2:3]
	s_lshl_b32 s22, s42, 2
	s_ashr_i32 s23, s22, 31
	v_readlane_b32 s65, v243, 4
	v_readlane_b32 s66, v243, 5
	v_readlane_b32 s67, v243, 6
	v_readlane_b32 s68, v243, 7
	v_readlane_b32 s69, v243, 8
	v_readlane_b32 s70, v243, 9
	v_readlane_b32 s71, v243, 10
	v_readlane_b32 s72, v243, 11
	v_readlane_b32 s73, v243, 12
	v_readlane_b32 s74, v243, 13
	v_readlane_b32 s75, v243, 14
	v_readlane_b32 s76, v243, 15
	v_readlane_b32 s77, v243, 16
	s_waitcnt vmcnt(0)
	v_pk_add_f32 v[126:127], v[126:127], v[216:217]
	v_pk_add_f32 v[124:125], v[124:125], v[214:215]
	v_pk_add_f32 v[116:117], v[116:117], v[222:223]
	v_pk_add_f32 v[122:123], v[122:123], v[220:221]
	v_pk_add_f32 v[120:121], v[120:121], v[218:219]
	v_pk_add_f32 v[214:215], v[112:113], v[226:227]
	global_store_dwordx4 v[232:233], v[124:127], off
	global_store_dwordx4 v[232:233], v[120:123], off offset:16
	v_cvt_pk_bf16_f32 v112, v124, v125
	v_mul_f32_e32 v125, v125, v125
	v_mul_f32_e32 v213, v117, v117
	v_pk_add_f32 v[118:119], v[118:119], v[224:225]
	v_fmac_f32_e32 v125, v124, v124
	v_fmac_f32_e32 v213, v116, v116
	v_fmac_f32_e32 v125, v126, v126
	v_fmac_f32_e32 v213, v118, v118
	v_fmac_f32_e32 v125, v127, v127
	v_fmac_f32_e32 v213, v119, v119
	v_fmac_f32_e32 v125, v120, v120
	v_fmac_f32_e32 v213, v214, v214
	v_pk_add_f32 v[216:217], v[114:115], v[228:229]
	v_fmac_f32_e32 v125, v121, v121
	v_fmac_f32_e32 v213, v215, v215
	v_fmac_f32_e32 v125, v122, v122
	v_fmac_f32_e32 v213, v216, v216
	v_fmac_f32_e32 v125, v123, v123
	v_fmac_f32_e32 v213, v217, v217
	v_cvt_pk_bf16_f32 v114, v120, v121
	v_add_f32_e32 v120, v125, v213
	ds_bpermute_b32 v121, v212, v120
	v_cvt_pk_bf16_f32 v113, v126, v127
	v_cvt_pk_bf16_f32 v115, v122, v123
	global_store_dwordx4 v[230:231], v[112:115], off
	global_store_dwordx4 v[232:233], v[116:119], off offset:512
	global_store_dwordx4 v[232:233], v[214:217], off offset:528
	v_cvt_pk_bf16_f32 v122, v116, v117
	s_waitcnt lgkmcnt(0)
	v_add_f32_e32 v112, v120, v121
	v_lshlrev_b32_e32 v120, 2, v234
	ds_bpermute_b32 v113, v120, v112
	v_cvt_pk_bf16_f32 v123, v118, v119
	v_cvt_pk_bf16_f32 v124, v214, v215
	v_cvt_pk_bf16_f32 v125, v216, v217
	global_store_dwordx4 v[230:231], v[122:125], off offset:256
	s_and_saveexec_b64 s[24:25], s[0:1]
	s_cbranch_execz .LBB0_731
	s_waitcnt lgkmcnt(0)
	v_add_f32_e32 v114, v112, v113
	v_lshlrev_b64 v[112:113], 7, v[196:197]
	v_lshl_add_u64 v[112:113], s[8:9], 0, v[112:113]
	v_lshl_add_u64 v[112:113], s[22:23], 2, v[112:113]
	s_lshl_b32 s12, s41, 2
	v_lshl_add_u64 v[112:113], v[112:113], 0, s[12:13]
	global_store_dword v[112:113], v114, off

; #define PG8_STAGE(bufoff, gbase, voff) do { _Pragma("unroll") for (int _i = 0; _i < 2; ++_i) \
;     __builtin_amdgcn_global_load_lds((const unsigned*)((const char*)(gbase) + (voff)[_i]), (LAS unsigned*)(lds + (bufoff) + ldsw + _i * 8192), 16, 0, 0); } while (0)
; #define PG8_LDA(dst, b, h) do { _Pragma("unroll") for (int m = 0; m < 4; ++m) _Pragma("unroll") for (int k = 0; k < 2; ++k) dst[m][k] = *(const LAS bf16x8*)(lds + PG8_SA(b, h) + aoff + m * 2048 + k * 1024); } while (0)
; #define PG8_LDB(dst, b, h) do { _Pragma("unroll") for (int n = 0; n < 2; ++n) _Pragma("unroll") for (int k = 0; k < 2; ++k) dst[n][k] = *(const LAS bf16x8*)(lds + PG8_SB(b, h) + boff + n * 2048 + k * 1024); } while (0)
; #define PG8_MMA(ai, bj, At, Bt) do { __builtin_amdgcn_s_setprio(1); _Pragma("unroll") for (int m = 0; m < 4; ++m) _Pragma("unroll") for (int n = 0; n < 2; ++n) _Pragma("unroll") for (int k = 0; k < 2; ++k) \
;     acc[ai][bj][m][n] = __builtin_amdgcn_mfma_f32_16x16x32_bf16(Bt[n][k], At[m][k], acc[ai][bj][m][n], 0, 0, 0); __builtin_amdgcn_s_setprio(0); } while (0)
; #define PG8_WAIT_V(n) asm volatile("s_waitcnt vmcnt(" #n ")" ::: "memory")
; #define PG8_WAIT_L(n) asm volatile("s_waitcnt lgkmcnt(" #n ")" ::: "memory")
; #define PG8_BAR __builtin_amdgcn_s_barrier()
; #define PG8_SCHED __builtin_amdgcn_sched_barrier(0)
; template <class Epi, class Sched = StaticOrder>
; DI void gemm_phase(LAS unsigned char* lds, const Gemm g, const Sched& S, const Epi& E) {
;     ...
;     for (int t = 0; t < nt; t += 2) {
;       const bool last = (t == nt - 2);
;       const char* a1 = cA + (size_t)(t + 1) * kstep;
;       const char* a2 = last ? nA : cA + (size_t)(t + 2) * kstep; const char* b2 = last ? nB : cB + (size_t)(t + 2) * kstep;
;       const char* a3 = a2 + kstep; const char* b3 = b2 + kstep;
;       PG8_LDB(B0, 0, 0); PG8_SCHED; PG8_LDA(At, 0, 0); PG8_STAGE(PG8_SA(1, 1), a1 + hstep, voffA);
;       PG8_WAIT_L(8); PG8_BAR; PG8_WAIT_L(0); PG8_MMA(0, 0, At, B0); PG8_BAR; PG8_SCHED;
;       PG8_LDB(B1, 0, 1); PG8_STAGE(PG8_SB(0, 0), b2, voffB);
;       PG8_BAR; PG8_WAIT_L(0); PG8_MMA(0, 1, At, B1); PG8_BAR;
;       PG8_LDA(At, 0, 1); PG8_STAGE(PG8_SA(0, 0), a2, voffA);
;       PG8_BAR; PG8_WAIT_L(0); PG8_MMA(1, 0, At, B0); PG8_BAR; PG8_SCHED;
;       PG8_STAGE(PG8_SB(0, 1), b2 + hstep, voffB);
;       PG8_WAIT_V(6); PG8_BAR; PG8_MMA(1, 1, At, B1); PG8_BAR;
.LBB0_811:
	s_add_u32 s46, s14, 0xfff80080
	s_addc_u32 s47, s15, -1
	s_cmp_eq_u32 s52, 28
	s_cselect_b32 s49, s37, s47
	s_cselect_b32 s48, s42, s46
	s_cselect_b32 s47, s35, s45
	s_cselect_b32 s46, s43, s44
	v_lshl_add_u64 v[196:197], s[14:15], 0, v[170:171]
	s_add_i32 m0, s62, 0xc000
	ds_read_b128 v[80:83], v202
	ds_read_b128 v[84:87], v202 offset:1024
	ds_read_b128 v[92:95], v202 offset:2048
	ds_read_b128 v[96:99], v202 offset:3072
	ds_read_b128 v[180:183], v202 offset:4096
	ds_read_b128 v[184:187], v202 offset:5120
	ds_read_b128 v[188:191], v202 offset:6144
	ds_read_b128 v[192:195], v202 offset:7168
	global_load_lds_dwordx4 v[196:197], off
	v_lshl_add_u64 v[196:197], s[14:15], 0, v[172:173]
	s_add_i32 m0, s62, 0xe000
	s_nop 0
	global_load_lds_dwordx4 v[196:197], off
	s_waitcnt lgkmcnt(0)
	s_setprio 1
	s_barrier
	v_mfma_f32_16x16x32_bf16 v[156:159], v[64:67], v[80:83], v[156:159]
	v_mfma_f32_16x16x32_bf16 v[144:147], v[72:75], v[80:83], v[144:147]
	v_mfma_f32_16x16x32_bf16 v[140:143], v[64:67], v[92:95], v[140:143]
	v_mfma_f32_16x16x32_bf16 v[132:135], v[72:75], v[92:95], v[132:135]
	v_mfma_f32_16x16x32_bf16 v[124:127], v[64:67], v[180:183], v[124:127]
	v_mfma_f32_16x16x32_bf16 v[116:119], v[72:75], v[180:183], v[116:119]
	v_mfma_f32_16x16x32_bf16 v[112:115], v[64:67], v[188:191], v[112:115]
	v_mfma_f32_16x16x32_bf16 v[108:111], v[72:75], v[188:191], v[108:111]
	v_mfma_f32_16x16x32_bf16 v[156:159], v[68:71], v[84:87], v[156:159]
	v_mfma_f32_16x16x32_bf16 v[144:147], v[76:79], v[84:87], v[144:147]
	v_mfma_f32_16x16x32_bf16 v[140:143], v[68:71], v[96:99], v[140:143]
	v_mfma_f32_16x16x32_bf16 v[132:135], v[76:79], v[96:99], v[132:135]
	v_mfma_f32_16x16x32_bf16 v[124:127], v[68:71], v[184:187], v[124:127]
	v_mfma_f32_16x16x32_bf16 v[116:119], v[76:79], v[184:187], v[116:119]
	v_mfma_f32_16x16x32_bf16 v[112:115], v[68:71], v[192:195], v[112:115]
	v_mfma_f32_16x16x32_bf16 v[108:111], v[76:79], v[192:195], v[108:111]
	s_barrier
	s_setprio 0
	s_add_i32 s53, s72, s60
	v_lshl_add_u64 v[196:197], s[46:47], 0, v[164:165]
	s_mov_b32 m0, s53
	ds_read_b128 v[206:209], v203
	ds_read_b128 v[212:215], v203 offset:1024
	ds_read_b128 v[216:219], v203 offset:2048
	ds_read_b128 v[220:223], v203 offset:3072
	global_load_lds_dwordx4 v[196:197], off
	v_lshl_add_u64 v[232:233], s[46:47], 0, v[160:161]
	s_add_i32 m0, s53, 0x2000
	s_nop 0
	global_load_lds_dwordx4 v[232:233], off
	s_waitcnt lgkmcnt(0)
	s_setprio 1
	s_barrier
	v_mfma_f32_16x16x32_bf16 v[152:155], v[206:209], v[80:83], v[152:155]
	v_mfma_f32_16x16x32_bf16 v[80:83], v[216:219], v[80:83], v[148:151]
	v_mfma_f32_16x16x32_bf16 v[152:155], v[212:215], v[84:87], v[152:155]
	v_mfma_f32_16x16x32_bf16 v[80:83], v[220:223], v[84:87], v[80:83]
	v_mfma_f32_16x16x32_bf16 v[84:87], v[206:209], v[92:95], v[136:139]
	v_mfma_f32_16x16x32_bf16 v[92:95], v[216:219], v[92:95], v[128:131]
	v_mfma_f32_16x16x32_bf16 v[104:107], v[216:219], v[180:183], v[104:107]
	v_mfma_f32_16x16x32_bf16 v[100:103], v[206:209], v[188:191], v[100:103]
	v_mfma_f32_16x16x32_bf16 v[88:91], v[216:219], v[188:191], v[88:91]
	v_mfma_f32_16x16x32_bf16 v[84:87], v[212:215], v[96:99], v[84:87]
	v_mfma_f32_16x16x32_bf16 v[92:95], v[220:223], v[96:99], v[92:95]
	v_mfma_f32_16x16x32_bf16 v[96:99], v[206:209], v[180:183], v[120:123]
	v_mfma_f32_16x16x32_bf16 v[104:107], v[220:223], v[184:187], v[104:107]
	v_mfma_f32_16x16x32_bf16 v[100:103], v[212:215], v[192:195], v[100:103]
	v_mfma_f32_16x16x32_bf16 v[88:91], v[220:223], v[192:195], v[88:91]
	v_mfma_f32_16x16x32_bf16 v[96:99], v[212:215], v[184:187], v[96:99]
	s_barrier
	s_setprio 0
	s_mov_b32 m0, s62
	v_lshl_add_u64 v[234:235], s[48:49], 0, v[166:167]
	ds_read_b128 v[120:123], v202 offset:16384
	ds_read_b128 v[128:131], v202 offset:17408
	ds_read_b128 v[136:139], v202 offset:18432
	ds_read_b128 v[148:151], v202 offset:19456
	ds_read_b128 v[180:183], v202 offset:20480
	ds_read_b128 v[184:187], v202 offset:21504
	ds_read_b128 v[188:191], v202 offset:22528
	ds_read_b128 v[192:195], v202 offset:23552
	global_load_lds_dwordx4 v[234:235], off
	v_lshl_add_u64 v[236:237], s[48:49], 0, v[162:163]
	s_mov_b32 m0, s63
	s_nop 0
	global_load_lds_dwordx4 v[236:237], off
	s_waitcnt vmcnt(10)
	s_waitcnt lgkmcnt(0)
	s_setprio 1
	s_barrier
	v_mfma_f32_16x16x32_bf16 v[60:63], v[64:67], v[120:123], v[60:63]
	v_mfma_f32_16x16x32_bf16 v[48:51], v[72:75], v[120:123], v[48:51]
	v_mfma_f32_16x16x32_bf16 v[44:47], v[64:67], v[136:139], v[44:47]
	v_mfma_f32_16x16x32_bf16 v[36:39], v[72:75], v[136:139], v[36:39]
	v_mfma_f32_16x16x32_bf16 v[28:31], v[64:67], v[180:183], v[28:31]
	v_mfma_f32_16x16x32_bf16 v[20:23], v[72:75], v[180:183], v[20:23]
	v_mfma_f32_16x16x32_bf16 v[16:19], v[64:67], v[188:191], v[16:19]
	v_mfma_f32_16x16x32_bf16 v[12:15], v[72:75], v[188:191], v[12:15]
	v_mfma_f32_16x16x32_bf16 v[60:63], v[68:71], v[128:131], v[60:63]
	v_mfma_f32_16x16x32_bf16 v[48:51], v[76:79], v[128:131], v[48:51]
	v_mfma_f32_16x16x32_bf16 v[44:47], v[68:71], v[148:151], v[44:47]
	v_mfma_f32_16x16x32_bf16 v[36:39], v[76:79], v[148:151], v[36:39]
	v_mfma_f32_16x16x32_bf16 v[28:31], v[68:71], v[184:187], v[28:31]
	v_mfma_f32_16x16x32_bf16 v[20:23], v[76:79], v[184:187], v[20:23]
	v_mfma_f32_16x16x32_bf16 v[16:19], v[68:71], v[192:195], v[16:19]
	v_mfma_f32_16x16x32_bf16 v[12:15], v[76:79], v[192:195], v[12:15]
	s_barrier
	s_setprio 0
	s_add_u32 s54, s46, 0x80000
	s_addc_u32 s55, s47, 0
	s_add_i32 s53, s73, s60
	v_lshl_add_u64 v[64:65], s[54:55], 0, v[164:165]
	s_mov_b32 m0, s53
	s_nop 0
	global_load_lds_dwordx4 v[64:65], off
	v_lshl_add_u64 v[64:65], s[54:55], 0, v[160:161]
	s_add_i32 m0, s53, 0x2000
	s_nop 0
	global_load_lds_dwordx4 v[64:65], off
	s_add_i32 s53, 0, 0x18000
	v_add_u32_e32 v76, s53, v198
	ds_read_b128 v[64:67], v76
	ds_read_b128 v[68:71], v76 offset:1024
	ds_read_b128 v[72:75], v76 offset:2048
	ds_read_b128 v[76:79], v76 offset:3072
	s_waitcnt vmcnt(6)
	s_setprio 1
	s_barrier
; #define PG8_STAGE(bufoff, gbase, voff) do { _Pragma("unroll") for (int _i = 0; _i < 2; ++_i) \
;     __builtin_amdgcn_global_load_lds((const unsigned*)((const char*)(gbase) + (voff)[_i]), (LAS unsigned*)(lds + (bufoff) + ldsw + _i * 8192), 16, 0, 0); } while (0)
; #define PG8_LDA(dst, b, h) do { _Pragma("unroll") for (int m = 0; m < 4; ++m) _Pragma("unroll") for (int k = 0; k < 2; ++k) dst[m][k] = *(const LAS bf16x8*)(lds + PG8_SA(b, h) + aoff + m * 2048 + k * 1024); } while (0)
; #define PG8_LDB(dst, b, h) do { _Pragma("unroll") for (int n = 0; n < 2; ++n) _Pragma("unroll") for (int k = 0; k < 2; ++k) dst[n][k] = *(const LAS bf16x8*)(lds + PG8_SB(b, h) + boff + n * 2048 + k * 1024); } while (0)
; #define PG8_MMA(ai, bj, At, Bt) do { __builtin_amdgcn_s_setprio(1); _Pragma("unroll") for (int m = 0; m < 4; ++m) _Pragma("unroll") for (int n = 0; n < 2; ++n) _Pragma("unroll") for (int k = 0; k < 2; ++k) \
;     acc[ai][bj][m][n] = __builtin_amdgcn_mfma_f32_16x16x32_bf16(Bt[n][k], At[m][k], acc[ai][bj][m][n], 0, 0, 0); __builtin_amdgcn_s_setprio(0); } while (0)
; #define PG8_WAIT_V(n) asm volatile("s_waitcnt vmcnt(" #n ")" ::: "memory")
; #define PG8_WAIT_L(n) asm volatile("s_waitcnt lgkmcnt(" #n ")" ::: "memory")
; #define PG8_BAR __builtin_amdgcn_s_barrier()
; #define PG8_SCHED __builtin_amdgcn_sched_barrier(0)
; template <class Epi, class Sched = StaticOrder>
; DI void gemm_phase(LAS unsigned char* lds, const Gemm g, const Sched& S, const Epi& E) {
;     ...
;       PG8_WAIT_V(6); PG8_BAR; PG8_MMA(1, 1, At, B1); PG8_BAR;
;       PG8_LDB(B0, 1, 0); PG8_SCHED; PG8_LDA(At, 1, 0); PG8_STAGE(PG8_SA(0, 1), a2 + hstep, voffA);
;       PG8_WAIT_L(8); PG8_BAR; PG8_WAIT_L(0); PG8_MMA(0, 0, At, B0); PG8_BAR; PG8_SCHED;
;       PG8_LDB(B1, 1, 1); PG8_STAGE(PG8_SB(1, 0), b3, voffB);
;       PG8_BAR; PG8_WAIT_L(0); PG8_MMA(0, 1, At, B1); PG8_BAR;
;       PG8_LDA(At, 1, 1); PG8_STAGE(PG8_SA(1, 0), a3, voffA);
;       PG8_BAR; PG8_WAIT_L(0); PG8_MMA(1, 0, At, B0); PG8_BAR; PG8_SCHED;
	v_mfma_f32_16x16x32_bf16 v[56:59], v[206:209], v[120:123], v[56:59]
	v_mfma_f32_16x16x32_bf16 v[52:55], v[216:219], v[120:123], v[52:55]
	v_mfma_f32_16x16x32_bf16 v[40:43], v[206:209], v[136:139], v[40:43]
	v_mfma_f32_16x16x32_bf16 v[32:35], v[216:219], v[136:139], v[32:35]
	v_mfma_f32_16x16x32_bf16 v[24:27], v[206:209], v[180:183], v[24:27]
	v_mfma_f32_16x16x32_bf16 v[8:11], v[216:219], v[180:183], v[8:11]
	v_mfma_f32_16x16x32_bf16 v[4:7], v[206:209], v[188:191], v[4:7]
	v_mfma_f32_16x16x32_bf16 v[0:3], v[216:219], v[188:191], v[0:3]
	v_mfma_f32_16x16x32_bf16 v[56:59], v[212:215], v[128:131], v[56:59]
	v_mfma_f32_16x16x32_bf16 v[52:55], v[220:223], v[128:131], v[52:55]
	v_mfma_f32_16x16x32_bf16 v[40:43], v[212:215], v[148:151], v[40:43]
	v_mfma_f32_16x16x32_bf16 v[32:35], v[220:223], v[148:151], v[32:35]
	v_mfma_f32_16x16x32_bf16 v[24:27], v[212:215], v[184:187], v[24:27]
	v_mfma_f32_16x16x32_bf16 v[8:11], v[220:223], v[184:187], v[8:11]
	v_mfma_f32_16x16x32_bf16 v[4:7], v[212:215], v[192:195], v[4:7]
	v_mfma_f32_16x16x32_bf16 v[0:3], v[220:223], v[192:195], v[0:3]
	s_barrier
	s_setprio 0
	s_add_u32 s48, s48, 0x80000
	s_addc_u32 s49, s49, 0
	s_mov_b32 m0, s64
	v_lshl_add_u64 v[136:137], s[48:49], 0, v[166:167]
	ds_read_b128 v[120:123], v202 offset:32768
	ds_read_b128 v[128:131], v202 offset:33792
	ds_read_b128 v[180:183], v202 offset:34816
	ds_read_b128 v[184:187], v202 offset:35840
	ds_read_b128 v[188:191], v202 offset:36864
	ds_read_b128 v[192:195], v202 offset:37888
	ds_read_b128 v[206:209], v202 offset:38912
	ds_read_b128 v[212:215], v202 offset:39936
	global_load_lds_dwordx4 v[136:137], off
	v_lshl_add_u64 v[136:137], s[48:49], 0, v[162:163]
	s_mov_b32 m0, s65
	s_nop 0
	global_load_lds_dwordx4 v[136:137], off
	s_waitcnt lgkmcnt(0)
	s_setprio 1
	s_barrier
	v_mfma_f32_16x16x32_bf16 v[136:139], v[64:67], v[120:123], v[156:159]
	v_mfma_f32_16x16x32_bf16 v[156:159], v[68:71], v[128:131], v[136:139]
	v_mfma_f32_16x16x32_bf16 v[136:139], v[72:75], v[120:123], v[144:147]
	v_mfma_f32_16x16x32_bf16 v[144:147], v[76:79], v[128:131], v[136:139]
	v_mfma_f32_16x16x32_bf16 v[136:139], v[64:67], v[180:183], v[140:143]
	v_mfma_f32_16x16x32_bf16 v[132:135], v[72:75], v[180:183], v[132:135]
	v_mfma_f32_16x16x32_bf16 v[124:127], v[64:67], v[188:191], v[124:127]
	v_mfma_f32_16x16x32_bf16 v[116:119], v[72:75], v[188:191], v[116:119]
	v_mfma_f32_16x16x32_bf16 v[112:115], v[64:67], v[206:209], v[112:115]
	v_mfma_f32_16x16x32_bf16 v[108:111], v[72:75], v[206:209], v[108:111]
	v_mfma_f32_16x16x32_bf16 v[140:143], v[68:71], v[184:187], v[136:139]
	v_mfma_f32_16x16x32_bf16 v[132:135], v[76:79], v[184:187], v[132:135]
	v_mfma_f32_16x16x32_bf16 v[124:127], v[68:71], v[192:195], v[124:127]
	v_mfma_f32_16x16x32_bf16 v[116:119], v[76:79], v[192:195], v[116:119]
	v_mfma_f32_16x16x32_bf16 v[112:115], v[68:71], v[212:215], v[112:115]
	v_mfma_f32_16x16x32_bf16 v[108:111], v[76:79], v[212:215], v[108:111]
	s_barrier
	s_setprio 0
	s_add_i32 s48, 0, 0x1c000
	v_add_u32_e32 v136, s48, v198
	s_add_i32 s49, s53, s60
	ds_read_b128 v[216:219], v136
	ds_read_b128 v[220:223], v136 offset:1024
	ds_read_b128 v[224:227], v136 offset:2048
	ds_read_b128 v[228:231], v136 offset:3072
	v_lshl_add_u64 v[136:137], v[196:197], 0, s[24:25]
	s_mov_b32 m0, s49
	s_nop 0
	global_load_lds_dwordx4 v[136:137], off
	v_lshl_add_u64 v[136:137], v[232:233], 0, s[24:25]
	s_add_i32 m0, s49, 0x2000
	s_nop 0
	global_load_lds_dwordx4 v[136:137], off
	s_waitcnt lgkmcnt(0)
	s_setprio 1
	s_barrier
	v_mfma_f32_16x16x32_bf16 v[80:83], v[224:227], v[120:123], v[80:83]
	v_mfma_f32_16x16x32_bf16 v[136:139], v[216:219], v[120:123], v[152:155]
	v_mfma_f32_16x16x32_bf16 v[148:151], v[228:231], v[128:131], v[80:83]
	v_mfma_f32_16x16x32_bf16 v[80:83], v[216:219], v[180:183], v[84:87]
	v_mfma_f32_16x16x32_bf16 v[152:155], v[220:223], v[128:131], v[136:139]
	v_mfma_f32_16x16x32_bf16 v[136:139], v[220:223], v[184:187], v[80:83]
	v_mfma_f32_16x16x32_bf16 v[80:83], v[224:227], v[180:183], v[92:95]
	v_mfma_f32_16x16x32_bf16 v[128:131], v[228:231], v[184:187], v[80:83]
	v_mfma_f32_16x16x32_bf16 v[80:83], v[216:219], v[188:191], v[96:99]
	v_mfma_f32_16x16x32_bf16 v[120:123], v[220:223], v[192:195], v[80:83]
	v_mfma_f32_16x16x32_bf16 v[80:83], v[224:227], v[188:191], v[104:107]
	v_mfma_f32_16x16x32_bf16 v[104:107], v[228:231], v[192:195], v[80:83]
	v_mfma_f32_16x16x32_bf16 v[80:83], v[216:219], v[206:209], v[100:103]
	v_mfma_f32_16x16x32_bf16 v[100:103], v[220:223], v[212:215], v[80:83]
	v_mfma_f32_16x16x32_bf16 v[80:83], v[224:227], v[206:209], v[88:91]
	v_mfma_f32_16x16x32_bf16 v[88:91], v[228:231], v[212:215], v[80:83]
	s_barrier
	s_setprio 0
	s_mov_b32 m0, s67
	v_lshl_add_u64 v[196:197], v[234:235], 0, s[24:25]
	s_nop 2
	ds_read_b128 v[80:83], v202 offset:49152
	ds_read_b128 v[84:87], v202 offset:50176
	ds_read_b128 v[92:95], v202 offset:51200
	ds_read_b128 v[96:99], v202 offset:52224
	ds_read_b128 v[180:183], v202 offset:53248
	ds_read_b128 v[184:187], v202 offset:54272
	ds_read_b128 v[188:191], v202 offset:55296
	ds_read_b128 v[192:195], v202 offset:56320
	global_load_lds_dwordx4 v[196:197], off
	v_lshl_add_u64 v[196:197], v[236:237], 0, s[24:25]
	s_mov_b32 m0, s68
	s_nop 0
	global_load_lds_dwordx4 v[196:197], off
	s_waitcnt vmcnt(10)
	s_waitcnt lgkmcnt(0)
	s_setprio 1
	s_barrier
; #define PG8_STAGE(bufoff, gbase, voff) do { _Pragma("unroll") for (int _i = 0; _i < 2; ++_i) \
;     __builtin_amdgcn_global_load_lds((const unsigned*)((const char*)(gbase) + (voff)[_i]), (LAS unsigned*)(lds + (bufoff) + ldsw + _i * 8192), 16, 0, 0); } while (0)
; #define PG8_MMA(ai, bj, At, Bt) do { __builtin_amdgcn_s_setprio(1); _Pragma("unroll") for (int m = 0; m < 4; ++m) _Pragma("unroll") for (int n = 0; n < 2; ++n) _Pragma("unroll") for (int k = 0; k < 2; ++k) \
;     acc[ai][bj][m][n] = __builtin_amdgcn_mfma_f32_16x16x32_bf16(Bt[n][k], At[m][k], acc[ai][bj][m][n], 0, 0, 0); __builtin_amdgcn_s_setprio(0); } while (0)
; #define PG8_WAIT_V(n) asm volatile("s_waitcnt vmcnt(" #n ")" ::: "memory")
; #define PG8_WAIT_L(n) asm volatile("s_waitcnt lgkmcnt(" #n ")" ::: "memory")
; #define PG8_BAR __builtin_amdgcn_s_barrier()
; #define PG8_SCHED __builtin_amdgcn_sched_barrier(0)
;   DI void operator()(const f32x4 (&acc)[2][2][4][2], const Unit& u, int wr, int wc, int fr, int fq) const {
;     const int col = u.pn * 128 + wc * 32 + 8 * fq;
;     float w0[8], w1[8], w2[8], bb[8];
; #pragma unroll
;     for (int e = 0; e < 8; ++e) { w0[e] = cw[col + e]; w1[e] = cw[5632 + col + e]; w2[e] = cw[2 * 5632 + col + e]; bb[e] = cb[col + e]; }
; #pragma unroll
;     for (int ai = 0; ai < 2; ++ai) {
;       const int row0 = u.pm * BM + ai * HALF + wr * 64, span = row0 >> 6;
;       float rsv[4];
; #pragma unroll
;       for (int m = 0; m < 4; ++m) rsv[m] = row_rstd(ssq, row0 + 16 * m + fr, fq);
; template <class Epi, class Sched = StaticOrder>
; DI void gemm_phase(LAS unsigned char* lds, const Gemm g, const Sched& S, const Epi& E) {
;     ...
;       PG8_BAR; PG8_WAIT_L(0); PG8_MMA(1, 0, At, B0); PG8_BAR; PG8_SCHED;
;       PG8_STAGE(PG8_SB(1, 1), b3 + hstep, voffB);
;       PG8_WAIT_V(6); PG8_BAR; PG8_MMA(1, 1, At, B1); PG8_BAR;
;     }
	v_mfma_f32_16x16x32_bf16 v[60:63], v[64:67], v[80:83], v[60:63]
	v_mfma_f32_16x16x32_bf16 v[48:51], v[72:75], v[80:83], v[48:51]
	v_mfma_f32_16x16x32_bf16 v[44:47], v[64:67], v[92:95], v[44:47]
	v_mfma_f32_16x16x32_bf16 v[36:39], v[72:75], v[92:95], v[36:39]
	v_mfma_f32_16x16x32_bf16 v[28:31], v[64:67], v[180:183], v[28:31]
	v_mfma_f32_16x16x32_bf16 v[20:23], v[72:75], v[180:183], v[20:23]
	v_mfma_f32_16x16x32_bf16 v[16:19], v[64:67], v[188:191], v[16:19]
	v_mfma_f32_16x16x32_bf16 v[12:15], v[72:75], v[188:191], v[12:15]
	v_mfma_f32_16x16x32_bf16 v[60:63], v[68:71], v[84:87], v[60:63]
	v_mfma_f32_16x16x32_bf16 v[48:51], v[76:79], v[84:87], v[48:51]
	v_mfma_f32_16x16x32_bf16 v[44:47], v[68:71], v[96:99], v[44:47]
	v_mfma_f32_16x16x32_bf16 v[36:39], v[76:79], v[96:99], v[36:39]
	v_mfma_f32_16x16x32_bf16 v[28:31], v[68:71], v[184:187], v[28:31]
	v_mfma_f32_16x16x32_bf16 v[20:23], v[76:79], v[184:187], v[20:23]
	v_mfma_f32_16x16x32_bf16 v[16:19], v[68:71], v[192:195], v[16:19]
	v_mfma_f32_16x16x32_bf16 v[12:15], v[76:79], v[192:195], v[12:15]
	s_barrier
	s_setprio 0
	s_add_u32 s46, s46, 0x80080
	s_addc_u32 s47, s47, 0
	s_add_i32 s48, s48, s60
	v_lshl_add_u64 v[64:65], s[46:47], 0, v[164:165]
	s_mov_b32 m0, s48
	s_nop 0
	global_load_lds_dwordx4 v[64:65], off
	v_lshl_add_u64 v[64:65], s[46:47], 0, v[160:161]
	s_add_i32 m0, s48, 0x2000
	s_nop 0
	global_load_lds_dwordx4 v[64:65], off
	ds_read_b128 v[64:67], v201
	ds_read_b128 v[68:71], v201 offset:1024
	ds_read_b128 v[72:75], v201 offset:2048
	ds_read_b128 v[76:79], v201 offset:3072
	s_waitcnt vmcnt(6)
	s_setprio 1
	s_barrier
	v_mfma_f32_16x16x32_bf16 v[56:59], v[216:219], v[80:83], v[56:59]
	v_mfma_f32_16x16x32_bf16 v[52:55], v[224:227], v[80:83], v[52:55]
	v_mfma_f32_16x16x32_bf16 v[40:43], v[216:219], v[92:95], v[40:43]
	v_mfma_f32_16x16x32_bf16 v[32:35], v[224:227], v[92:95], v[32:35]
	v_mfma_f32_16x16x32_bf16 v[24:27], v[216:219], v[180:183], v[24:27]
	v_mfma_f32_16x16x32_bf16 v[8:11], v[224:227], v[180:183], v[8:11]
	v_mfma_f32_16x16x32_bf16 v[4:7], v[216:219], v[188:191], v[4:7]
	v_mfma_f32_16x16x32_bf16 v[0:3], v[224:227], v[188:191], v[0:3]
	v_mfma_f32_16x16x32_bf16 v[56:59], v[220:223], v[84:87], v[56:59]
	v_mfma_f32_16x16x32_bf16 v[52:55], v[228:231], v[84:87], v[52:55]
	v_mfma_f32_16x16x32_bf16 v[40:43], v[220:223], v[96:99], v[40:43]
	v_mfma_f32_16x16x32_bf16 v[32:35], v[228:231], v[96:99], v[32:35]
	v_mfma_f32_16x16x32_bf16 v[24:27], v[220:223], v[184:187], v[24:27]
	v_mfma_f32_16x16x32_bf16 v[8:11], v[228:231], v[184:187], v[8:11]
	v_mfma_f32_16x16x32_bf16 v[4:7], v[220:223], v[192:195], v[4:7]
	v_mfma_f32_16x16x32_bf16 v[0:3], v[228:231], v[192:195], v[0:3]
	s_add_i32 s52, s52, 2
	s_add_u32 s14, s14, 0x100
	s_addc_u32 s15, s15, 0
	s_add_u32 s44, s44, 0x100
	s_addc_u32 s45, s45, 0
	s_cmp_gt_u32 s52, 29
	s_barrier
	s_setprio 0
	s_cbranch_scc0 .LBB0_811
	s_waitcnt lgkmcnt(0)
	s_lshl_b32 s35, s12, 8
	s_add_i32 s35, s35, s66
	v_or_b32_e32 v190, s35, v179
	v_ashrrev_i32_e32 v191, 31, v190
	v_lshlrev_b64 v[64:65], 7, v[190:191]
	v_or_b32_e32 v188, 16, v190
	v_lshl_add_u64 v[64:65], v[168:169], 0, v[64:65]
	v_ashrrev_i32_e32 v189, 31, v188
	global_load_dwordx4 v[192:195], v[64:65], off
	global_load_dwordx4 v[206:209], v[64:65], off offset:16
	v_lshlrev_b64 v[64:65], 7, v[188:189]
	v_lshl_add_u64 v[64:65], v[168:169], 0, v[64:65]
	global_load_dwordx4 v[212:215], v[64:65], off
	global_load_dwordx4 v[216:219], v[64:65], off offset:16
	v_or_b32_e32 v186, 32, v190
	v_ashrrev_i32_e32 v187, 31, v186
	v_lshlrev_b64 v[64:65], 7, v[186:187]
	v_or_b32_e32 v184, 48, v190
	v_lshl_add_u64 v[64:65], v[168:169], 0, v[64:65]
	v_ashrrev_i32_e32 v185, 31, v184
	global_load_dwordx4 v[220:223], v[64:65], off
	global_load_dwordx4 v[224:227], v[64:65], off offset:16
	v_lshlrev_b64 v[64:65], 7, v[184:185]
	v_lshl_add_u64 v[64:65], v[168:169], 0, v[64:65]
	global_load_dwordx4 v[228:231], v[64:65], off
	global_load_dwordx4 v[232:235], v[64:65], off offset:16
	v_lshl_or_b32 v180, s13, 7, v200
	v_and_b32_e32 v65, 64, v204
	v_xor_b32_e32 v64, 16, v204
	v_ashrrev_i32_e32 v181, 31, v180
	v_add_u32_e32 v65, 64, v65
	v_readlane_b32 s44, v243, 3
	v_xor_b32_e32 v66, 32, v204
	v_lshlrev_b64 v[182:183], 2, v[180:181]
	v_cmp_lt_i32_e32 vcc, v64, v65
	v_readlane_b32 s52, v243, 11
	v_readlane_b32 s53, v243, 12
	v_cndmask_b32_e32 v64, v204, v64, vcc
	v_cmp_lt_i32_e32 vcc, v66, v65
	v_lshl_add_u64 v[92:93], s[52:53], 0, v[182:183]
	v_readlane_b32 s54, v243, 13
	v_cndmask_b32_e32 v65, v204, v66, vcc
	v_add_co_u32_e32 v94, vcc, 0x5000, v92
	v_readlane_b32 s55, v243, 14
	s_nop 0
	v_addc_co_u32_e32 v95, vcc, 0, v93, vcc
	v_add_co_u32_e32 v96, vcc, 0xb000, v92
	v_lshl_add_u64 v[72:73], s[54:55], 0, v[182:183]
	v_lshl_add_u64 v[74:75], v[92:93], 0, s[26:27]
	v_lshl_add_u64 v[76:77], v[92:93], 0, s[28:29]
	v_addc_co_u32_e32 v97, vcc, 0, v93, vcc
	v_lshlrev_b32_e32 v187, 2, v64
	v_lshlrev_b32_e32 v185, 2, v65
	global_load_dwordx4 v[64:67], v[92:93], off offset:16
	global_load_dwordx4 v[80:83], v[92:93], off
	global_load_dwordx4 v[68:71], v[72:73], off offset:16
	global_load_dwordx4 v[84:87], v[72:73], off
	s_nop 0
	global_load_dwordx4 v[72:75], v[74:75], off offset:16
	s_nop 0
	global_load_dwordx4 v[76:79], v[76:77], off offset:16
	s_nop 0
	global_load_dwordx4 v[92:95], v[94:95], off offset:2048
	s_nop 0
	global_load_dwordx4 v[96:99], v[96:97], off
	v_mov_b32_e32 v211, 0
	v_mov_b32_e32 v205, 0
	v_readlane_b32 s45, v243, 4
	v_readlane_b32 s46, v243, 5
	v_readlane_b32 s47, v243, 6
	v_readlane_b32 s48, v243, 7
	v_readlane_b32 s49, v243, 8
	v_readlane_b32 s50, v243, 9
	v_readlane_b32 s51, v243, 10
	v_readlane_b32 s56, v243, 15
	v_readlane_b32 s57, v243, 16
	v_readlane_b32 s58, v243, 17
	v_readlane_b32 s59, v243, 18
	s_waitcnt vmcnt(0)
; DI float dpp_ror1(float v) { return __int_as_float(__builtin_amdgcn_update_dpp(0, __float_as_int(v), 0x121, 0xf, 0xf, false)); }
; DI float dpp_ror2(float v) { return __int_as_float(__builtin_amdgcn_update_dpp(0, __float_as_int(v), 0x122, 0xf, 0xf, false)); }
;   DI void operator()(const f32x4 (&acc)[2][2][4][2], const Unit& u, int wr, int wc, int fr, int fq) const {
;     ...
;     for (int ai = 0; ai < 2; ++ai) {
;       const int row0 = u.pm * BM + ai * HALF + wr * 64, span = row0 >> 6;
;       float rsv[4];
; #pragma unroll
;       for (int m = 0; m < 4; ++m) rsv[m] = row_rstd(ssq, row0 + 16 * m + fr, fq);
;       float p1[8], p2[8];
; #pragma unroll
;       for (int e = 0; e < 8; ++e) { p1[e] = 0.f; p2[e] = 0.f; }
; #pragma unroll
;       for (int m = 0; m < 4; ++m) {
;         float g[8], uu[8], a[8];
;         const float rs = rsv[m];
; #pragma unroll
;         for (int e = 0; e < 4; ++e) { g[e] = acc[ai][0][m][0][e] * rs; g[4 + e] = acc[ai][0][m][1][e] * rs; uu[e] = acc[ai][1][m][0][e] * rs; uu[4 + e] = acc[ai][1][m][1][e] * rs; }
; #pragma unroll
;         for (int e = 0; e < 8; ++e) {
;           const float x1 = dpp_ror1(g[e]), x2 = dpp_ror2(g[e]);
;           const float pr1 = (fr == 0) ? p1[e] : x1, pr2 = (fr < 2) ? p2[e] : x2;
;           a[e] = w2[e] * g[e] + w1[e] * pr1 + w0[e] * pr2 + bb[e];
;           p1[e] = x1; p2[e] = x2;
;         }
	v_mov_b32_e32 v196, v192
	v_mov_b32_e32 v197, v206
	v_mov_b32_e32 v206, v193
	v_mov_b32_e32 v192, v194
	v_mov_b32_e32 v193, v208
	v_mov_b32_e32 v208, v195
	v_pk_add_f32 v[194:195], v[196:197], v[206:207]
	v_pk_add_f32 v[192:193], v[192:193], v[208:209]
	v_mov_b32_e32 v196, v212
	v_mov_b32_e32 v197, v216
	v_mov_b32_e32 v216, v213
	v_mov_b32_e32 v206, v214
	v_mov_b32_e32 v207, v218
	v_mov_b32_e32 v218, v215
	v_pk_add_f32 v[192:193], v[194:195], v[192:193]
	v_pk_add_f32 v[194:195], v[196:197], v[216:217]
	v_pk_add_f32 v[196:197], v[206:207], v[218:219]
	v_mov_b32_e32 v208, v220
	v_pk_add_f32 v[194:195], v[194:195], v[196:197]
	v_mov_b32_e32 v197, v192
	v_mov_b32_e32 v196, v194
	v_mov_b32_e32 v192, v195
	v_pk_add_f32 v[192:193], v[196:197], v[192:193]
	ds_bpermute_b32 v195, v187, v193
	ds_bpermute_b32 v194, v187, v192
	v_mov_b32_e32 v209, v224
	v_mov_b32_e32 v224, v221
	v_mov_b32_e32 v212, v222
	v_mov_b32_e32 v213, v226
	s_waitcnt lgkmcnt(0)
	v_pk_add_f32 v[192:193], v[192:193], v[194:195]
	ds_bpermute_b32 v195, v185, v193
	ds_bpermute_b32 v194, v185, v192
	v_mov_b32_e32 v226, v223
	v_mov_b32_e32 v196, v228
	v_mov_b32_e32 v197, v232
	v_mov_b32_e32 v232, v229
	s_waitcnt lgkmcnt(0)
	v_pk_add_f32 v[192:193], v[192:193], v[194:195]
	v_mov_b32_e32 v206, v230
	v_pk_fma_f32 v[192:193], v[192:193], s[30:31], v[178:179] op_sel_hi:[1,0,0]
	v_mov_b32_e32 v207, v234
	v_mul_f32_e32 v189, 0x4b800000, v193
	v_cmp_gt_f32_e64 s[12:13], s74, v193
	v_mov_b32_e32 v234, v231
	v_pk_add_f32 v[208:209], v[208:209], v[224:225]
	v_cndmask_b32_e64 v189, v193, v189, s[12:13]
	v_rsq_f32_e32 v189, v189
	v_pk_add_f32 v[212:213], v[212:213], v[226:227]
	v_pk_add_f32 v[196:197], v[196:197], v[232:233]
	v_pk_add_f32 v[194:195], v[206:207], v[234:235]
	v_mul_f32_e32 v191, 0x45800000, v189
	v_cndmask_b32_e64 v220, v189, v191, s[12:13]
	v_pk_add_f32 v[208:209], v[208:209], v[212:213]
	v_pk_add_f32 v[194:195], v[196:197], v[194:195]
	v_pk_mul_f32 v[156:157], v[156:157], v[220:221] op_sel_hi:[1,0]
	v_mov_b32_e32 v216, 0
	v_mov_b32_e32 v218, 0
	v_mov_b32_e32 v196, v194
	v_mov_b32_e32 v197, v208
	v_mov_b32_e32 v208, v195
	v_mov_b32_dpp v216, v156 row_ror:1 row_mask:0xf bank_mask:0xf
	v_mov_b32_dpp v218, v157 row_ror:1 row_mask:0xf bank_mask:0xf
	v_pk_add_f32 v[194:195], v[196:197], v[208:209]
	v_cndmask_b32_e64 v207, v218, 0, s[0:1]
	v_cndmask_b32_e64 v206, v216, 0, s[0:1]
	v_pk_mul_f32 v[158:159], v[158:159], v[220:221] op_sel_hi:[1,0]
	v_mov_b32_e32 v212, 0
	v_mov_b32_e32 v214, 0
	ds_bpermute_b32 v197, v187, v195
	ds_bpermute_b32 v196, v187, v194
	v_mov_b32_e32 v215, 0
	v_mov_b32_e32 v217, 0
	v_pk_mul_f32 v[206:207], v[92:93], v[206:207]
	v_mov_b32_dpp v212, v158 row_ror:1 row_mask:0xf bank_mask:0xf
	v_mov_b32_dpp v214, v159 row_ror:1 row_mask:0xf bank_mask:0xf
	v_mov_b32_dpp v215, v156 row_ror:2 row_mask:0xf bank_mask:0xf
	v_mov_b32_dpp v217, v157 row_ror:2 row_mask:0xf bank_mask:0xf
	v_pk_fma_f32 v[156:157], v[96:97], v[156:157], v[206:207]
	v_mov_b32_e32 v213, 0
	v_cndmask_b32_e64 v207, v214, 0, s[0:1]
	v_cndmask_b32_e64 v206, v212, 0, s[0:1]
	v_cndmask_b32_e64 v209, v217, 0, s[4:5]
	v_cndmask_b32_e64 v208, v215, 0, s[4:5]
	v_mov_b32_dpp v211, v158 row_ror:2 row_mask:0xf bank_mask:0xf
	v_mov_b32_dpp v213, v159 row_ror:2 row_mask:0xf bank_mask:0xf
	v_pk_mul_f32 v[206:207], v[94:95], v[206:207]
	v_pk_fma_f32 v[156:157], v[80:81], v[208:209], v[156:157]
	v_cndmask_b32_e64 v209, v213, 0, s[4:5]
	v_cndmask_b32_e64 v208, v211, 0, s[4:5]
	v_pk_fma_f32 v[158:159], v[98:99], v[158:159], v[206:207]
	v_pk_mul_f32 v[144:145], v[144:145], v[220:221] op_sel_hi:[1,0]
	v_pk_fma_f32 v[158:159], v[82:83], v[208:209], v[158:159]
	v_mov_b32_e32 v207, 0
	v_mov_b32_e32 v209, 0
	v_pk_mul_f32 v[146:147], v[146:147], v[220:221] op_sel_hi:[1,0]
	v_mov_b32_e32 v191, 0
	s_waitcnt lgkmcnt(0)
	v_pk_add_f32 v[194:195], v[194:195], v[196:197]
	v_mov_b32_dpp v207, v144 row_ror:1 row_mask:0xf bank_mask:0xf
	v_mov_b32_dpp v209, v145 row_ror:1 row_mask:0xf bank_mask:0xf
	v_mov_b32_dpp v191, v146 row_ror:1 row_mask:0xf bank_mask:0xf
	v_mov_b32_dpp v205, v147 row_ror:1 row_mask:0xf bank_mask:0xf
	ds_bpermute_b32 v197, v185, v195
	ds_bpermute_b32 v196, v185, v194
	v_pk_mul_f32 v[152:153], v[152:153], v[220:221] op_sel_hi:[1,0]
	v_pk_mul_f32 v[148:149], v[148:149], v[220:221] op_sel_hi:[1,0]
	v_pk_mul_f32 v[154:155], v[154:155], v[220:221] op_sel_hi:[1,0]
	v_pk_mul_f32 v[150:151], v[150:151], v[220:221] op_sel_hi:[1,0]
	v_mov_b32_e32 v206, 0
	v_mov_b32_e32 v208, 0
	v_cndmask_b32_e64 v223, v209, 0, s[0:1]
	v_cndmask_b32_e64 v222, v207, 0, s[0:1]
	v_mov_b32_e32 v189, 0
	v_mov_b32_e32 v193, 0
	v_cndmask_b32_e64 v221, v205, 0, s[0:1]
	v_cndmask_b32_e64 v220, v191, 0, s[0:1]
	v_mov_b32_dpp v206, v144 row_ror:2 row_mask:0xf bank_mask:0xf
	v_mov_b32_dpp v208, v145 row_ror:2 row_mask:0xf bank_mask:0xf
	v_pk_mul_f32 v[222:223], v[72:73], v[222:223]
	v_mov_b32_dpp v189, v146 row_ror:2 row_mask:0xf bank_mask:0xf
	v_mov_b32_dpp v193, v147 row_ror:2 row_mask:0xf bank_mask:0xf
	v_pk_mul_f32 v[220:221], v[74:75], v[220:221]
	v_cndmask_b32_e64 v225, v208, 0, s[4:5]
	v_cndmask_b32_e64 v224, v206, 0, s[4:5]
	v_pk_fma_f32 v[144:145], v[76:77], v[144:145], v[222:223]
	v_cndmask_b32_e64 v223, v193, 0, s[4:5]
	v_cndmask_b32_e64 v222, v189, 0, s[4:5]
	v_pk_fma_f32 v[146:147], v[78:79], v[146:147], v[220:221]
	v_pk_fma_f32 v[144:145], v[64:65], v[224:225], v[144:145]
	v_pk_fma_f32 v[146:147], v[66:67], v[222:223], v[146:147]
	v_cmp_gt_f32_e32 vcc, s74, v192
	v_pk_add_f32 v[156:157], v[84:85], v[156:157]
	v_pk_add_f32 v[158:159], v[86:87], v[158:159]
	v_pk_add_f32 v[144:145], v[68:69], v[144:145]
	v_pk_add_f32 v[146:147], v[70:71], v[146:147]
	s_and_saveexec_b64 s[12:13], s[10:11]
	s_xor_b64 s[12:13], exec, s[12:13]
	s_cbranch_execz .LBB0_814
; DI unsigned pack2(float lo, float hi) { f32x2 v = {lo, hi}; bf16v2 r = __builtin_convertvector(v, bf16v2); return __builtin_bit_cast(unsigned, r); }
; DI float silu_f(float x) { return x * sigmoid_f(x); }
;   DI void operator()(const f32x4 (&acc)[2][2][4][2], const Unit& u, int wr, int wc, int fr, int fq) const {
;     ...
;         } else {
;           u32x4 w;
;           w.x = pack2(silu_f(a[0]) * uu[0], silu_f(a[1]) * uu[1]);
;           w.y = pack2(silu_f(a[2]) * uu[2], silu_f(a[3]) * uu[3]);
;           w.z = pack2(silu_f(a[4]) * uu[4], silu_f(a[5]) * uu[5]);
;           w.w = pack2(silu_f(a[6]) * uu[6], silu_f(a[7]) * uu[7]);
;           *(u32x4*)(H + (size_t)(row0 + 16 * m + fr) * 5632 + col) = w;
;         }
	v_mul_f32_e32 v219, 0xbfb8aa3b, v156
	v_exp_f32_e32 v219, v219
	v_mul_f32_e32 v220, 0xbfb8aa3b, v157
	v_exp_f32_e32 v220, v220
	v_mul_f32_e32 v222, 0xbfb8aa3b, v159
	v_add_f32_e32 v219, 1.0, v219
	v_exp_f32_e32 v223, v222
	v_add_f32_e32 v221, 1.0, v220
	v_rcp_f32_e32 v220, v219
	v_mul_f32_e32 v219, 0xbfb8aa3b, v158
	v_exp_f32_e32 v219, v219
	v_rcp_f32_e32 v221, v221
	v_add_f32_e32 v219, 1.0, v219
	v_rcp_f32_e32 v222, v219
	v_add_f32_e32 v219, 1.0, v223
	v_rcp_f32_e32 v223, v219
	v_pk_mul_f32 v[156:157], v[156:157], v[220:221]
	s_nop 0
	v_pk_mul_f32 v[152:153], v[152:153], v[156:157]
	v_pk_mul_f32 v[156:157], v[158:159], v[222:223]
	v_cvt_pk_bf16_f32 v152, v152, v153
	v_mul_f32_e32 v153, 0xbfb8aa3b, v144
	v_pk_mul_f32 v[154:155], v[154:155], v[156:157]
	v_exp_f32_e32 v156, v153
	v_mul_f32_e32 v153, 0xbfb8aa3b, v145
	v_exp_f32_e32 v157, v153
	v_cvt_pk_bf16_f32 v153, v154, v155
	v_add_f32_e32 v154, 1.0, v156
	v_mul_f32_e32 v156, 0xbfb8aa3b, v146
	v_add_f32_e32 v155, 1.0, v157
	v_mul_f32_e32 v157, 0xbfb8aa3b, v147
	v_exp_f32_e32 v156, v156
	v_exp_f32_e32 v157, v157
	v_rcp_f32_e32 v154, v154
	v_rcp_f32_e32 v155, v155
	v_add_f32_e32 v156, 1.0, v156
	v_add_f32_e32 v157, 1.0, v157
	v_rcp_f32_e32 v156, v156
	v_rcp_f32_e32 v157, v157
	v_pk_mul_f32 v[144:145], v[144:145], v[154:155]
	s_nop 0
	v_pk_mul_f32 v[144:145], v[148:149], v[144:145]
	s_nop 0
	v_cvt_pk_bf16_f32 v154, v144, v145
	v_pk_mul_f32 v[144:145], v[146:147], v[156:157]
	s_nop 0
	v_pk_mul_f32 v[144:145], v[150:151], v[144:145]
	s_nop 0
	v_cvt_pk_bf16_f32 v155, v144, v145
	v_mov_b64_e32 v[144:145], s[16:17]
	v_mad_i64_i32 v[144:145], s[14:15], v190, s75, v[144:145]
	v_lshl_add_u64 v[144:145], v[180:181], 1, v[144:145]
	global_store_dwordx4 v[144:145], v[152:155], off

; #define PG8_STAGE(bufoff, gbase, voff) do { _Pragma("unroll") for (int _i = 0; _i < 2; ++_i) \
;     __builtin_amdgcn_global_load_lds((const unsigned*)((const char*)(gbase) + (voff)[_i]), (LAS unsigned*)(lds + (bufoff) + ldsw + _i * 8192), 16, 0, 0); } while (0)
; #define PG8_LDA(dst, b, h) do { _Pragma("unroll") for (int m = 0; m < 4; ++m) _Pragma("unroll") for (int k = 0; k < 2; ++k) dst[m][k] = *(const LAS bf16x8*)(lds + PG8_SA(b, h) + aoff + m * 2048 + k * 1024); } while (0)
; #define PG8_LDB(dst, b, h) do { _Pragma("unroll") for (int n = 0; n < 2; ++n) _Pragma("unroll") for (int k = 0; k < 2; ++k) dst[n][k] = *(const LAS bf16x8*)(lds + PG8_SB(b, h) + boff + n * 2048 + k * 1024); } while (0)
; #define PG8_MMA(ai, bj, At, Bt) do { __builtin_amdgcn_s_setprio(1); _Pragma("unroll") for (int m = 0; m < 4; ++m) _Pragma("unroll") for (int n = 0; n < 2; ++n) _Pragma("unroll") for (int k = 0; k < 2; ++k) \
;     acc[ai][bj][m][n] = __builtin_amdgcn_mfma_f32_16x16x32_bf16(Bt[n][k], At[m][k], acc[ai][bj][m][n], 0, 0, 0); __builtin_amdgcn_s_setprio(0); } while (0)
; #define PG8_WAIT_V(n) asm volatile("s_waitcnt vmcnt(" #n ")" ::: "memory")
; #define PG8_WAIT_L(n) asm volatile("s_waitcnt lgkmcnt(" #n ")" ::: "memory")
; #define PG8_BAR __builtin_amdgcn_s_barrier()
; #define PG8_SCHED __builtin_amdgcn_sched_barrier(0)
; template <class Epi, class Sched = StaticOrder>
; DI void gemm_phase(LAS unsigned char* lds, const Gemm g, const Sched& S, const Epi& E) {
;     ...
;     for (int t = 0; t < nt; t += 2) {
;       const bool last = (t == nt - 2);
;       const char* a1 = cA + (size_t)(t + 1) * kstep;
;       const char* a2 = last ? nA : cA + (size_t)(t + 2) * kstep; const char* b2 = last ? nB : cB + (size_t)(t + 2) * kstep;
;       const char* a3 = a2 + kstep; const char* b3 = b2 + kstep;
;       PG8_LDB(B0, 0, 0); PG8_SCHED; PG8_LDA(At, 0, 0); PG8_STAGE(PG8_SA(1, 1), a1 + hstep, voffA);
;       PG8_WAIT_L(8); PG8_BAR; PG8_WAIT_L(0); PG8_MMA(0, 0, At, B0); PG8_BAR; PG8_SCHED;
;       PG8_LDB(B1, 0, 1); PG8_STAGE(PG8_SB(0, 0), b2, voffB);
;       PG8_BAR; PG8_WAIT_L(0); PG8_MMA(0, 1, At, B1); PG8_BAR;
;       PG8_LDA(At, 0, 1); PG8_STAGE(PG8_SA(0, 0), a2, voffA);
;       PG8_BAR; PG8_WAIT_L(0); PG8_MMA(1, 0, At, B0); PG8_BAR; PG8_SCHED;
;       PG8_STAGE(PG8_SB(0, 1), b2 + hstep, voffB);
;       PG8_WAIT_V(6); PG8_BAR; PG8_MMA(1, 1, At, B1); PG8_BAR;
.LBB0_961:
	s_add_u32 s20, s18, 0xffea0080
	s_addc_u32 s21, s19, -1
	s_cmpk_eq_i32 s44, 0x54
	s_cselect_b32 s23, s5, s21
	s_cselect_b32 s22, s4, s20
	s_cselect_b32 s21, s7, s43
	s_cselect_b32 s20, s6, s42
	v_lshl_add_u64 v[192:193], s[18:19], 0, v[184:185]
	s_add_i32 m0, s31, 0xc000
	ds_read_b128 v[144:147], v215
	ds_read_b128 v[148:151], v215 offset:1024
	ds_read_b128 v[152:155], v215 offset:2048
	ds_read_b128 v[156:159], v215 offset:3072
	ds_read_b128 v[160:163], v215 offset:4096
	ds_read_b128 v[164:167], v215 offset:5120
	ds_read_b128 v[168:171], v215 offset:6144
	ds_read_b128 v[172:175], v215 offset:7168
	global_load_lds_dwordx4 v[192:193], off
	v_lshl_add_u64 v[192:193], s[18:19], 0, v[186:187]
	s_add_i32 m0, s31, 0xe000
	s_nop 0
	global_load_lds_dwordx4 v[192:193], off
	s_waitcnt lgkmcnt(0)
	s_setprio 1
	s_barrier
	v_mfma_f32_16x16x32_bf16 v[124:127], v[128:131], v[144:147], v[124:127]
	v_mfma_f32_16x16x32_bf16 v[120:123], v[136:139], v[144:147], v[120:123]
	v_mfma_f32_16x16x32_bf16 v[108:111], v[128:131], v[152:155], v[108:111]
	v_mfma_f32_16x16x32_bf16 v[104:107], v[136:139], v[152:155], v[104:107]
	v_mfma_f32_16x16x32_bf16 v[92:95], v[128:131], v[160:163], v[92:95]
	v_mfma_f32_16x16x32_bf16 v[88:91], v[136:139], v[160:163], v[88:91]
	v_mfma_f32_16x16x32_bf16 v[76:79], v[128:131], v[168:171], v[76:79]
	v_mfma_f32_16x16x32_bf16 v[72:75], v[136:139], v[168:171], v[72:75]
	v_mfma_f32_16x16x32_bf16 v[124:127], v[132:135], v[148:151], v[124:127]
	v_mfma_f32_16x16x32_bf16 v[120:123], v[140:143], v[148:151], v[120:123]
	v_mfma_f32_16x16x32_bf16 v[108:111], v[132:135], v[156:159], v[108:111]
	v_mfma_f32_16x16x32_bf16 v[104:107], v[140:143], v[156:159], v[104:107]
	v_mfma_f32_16x16x32_bf16 v[92:95], v[132:135], v[164:167], v[92:95]
	v_mfma_f32_16x16x32_bf16 v[88:91], v[140:143], v[164:167], v[88:91]
	v_mfma_f32_16x16x32_bf16 v[76:79], v[132:135], v[172:175], v[76:79]
	v_mfma_f32_16x16x32_bf16 v[72:75], v[140:143], v[172:175], v[72:75]
	s_barrier
	s_setprio 0
	s_add_i32 s45, s46, s30
	v_lshl_add_u64 v[208:209], s[20:21], 0, v[178:179]
	s_mov_b32 m0, s45
	ds_read_b128 v[192:195], v216
	ds_read_b128 v[196:199], v216 offset:1024
	ds_read_b128 v[200:203], v216 offset:2048
	ds_read_b128 v[204:207], v216 offset:3072
	global_load_lds_dwordx4 v[208:209], off
	v_lshl_add_u64 v[218:219], s[20:21], 0, v[182:183]
	s_add_i32 m0, s45, 0x2000
	s_nop 0
	global_load_lds_dwordx4 v[218:219], off
	s_waitcnt lgkmcnt(0)
	s_setprio 1
	s_barrier
	v_mfma_f32_16x16x32_bf16 v[116:119], v[192:195], v[144:147], v[116:119]
	v_mfma_f32_16x16x32_bf16 v[112:115], v[200:203], v[144:147], v[112:115]
	v_mfma_f32_16x16x32_bf16 v[100:103], v[192:195], v[152:155], v[100:103]
	v_mfma_f32_16x16x32_bf16 v[96:99], v[200:203], v[152:155], v[96:99]
	v_mfma_f32_16x16x32_bf16 v[84:87], v[192:195], v[160:163], v[84:87]
	v_mfma_f32_16x16x32_bf16 v[80:83], v[200:203], v[160:163], v[80:83]
	v_mfma_f32_16x16x32_bf16 v[68:71], v[192:195], v[168:171], v[68:71]
	v_mfma_f32_16x16x32_bf16 v[64:67], v[200:203], v[168:171], v[64:67]
	v_mfma_f32_16x16x32_bf16 v[116:119], v[196:199], v[148:151], v[116:119]
	v_mfma_f32_16x16x32_bf16 v[112:115], v[204:207], v[148:151], v[112:115]
	v_mfma_f32_16x16x32_bf16 v[100:103], v[196:199], v[156:159], v[100:103]
	v_mfma_f32_16x16x32_bf16 v[96:99], v[204:207], v[156:159], v[96:99]
	v_mfma_f32_16x16x32_bf16 v[84:87], v[196:199], v[164:167], v[84:87]
	v_mfma_f32_16x16x32_bf16 v[80:83], v[204:207], v[164:167], v[80:83]
	v_mfma_f32_16x16x32_bf16 v[68:71], v[196:199], v[172:175], v[68:71]
	v_mfma_f32_16x16x32_bf16 v[64:67], v[204:207], v[172:175], v[64:67]
	s_barrier
	s_setprio 0
	s_mov_b32 m0, s31
	v_lshl_add_u64 v[220:221], s[22:23], 0, v[176:177]
	ds_read_b128 v[144:147], v215 offset:16384
	ds_read_b128 v[148:151], v215 offset:17408
	ds_read_b128 v[152:155], v215 offset:18432
	ds_read_b128 v[156:159], v215 offset:19456
	ds_read_b128 v[160:163], v215 offset:20480
	ds_read_b128 v[164:167], v215 offset:21504
	ds_read_b128 v[168:171], v215 offset:22528
	ds_read_b128 v[172:175], v215 offset:23552
	global_load_lds_dwordx4 v[220:221], off
	v_lshl_add_u64 v[222:223], s[22:23], 0, v[180:181]
	s_mov_b32 m0, s33
	s_nop 0
	global_load_lds_dwordx4 v[222:223], off
	s_waitcnt vmcnt(10)
	s_waitcnt lgkmcnt(0)
	s_setprio 1
	s_barrier
	v_mfma_f32_16x16x32_bf16 v[60:63], v[128:131], v[144:147], v[60:63]
	v_mfma_f32_16x16x32_bf16 v[56:59], v[136:139], v[144:147], v[56:59]
	v_mfma_f32_16x16x32_bf16 v[44:47], v[128:131], v[152:155], v[44:47]
	v_mfma_f32_16x16x32_bf16 v[40:43], v[136:139], v[152:155], v[40:43]
	v_mfma_f32_16x16x32_bf16 v[28:31], v[128:131], v[160:163], v[28:31]
	v_mfma_f32_16x16x32_bf16 v[24:27], v[136:139], v[160:163], v[24:27]
	v_mfma_f32_16x16x32_bf16 v[12:15], v[128:131], v[168:171], v[12:15]
	v_mfma_f32_16x16x32_bf16 v[8:11], v[136:139], v[168:171], v[8:11]
	v_mfma_f32_16x16x32_bf16 v[60:63], v[132:135], v[148:151], v[60:63]
	v_mfma_f32_16x16x32_bf16 v[56:59], v[140:143], v[148:151], v[56:59]
	v_mfma_f32_16x16x32_bf16 v[44:47], v[132:135], v[156:159], v[44:47]
	v_mfma_f32_16x16x32_bf16 v[40:43], v[140:143], v[156:159], v[40:43]
	v_mfma_f32_16x16x32_bf16 v[28:31], v[132:135], v[164:167], v[28:31]
	v_mfma_f32_16x16x32_bf16 v[24:27], v[140:143], v[164:167], v[24:27]
	v_mfma_f32_16x16x32_bf16 v[12:15], v[132:135], v[172:175], v[12:15]
	v_mfma_f32_16x16x32_bf16 v[8:11], v[140:143], v[172:175], v[8:11]
	s_barrier
; #define PG8_STAGE(bufoff, gbase, voff) do { _Pragma("unroll") for (int _i = 0; _i < 2; ++_i) \
;     __builtin_amdgcn_global_load_lds((const unsigned*)((const char*)(gbase) + (voff)[_i]), (LAS unsigned*)(lds + (bufoff) + ldsw + _i * 8192), 16, 0, 0); } while (0)
; #define PG8_LDA(dst, b, h) do { _Pragma("unroll") for (int m = 0; m < 4; ++m) _Pragma("unroll") for (int k = 0; k < 2; ++k) dst[m][k] = *(const LAS bf16x8*)(lds + PG8_SA(b, h) + aoff + m * 2048 + k * 1024); } while (0)
; #define PG8_LDB(dst, b, h) do { _Pragma("unroll") for (int n = 0; n < 2; ++n) _Pragma("unroll") for (int k = 0; k < 2; ++k) dst[n][k] = *(const LAS bf16x8*)(lds + PG8_SB(b, h) + boff + n * 2048 + k * 1024); } while (0)
; #define PG8_MMA(ai, bj, At, Bt) do { __builtin_amdgcn_s_setprio(1); _Pragma("unroll") for (int m = 0; m < 4; ++m) _Pragma("unroll") for (int n = 0; n < 2; ++n) _Pragma("unroll") for (int k = 0; k < 2; ++k) \
;     acc[ai][bj][m][n] = __builtin_amdgcn_mfma_f32_16x16x32_bf16(Bt[n][k], At[m][k], acc[ai][bj][m][n], 0, 0, 0); __builtin_amdgcn_s_setprio(0); } while (0)
; #define PG8_WAIT_V(n) asm volatile("s_waitcnt vmcnt(" #n ")" ::: "memory")
; #define PG8_WAIT_L(n) asm volatile("s_waitcnt lgkmcnt(" #n ")" ::: "memory")
; #define PG8_BAR __builtin_amdgcn_s_barrier()
; #define PG8_SCHED __builtin_amdgcn_sched_barrier(0)
; template <class Epi, class Sched = StaticOrder>
; DI void gemm_phase(LAS unsigned char* lds, const Gemm g, const Sched& S, const Epi& E) {
;     ...
;       PG8_STAGE(PG8_SB(0, 1), b2 + hstep, voffB);
;       PG8_WAIT_V(6); PG8_BAR; PG8_MMA(1, 1, At, B1); PG8_BAR;
;       PG8_LDB(B0, 1, 0); PG8_SCHED; PG8_LDA(At, 1, 0); PG8_STAGE(PG8_SA(0, 1), a2 + hstep, voffA);
;       PG8_WAIT_L(8); PG8_BAR; PG8_WAIT_L(0); PG8_MMA(0, 0, At, B0); PG8_BAR; PG8_SCHED;
;       PG8_LDB(B1, 1, 1); PG8_STAGE(PG8_SB(1, 0), b3, voffB);
;       PG8_BAR; PG8_WAIT_L(0); PG8_MMA(0, 1, At, B1); PG8_BAR;
;       PG8_LDA(At, 1, 1); PG8_STAGE(PG8_SA(1, 0), a3, voffA);
;       PG8_BAR; PG8_WAIT_L(0); PG8_MMA(1, 0, At, B0); PG8_BAR; PG8_SCHED;
	s_setprio 0
	s_add_u32 s52, s20, 0x160000
	s_addc_u32 s53, s21, 0
	s_add_i32 s45, s47, s30
	v_lshl_add_u64 v[128:129], s[52:53], 0, v[178:179]
	s_mov_b32 m0, s45
	s_nop 0
	global_load_lds_dwordx4 v[128:129], off
	v_lshl_add_u64 v[128:129], s[52:53], 0, v[182:183]
	s_add_i32 m0, s45, 0x2000
	s_nop 0
	global_load_lds_dwordx4 v[128:129], off
	s_add_i32 s45, 0, 0x18000
	v_add_u32_e32 v140, s45, v212
	ds_read_b128 v[128:131], v140
	ds_read_b128 v[132:135], v140 offset:1024
	ds_read_b128 v[136:139], v140 offset:2048
	ds_read_b128 v[140:143], v140 offset:3072
	s_waitcnt vmcnt(6)
	s_setprio 1
	s_barrier
	v_mfma_f32_16x16x32_bf16 v[52:55], v[192:195], v[144:147], v[52:55]
	v_mfma_f32_16x16x32_bf16 v[48:51], v[200:203], v[144:147], v[48:51]
	v_mfma_f32_16x16x32_bf16 v[36:39], v[192:195], v[152:155], v[36:39]
	v_mfma_f32_16x16x32_bf16 v[32:35], v[200:203], v[152:155], v[32:35]
	v_mfma_f32_16x16x32_bf16 v[20:23], v[192:195], v[160:163], v[20:23]
	v_mfma_f32_16x16x32_bf16 v[16:19], v[200:203], v[160:163], v[16:19]
	v_mfma_f32_16x16x32_bf16 v[4:7], v[192:195], v[168:171], v[4:7]
	v_mfma_f32_16x16x32_bf16 v[0:3], v[200:203], v[168:171], v[0:3]
	v_mfma_f32_16x16x32_bf16 v[52:55], v[196:199], v[148:151], v[52:55]
	v_mfma_f32_16x16x32_bf16 v[48:51], v[204:207], v[148:151], v[48:51]
	v_mfma_f32_16x16x32_bf16 v[36:39], v[196:199], v[156:159], v[36:39]
	v_mfma_f32_16x16x32_bf16 v[32:35], v[204:207], v[156:159], v[32:35]
	v_mfma_f32_16x16x32_bf16 v[20:23], v[196:199], v[164:167], v[20:23]
	v_mfma_f32_16x16x32_bf16 v[16:19], v[204:207], v[164:167], v[16:19]
	v_mfma_f32_16x16x32_bf16 v[4:7], v[196:199], v[172:175], v[4:7]
	v_mfma_f32_16x16x32_bf16 v[0:3], v[204:207], v[172:175], v[0:3]
	s_barrier
	s_setprio 0
	s_add_u32 s22, s22, 0x160000
	s_addc_u32 s23, s23, 0
	s_mov_b32 m0, s34
	v_lshl_add_u64 v[192:193], s[22:23], 0, v[176:177]
	ds_read_b128 v[144:147], v215 offset:32768
	ds_read_b128 v[148:151], v215 offset:33792
	ds_read_b128 v[152:155], v215 offset:34816
	ds_read_b128 v[156:159], v215 offset:35840
	ds_read_b128 v[160:163], v215 offset:36864
	ds_read_b128 v[164:167], v215 offset:37888
	ds_read_b128 v[168:171], v215 offset:38912
	ds_read_b128 v[172:175], v215 offset:39936
	global_load_lds_dwordx4 v[192:193], off
	v_lshl_add_u64 v[192:193], s[22:23], 0, v[180:181]
	s_mov_b32 m0, s35
	s_nop 0
	global_load_lds_dwordx4 v[192:193], off
	s_waitcnt lgkmcnt(0)
	s_setprio 1
	s_barrier
	v_mfma_f32_16x16x32_bf16 v[124:127], v[128:131], v[144:147], v[124:127]
	v_mfma_f32_16x16x32_bf16 v[120:123], v[136:139], v[144:147], v[120:123]
	v_mfma_f32_16x16x32_bf16 v[108:111], v[128:131], v[152:155], v[108:111]
	v_mfma_f32_16x16x32_bf16 v[104:107], v[136:139], v[152:155], v[104:107]
	v_mfma_f32_16x16x32_bf16 v[92:95], v[128:131], v[160:163], v[92:95]
	v_mfma_f32_16x16x32_bf16 v[88:91], v[136:139], v[160:163], v[88:91]
	v_mfma_f32_16x16x32_bf16 v[76:79], v[128:131], v[168:171], v[76:79]
	v_mfma_f32_16x16x32_bf16 v[72:75], v[136:139], v[168:171], v[72:75]
	v_mfma_f32_16x16x32_bf16 v[124:127], v[132:135], v[148:151], v[124:127]
	v_mfma_f32_16x16x32_bf16 v[120:123], v[140:143], v[148:151], v[120:123]
	v_mfma_f32_16x16x32_bf16 v[108:111], v[132:135], v[156:159], v[108:111]
	v_mfma_f32_16x16x32_bf16 v[104:107], v[140:143], v[156:159], v[104:107]
	v_mfma_f32_16x16x32_bf16 v[92:95], v[132:135], v[164:167], v[92:95]
	v_mfma_f32_16x16x32_bf16 v[88:91], v[140:143], v[164:167], v[88:91]
	v_mfma_f32_16x16x32_bf16 v[76:79], v[132:135], v[172:175], v[76:79]
	v_mfma_f32_16x16x32_bf16 v[72:75], v[140:143], v[172:175], v[72:75]
	s_barrier
	s_setprio 0
	s_add_i32 s22, 0, 0x1c000
	s_add_i32 s23, s45, s30
	v_add_u32_e32 v204, s22, v212
	v_lshl_add_u64 v[208:209], v[208:209], 0, s[16:17]
	s_mov_b32 m0, s23
	ds_read_b128 v[192:195], v204
	ds_read_b128 v[196:199], v204 offset:1024
	ds_read_b128 v[200:203], v204 offset:2048
	ds_read_b128 v[204:207], v204 offset:3072
	global_load_lds_dwordx4 v[208:209], off
	v_lshl_add_u64 v[208:209], v[218:219], 0, s[16:17]
	s_add_i32 m0, s23, 0x2000
	s_nop 0
	global_load_lds_dwordx4 v[208:209], off
	s_waitcnt lgkmcnt(0)
	s_setprio 1
	s_barrier
	v_mfma_f32_16x16x32_bf16 v[116:119], v[192:195], v[144:147], v[116:119]
	v_mfma_f32_16x16x32_bf16 v[112:115], v[200:203], v[144:147], v[112:115]
	v_mfma_f32_16x16x32_bf16 v[100:103], v[192:195], v[152:155], v[100:103]
	v_mfma_f32_16x16x32_bf16 v[96:99], v[200:203], v[152:155], v[96:99]
	v_mfma_f32_16x16x32_bf16 v[84:87], v[192:195], v[160:163], v[84:87]
	v_mfma_f32_16x16x32_bf16 v[80:83], v[200:203], v[160:163], v[80:83]
	v_mfma_f32_16x16x32_bf16 v[68:71], v[192:195], v[168:171], v[68:71]
	v_mfma_f32_16x16x32_bf16 v[64:67], v[200:203], v[168:171], v[64:67]
	v_mfma_f32_16x16x32_bf16 v[116:119], v[196:199], v[148:151], v[116:119]
	v_mfma_f32_16x16x32_bf16 v[112:115], v[204:207], v[148:151], v[112:115]
	v_mfma_f32_16x16x32_bf16 v[100:103], v[196:199], v[156:159], v[100:103]
	v_mfma_f32_16x16x32_bf16 v[96:99], v[204:207], v[156:159], v[96:99]
	v_mfma_f32_16x16x32_bf16 v[84:87], v[196:199], v[164:167], v[84:87]
	v_mfma_f32_16x16x32_bf16 v[80:83], v[204:207], v[164:167], v[80:83]
	v_mfma_f32_16x16x32_bf16 v[68:71], v[196:199], v[172:175], v[68:71]
	v_mfma_f32_16x16x32_bf16 v[64:67], v[204:207], v[172:175], v[64:67]
	s_barrier
	s_setprio 0
	s_mov_b32 m0, s37
	v_lshl_add_u64 v[208:209], v[220:221], 0, s[16:17]
	ds_read_b128 v[144:147], v215 offset:49152
	ds_read_b128 v[148:151], v215 offset:50176
	ds_read_b128 v[152:155], v215 offset:51200
	ds_read_b128 v[156:159], v215 offset:52224
	ds_read_b128 v[160:163], v215 offset:53248
	ds_read_b128 v[164:167], v215 offset:54272
	ds_read_b128 v[168:171], v215 offset:55296
	ds_read_b128 v[172:175], v215 offset:56320
	global_load_lds_dwordx4 v[208:209], off
	v_lshl_add_u64 v[208:209], v[222:223], 0, s[16:17]
	s_mov_b32 m0, s38
	s_nop 0
	global_load_lds_dwordx4 v[208:209], off
	s_waitcnt vmcnt(10)
	s_waitcnt lgkmcnt(0)
	s_setprio 1
	s_barrier
; #define PG8_STAGE(bufoff, gbase, voff) do { _Pragma("unroll") for (int _i = 0; _i < 2; ++_i) \
;     __builtin_amdgcn_global_load_lds((const unsigned*)((const char*)(gbase) + (voff)[_i]), (LAS unsigned*)(lds + (bufoff) + ldsw + _i * 8192), 16, 0, 0); } while (0)
; #define PG8_MMA(ai, bj, At, Bt) do { __builtin_amdgcn_s_setprio(1); _Pragma("unroll") for (int m = 0; m < 4; ++m) _Pragma("unroll") for (int n = 0; n < 2; ++n) _Pragma("unroll") for (int k = 0; k < 2; ++k) \
;     acc[ai][bj][m][n] = __builtin_amdgcn_mfma_f32_16x16x32_bf16(Bt[n][k], At[m][k], acc[ai][bj][m][n], 0, 0, 0); __builtin_amdgcn_s_setprio(0); } while (0)
; #define PG8_WAIT_V(n) asm volatile("s_waitcnt vmcnt(" #n ")" ::: "memory")
; #define PG8_WAIT_L(n) asm volatile("s_waitcnt lgkmcnt(" #n ")" ::: "memory")
; #define PG8_BAR __builtin_amdgcn_s_barrier()
; #define PG8_SCHED __builtin_amdgcn_sched_barrier(0)
; template <class Epi, class Sched = StaticOrder>
; DI void gemm_phase(LAS unsigned char* lds, const Gemm g, const Sched& S, const Epi& E) {
;     ...
;       PG8_BAR; PG8_WAIT_L(0); PG8_MMA(1, 0, At, B0); PG8_BAR; PG8_SCHED;
;       PG8_STAGE(PG8_SB(1, 1), b3 + hstep, voffB);
;       PG8_WAIT_V(6); PG8_BAR; PG8_MMA(1, 1, At, B1); PG8_BAR;
;     }
	v_mfma_f32_16x16x32_bf16 v[60:63], v[128:131], v[144:147], v[60:63]
	v_mfma_f32_16x16x32_bf16 v[56:59], v[136:139], v[144:147], v[56:59]
	v_mfma_f32_16x16x32_bf16 v[44:47], v[128:131], v[152:155], v[44:47]
	v_mfma_f32_16x16x32_bf16 v[40:43], v[136:139], v[152:155], v[40:43]
	v_mfma_f32_16x16x32_bf16 v[28:31], v[128:131], v[160:163], v[28:31]
	v_mfma_f32_16x16x32_bf16 v[24:27], v[136:139], v[160:163], v[24:27]
	v_mfma_f32_16x16x32_bf16 v[12:15], v[128:131], v[168:171], v[12:15]
	v_mfma_f32_16x16x32_bf16 v[8:11], v[136:139], v[168:171], v[8:11]
	v_mfma_f32_16x16x32_bf16 v[60:63], v[132:135], v[148:151], v[60:63]
	v_mfma_f32_16x16x32_bf16 v[56:59], v[140:143], v[148:151], v[56:59]
	v_mfma_f32_16x16x32_bf16 v[44:47], v[132:135], v[156:159], v[44:47]
	v_mfma_f32_16x16x32_bf16 v[40:43], v[140:143], v[156:159], v[40:43]
	v_mfma_f32_16x16x32_bf16 v[28:31], v[132:135], v[164:167], v[28:31]
	v_mfma_f32_16x16x32_bf16 v[24:27], v[140:143], v[164:167], v[24:27]
	v_mfma_f32_16x16x32_bf16 v[12:15], v[132:135], v[172:175], v[12:15]
	v_mfma_f32_16x16x32_bf16 v[8:11], v[140:143], v[172:175], v[8:11]
	s_barrier
	s_setprio 0
	s_add_u32 s20, s20, 0x160080
	s_addc_u32 s21, s21, 0
	s_add_i32 s22, s22, s30
	v_lshl_add_u64 v[128:129], s[20:21], 0, v[178:179]
	s_mov_b32 m0, s22
	s_nop 0
	global_load_lds_dwordx4 v[128:129], off
	v_lshl_add_u64 v[128:129], s[20:21], 0, v[182:183]
	s_add_i32 m0, s22, 0x2000
	s_nop 0
	global_load_lds_dwordx4 v[128:129], off
	ds_read_b128 v[128:131], v214
	ds_read_b128 v[132:135], v214 offset:1024
	ds_read_b128 v[136:139], v214 offset:2048
	ds_read_b128 v[140:143], v214 offset:3072
	s_waitcnt vmcnt(6)
	s_setprio 1
	s_barrier
	v_mfma_f32_16x16x32_bf16 v[52:55], v[192:195], v[144:147], v[52:55]
	v_mfma_f32_16x16x32_bf16 v[48:51], v[200:203], v[144:147], v[48:51]
	v_mfma_f32_16x16x32_bf16 v[36:39], v[192:195], v[152:155], v[36:39]
	v_mfma_f32_16x16x32_bf16 v[32:35], v[200:203], v[152:155], v[32:35]
	v_mfma_f32_16x16x32_bf16 v[20:23], v[192:195], v[160:163], v[20:23]
	v_mfma_f32_16x16x32_bf16 v[16:19], v[200:203], v[160:163], v[16:19]
	v_mfma_f32_16x16x32_bf16 v[4:7], v[192:195], v[168:171], v[4:7]
	v_mfma_f32_16x16x32_bf16 v[0:3], v[200:203], v[168:171], v[0:3]
	v_mfma_f32_16x16x32_bf16 v[52:55], v[196:199], v[148:151], v[52:55]
	v_mfma_f32_16x16x32_bf16 v[48:51], v[204:207], v[148:151], v[48:51]
	v_mfma_f32_16x16x32_bf16 v[36:39], v[196:199], v[156:159], v[36:39]
	v_mfma_f32_16x16x32_bf16 v[32:35], v[204:207], v[156:159], v[32:35]
	v_mfma_f32_16x16x32_bf16 v[20:23], v[196:199], v[164:167], v[20:23]
	v_mfma_f32_16x16x32_bf16 v[16:19], v[204:207], v[164:167], v[16:19]
	v_mfma_f32_16x16x32_bf16 v[4:7], v[196:199], v[172:175], v[4:7]
	v_mfma_f32_16x16x32_bf16 v[0:3], v[204:207], v[172:175], v[0:3]
	s_add_i32 s44, s44, 2
	s_add_u32 s18, s18, 0x100
	s_addc_u32 s19, s19, 0
	s_add_u32 s42, s42, 0x100
	s_addc_u32 s43, s43, 0
	s_cmpk_gt_u32 s44, 0x55
	s_barrier
	s_setprio 0
	s_cbranch_scc0 .LBB0_961
; DI unsigned pack2(float lo, float hi) { f32x2 v = {lo, hi}; bf16v2 r = __builtin_convertvector(v, bf16v2); return __builtin_bit_cast(unsigned, r); }
;   DI void operator()(const f32x4 (&acc)[2][2][4][2], const Unit& u, int wr, int wc, int fr, int fq) const {
;     const int row0 = u.pm * BM + wr * 64 + fr, col0 = u.pn * BM + wc * 32 + 8 * fq;
; #pragma unroll
;     for (int ai = 0; ai < 2; ++ai) {
;       f32x4 bv[4][2][2];
; #pragma unroll
;       for (int m = 0; m < 4; ++m)
; #pragma unroll
;         for (int bj = 0; bj < 2; ++bj) {
;           const float* bp = base + (size_t)(row0 + ai * HALF + m * 16) * 2048 + col0 + bj * HALF;
;           bv[m][bj][0] = *(const f32x4*)bp; bv[m][bj][1] = *(const f32x4*)(bp + 4);
;         }
; #pragma unroll
;       for (int m = 0; m < 4; ++m) {
;         const int row = row0 + ai * HALF + m * 16;
;         const size_t off = (size_t)row * 2048 + col0;
;         float ss = 0.f;
; #pragma unroll
;         for (int bj = 0; bj < 2; ++bj) {
;           const f32x4 v0 = acc[ai][bj][m][0] + bv[m][bj][0], v1 = acc[ai][bj][m][1] + bv[m][bj][1];
;           *(f32x4*)(C + off + bj * HALF) = v0; *(f32x4*)(C + off + bj * HALF + 4) = v1;
;           if (xb) {
;             u32x4 w; w.x = pack2(v0[0], v0[1]); w.y = pack2(v0[2], v0[3]); w.z = pack2(v1[0], v1[1]); w.w = pack2(v1[2], v1[3]);
;             *(u32x4*)(xb + off + bj * HALF) = w;
;             ss += v0[0] * v0[0] + v0[1] * v0[1] + v0[2] * v0[2] + v0[3] * v0[3] + v1[0] * v1[0] + v1[1] * v1[1] + v1[2] * v1[2] + v1[3] * v1[3];
;           }
;         }
;         if (xb) {
;           ss += __shfl_xor(ss, 16); ss += __shfl_xor(ss, 32);
;           if (fq == 0) ssq[(size_t)row * 32 + u.pn * 4 + wc] = ss;
;         }
	s_waitcnt lgkmcnt(0)
	v_lshl_add_u32 v194, s51, 8, v211
	v_lshl_or_b32 v192, s2, 8, v213
	v_readlane_b32 s52, v243, 3
	v_ashrrev_i32_e32 v193, 31, v192
	v_readlane_b32 s66, v243, 17
	v_readlane_b32 s67, v243, 18
	v_ashrrev_i32_e32 v195, 31, v194
	v_lshlrev_b64 v[128:129], 13, v[194:195]
	v_lshl_add_u64 v[196:197], v[192:193], 2, s[66:67]
	v_lshl_add_u64 v[236:237], v[196:197], 0, v[128:129]
	global_load_dwordx4 v[220:223], v[236:237], off
	global_load_dwordx4 v[224:227], v[236:237], off offset:16
	global_load_dwordx4 v[228:231], v[236:237], off offset:512
	global_load_dwordx4 v[232:235], v[236:237], off offset:528
	v_or_b32_e32 v206, 16, v194
	v_or_b32_e32 v202, 32, v194
	v_or_b32_e32 v198, 48, v194
	v_ashrrev_i32_e32 v207, 31, v206
	v_ashrrev_i32_e32 v203, 31, v202
	v_ashrrev_i32_e32 v199, 31, v198
	v_lshlrev_b64 v[128:129], 13, v[206:207]
	v_lshlrev_b64 v[130:131], 13, v[202:203]
	v_lshlrev_b64 v[132:133], 13, v[198:199]
	v_lshl_add_u64 v[208:209], v[196:197], 0, v[128:129]
	v_lshl_add_u64 v[204:205], v[196:197], 0, v[130:131]
	v_lshl_add_u64 v[200:201], v[196:197], 0, v[132:133]
	global_load_dwordx4 v[168:171], v[208:209], off offset:16
	global_load_dwordx4 v[172:175], v[208:209], off
	global_load_dwordx4 v[160:163], v[208:209], off offset:528
	global_load_dwordx4 v[164:167], v[208:209], off offset:512
	global_load_dwordx4 v[152:155], v[204:205], off offset:16
	global_load_dwordx4 v[156:159], v[204:205], off
	global_load_dwordx4 v[144:147], v[204:205], off offset:528
	global_load_dwordx4 v[148:151], v[204:205], off offset:512
	global_load_dwordx4 v[136:139], v[200:201], off offset:16
	global_load_dwordx4 v[140:143], v[200:201], off
	global_load_dwordx4 v[128:131], v[200:201], off offset:528
	global_load_dwordx4 v[132:135], v[200:201], off offset:512
	v_and_b32_e32 v218, 64, v217
	v_xor_b32_e32 v238, 16, v217
	v_add_u32_e32 v240, 64, v218
	v_xor_b32_e32 v239, 32, v217
	v_cmp_lt_i32_e32 vcc, v238, v240
	v_lshlrev_b64 v[218:219], 11, v[194:195]
	s_lshl_b32 s18, s2, 2
	v_cndmask_b32_e32 v241, v217, v238, vcc
	v_cmp_lt_i32_e32 vcc, v239, v240
	s_ashr_i32 s19, s18, 31
	v_readlane_b32 s53, v243, 4
	v_cndmask_b32_e32 v240, v217, v239, vcc
	v_lshl_add_u64 v[238:239], v[218:219], 0, v[192:193]
	v_lshlrev_b32_e32 v218, 2, v241
	v_lshl_add_u64 v[238:239], v[238:239], 1, s[12:13]
	v_readlane_b32 s54, v243, 5
	v_readlane_b32 s55, v243, 6
	v_readlane_b32 s56, v243, 7
	v_readlane_b32 s57, v243, 8
	v_readlane_b32 s58, v243, 9
	v_readlane_b32 s59, v243, 10
	v_readlane_b32 s60, v243, 11
	v_readlane_b32 s61, v243, 12
	v_readlane_b32 s62, v243, 13
	v_readlane_b32 s63, v243, 14
	v_readlane_b32 s64, v243, 15
	v_readlane_b32 s65, v243, 16
	s_waitcnt vmcnt(0)
	v_pk_add_f32 v[126:127], v[126:127], v[222:223]
	v_pk_add_f32 v[124:125], v[124:125], v[220:221]
	v_pk_add_f32 v[116:117], v[116:117], v[228:229]
	v_pk_add_f32 v[122:123], v[122:123], v[226:227]
	v_pk_add_f32 v[120:121], v[120:121], v[224:225]
	v_pk_add_f32 v[220:221], v[112:113], v[232:233]
	global_store_dwordx4 v[236:237], v[124:127], off
	global_store_dwordx4 v[236:237], v[120:123], off offset:16
	v_cvt_pk_bf16_f32 v112, v124, v125
	v_mul_f32_e32 v125, v125, v125
	v_mul_f32_e32 v219, v117, v117
	v_pk_add_f32 v[118:119], v[118:119], v[230:231]
	v_fmac_f32_e32 v125, v124, v124
	v_fmac_f32_e32 v219, v116, v116
	v_fmac_f32_e32 v125, v126, v126
	v_fmac_f32_e32 v219, v118, v118
	v_fmac_f32_e32 v125, v127, v127
	v_fmac_f32_e32 v219, v119, v119
	v_fmac_f32_e32 v125, v120, v120
	v_fmac_f32_e32 v219, v220, v220
	v_pk_add_f32 v[222:223], v[114:115], v[234:235]
	v_fmac_f32_e32 v125, v121, v121
	v_fmac_f32_e32 v219, v221, v221
	v_fmac_f32_e32 v125, v122, v122
	v_fmac_f32_e32 v219, v222, v222
	v_fmac_f32_e32 v125, v123, v123
	v_fmac_f32_e32 v219, v223, v223
	v_cvt_pk_bf16_f32 v114, v120, v121
	v_add_f32_e32 v121, v125, v219
	v_cvt_pk_bf16_f32 v115, v122, v123
	ds_bpermute_b32 v122, v218, v121
	v_cvt_pk_bf16_f32 v113, v126, v127
	global_store_dwordx4 v[238:239], v[112:115], off
	global_store_dwordx4 v[236:237], v[116:119], off offset:512
	global_store_dwordx4 v[236:237], v[220:223], off offset:528
	v_lshlrev_b32_e32 v126, 2, v240
	v_cvt_pk_bf16_f32 v120, v116, v117
	s_waitcnt lgkmcnt(0)
	v_add_f32_e32 v112, v121, v122
	ds_bpermute_b32 v113, v126, v112
	v_cvt_pk_bf16_f32 v121, v118, v119
	v_cvt_pk_bf16_f32 v122, v220, v221
	v_cvt_pk_bf16_f32 v123, v222, v223
	global_store_dwordx4 v[238:239], v[120:123], off offset:256
	s_and_saveexec_b64 s[20:21], s[0:1]
	s_cbranch_execz .LBB0_964
	s_waitcnt lgkmcnt(0)
	v_add_f32_e32 v114, v112, v113
	v_lshlrev_b64 v[112:113], 7, v[194:195]
	v_lshl_add_u64 v[112:113], s[14:15], 0, v[112:113]
	v_lshl_add_u64 v[112:113], s[18:19], 2, v[112:113]
	s_lshl_b32 s2, s36, 2
	v_lshl_add_u64 v[112:113], v[112:113], 0, s[2:3]
	global_store_dword v[112:113], v114, off

; #define PG8_STAGE(bufoff, gbase, voff) do { _Pragma("unroll") for (int _i = 0; _i < 2; ++_i) \
;     __builtin_amdgcn_global_load_lds((const unsigned*)((const char*)(gbase) + (voff)[_i]), (LAS unsigned*)(lds + (bufoff) + ldsw + _i * 8192), 16, 0, 0); } while (0)
; #define PG8_LDA(dst, b, h) do { _Pragma("unroll") for (int m = 0; m < 4; ++m) _Pragma("unroll") for (int k = 0; k < 2; ++k) dst[m][k] = *(const LAS bf16x8*)(lds + PG8_SA(b, h) + aoff + m * 2048 + k * 1024); } while (0)
; #define PG8_LDB(dst, b, h) do { _Pragma("unroll") for (int n = 0; n < 2; ++n) _Pragma("unroll") for (int k = 0; k < 2; ++k) dst[n][k] = *(const LAS bf16x8*)(lds + PG8_SB(b, h) + boff + n * 2048 + k * 1024); } while (0)
; #define PG8_MMA(ai, bj, At, Bt) do { __builtin_amdgcn_s_setprio(1); _Pragma("unroll") for (int m = 0; m < 4; ++m) _Pragma("unroll") for (int n = 0; n < 2; ++n) _Pragma("unroll") for (int k = 0; k < 2; ++k) \
;     acc[ai][bj][m][n] = __builtin_amdgcn_mfma_f32_16x16x32_bf16(Bt[n][k], At[m][k], acc[ai][bj][m][n], 0, 0, 0); __builtin_amdgcn_s_setprio(0); } while (0)
; #define PG8_WAIT_V(n) asm volatile("s_waitcnt vmcnt(" #n ")" ::: "memory")
; #define PG8_WAIT_L(n) asm volatile("s_waitcnt lgkmcnt(" #n ")" ::: "memory")
; #define PG8_BAR __builtin_amdgcn_s_barrier()
; #define PG8_SCHED __builtin_amdgcn_sched_barrier(0)
; template <class Epi, class Sched = StaticOrder>
; DI void gemm_phase(LAS unsigned char* lds, const Gemm g, const Sched& S, const Epi& E) {
;     ...
;     for (int t = 0; t < nt; t += 2) {
;       const bool last = (t == nt - 2);
;       const char* a1 = cA + (size_t)(t + 1) * kstep;
;       const char* a2 = last ? nA : cA + (size_t)(t + 2) * kstep; const char* b2 = last ? nB : cB + (size_t)(t + 2) * kstep;
;       const char* a3 = a2 + kstep; const char* b3 = b2 + kstep;
;       PG8_LDB(B0, 0, 0); PG8_SCHED; PG8_LDA(At, 0, 0); PG8_STAGE(PG8_SA(1, 1), a1 + hstep, voffA);
;       PG8_WAIT_L(8); PG8_BAR; PG8_WAIT_L(0); PG8_MMA(0, 0, At, B0); PG8_BAR; PG8_SCHED;
;       PG8_LDB(B1, 0, 1); PG8_STAGE(PG8_SB(0, 0), b2, voffB);
;       PG8_BAR; PG8_WAIT_L(0); PG8_MMA(0, 1, At, B1); PG8_BAR;
;       PG8_LDA(At, 0, 1); PG8_STAGE(PG8_SA(0, 0), a2, voffA);
;       PG8_BAR; PG8_WAIT_L(0); PG8_MMA(1, 0, At, B0); PG8_BAR; PG8_SCHED;
;       PG8_STAGE(PG8_SB(0, 1), b2 + hstep, voffB);
;       PG8_WAIT_V(6); PG8_BAR; PG8_MMA(1, 1, At, B1); PG8_BAR;
.LBB0_1052:
	s_add_u32 s12, s10, 0xfff80080
	s_addc_u32 s13, s11, -1
	s_cmp_eq_u32 s52, 28
	s_cselect_b32 s65, s41, s13
	s_cselect_b32 s64, s42, s12
	s_cselect_b32 s13, s43, s49
	s_cselect_b32 s12, s44, s45
	v_lshl_add_u64 v[194:195], s[10:11], 0, v[172:173]
	s_add_i32 m0, s61, 0xc000
	ds_read_b128 v[144:147], v204
	ds_read_b128 v[148:151], v204 offset:1024
	ds_read_b128 v[152:155], v204 offset:2048
	ds_read_b128 v[156:159], v204 offset:3072
	ds_read_b128 v[178:181], v204 offset:4096
	ds_read_b128 v[182:185], v204 offset:5120
	ds_read_b128 v[186:189], v204 offset:6144
	ds_read_b128 v[190:193], v204 offset:7168
	global_load_lds_dwordx4 v[194:195], off
	v_lshl_add_u64 v[194:195], s[10:11], 0, v[174:175]
	s_add_i32 m0, s61, 0xe000
	s_nop 0
	global_load_lds_dwordx4 v[194:195], off
	s_waitcnt lgkmcnt(0)
	s_setprio 1
	s_barrier
	v_mfma_f32_16x16x32_bf16 v[124:127], v[128:131], v[144:147], v[124:127]
	v_mfma_f32_16x16x32_bf16 v[120:123], v[136:139], v[144:147], v[120:123]
	v_mfma_f32_16x16x32_bf16 v[116:119], v[128:131], v[152:155], v[116:119]
	v_mfma_f32_16x16x32_bf16 v[104:107], v[136:139], v[152:155], v[104:107]
	v_mfma_f32_16x16x32_bf16 v[92:95], v[128:131], v[178:181], v[92:95]
	v_mfma_f32_16x16x32_bf16 v[88:91], v[136:139], v[178:181], v[88:91]
	v_mfma_f32_16x16x32_bf16 v[84:87], v[128:131], v[186:189], v[84:87]
	v_mfma_f32_16x16x32_bf16 v[72:75], v[136:139], v[186:189], v[72:75]
	v_mfma_f32_16x16x32_bf16 v[124:127], v[132:135], v[148:151], v[124:127]
	v_mfma_f32_16x16x32_bf16 v[120:123], v[140:143], v[148:151], v[120:123]
	v_mfma_f32_16x16x32_bf16 v[116:119], v[132:135], v[156:159], v[116:119]
	v_mfma_f32_16x16x32_bf16 v[104:107], v[140:143], v[156:159], v[104:107]
	v_mfma_f32_16x16x32_bf16 v[92:95], v[132:135], v[182:185], v[92:95]
	v_mfma_f32_16x16x32_bf16 v[88:91], v[140:143], v[182:185], v[88:91]
	v_mfma_f32_16x16x32_bf16 v[84:87], v[132:135], v[190:193], v[84:87]
	v_mfma_f32_16x16x32_bf16 v[72:75], v[140:143], v[190:193], v[72:75]
	s_barrier
	s_setprio 0
	s_add_i32 s53, s80, s70
	v_lshl_add_u64 v[208:209], s[12:13], 0, v[162:163]
	s_mov_b32 m0, s53
	ds_read_b128 v[194:197], v205
	ds_read_b128 v[212:215], v205 offset:1024
	ds_read_b128 v[216:219], v205 offset:2048
	ds_read_b128 v[220:223], v205 offset:3072
	global_load_lds_dwordx4 v[208:209], off
	v_lshl_add_u64 v[224:225], s[12:13], 0, v[166:167]
	s_add_i32 m0, s53, 0x2000
	s_nop 0
	global_load_lds_dwordx4 v[224:225], off
	s_waitcnt lgkmcnt(0)
	s_setprio 1
	s_barrier
	v_mfma_f32_16x16x32_bf16 v[112:115], v[194:197], v[144:147], v[112:115]
	v_mfma_f32_16x16x32_bf16 v[108:111], v[216:219], v[144:147], v[108:111]
	v_mfma_f32_16x16x32_bf16 v[100:103], v[194:197], v[152:155], v[100:103]
	v_mfma_f32_16x16x32_bf16 v[96:99], v[216:219], v[152:155], v[96:99]
	v_mfma_f32_16x16x32_bf16 v[80:83], v[194:197], v[178:181], v[80:83]
	v_mfma_f32_16x16x32_bf16 v[76:79], v[216:219], v[178:181], v[76:79]
	v_mfma_f32_16x16x32_bf16 v[68:71], v[194:197], v[186:189], v[68:71]
	v_mfma_f32_16x16x32_bf16 v[64:67], v[216:219], v[186:189], v[64:67]
	v_mfma_f32_16x16x32_bf16 v[112:115], v[212:215], v[148:151], v[112:115]
	v_mfma_f32_16x16x32_bf16 v[108:111], v[220:223], v[148:151], v[108:111]
	v_mfma_f32_16x16x32_bf16 v[100:103], v[212:215], v[156:159], v[100:103]
	v_mfma_f32_16x16x32_bf16 v[96:99], v[220:223], v[156:159], v[96:99]
	v_mfma_f32_16x16x32_bf16 v[80:83], v[212:215], v[182:185], v[80:83]
	v_mfma_f32_16x16x32_bf16 v[76:79], v[220:223], v[182:185], v[76:79]
	v_mfma_f32_16x16x32_bf16 v[68:71], v[212:215], v[190:193], v[68:71]
	v_mfma_f32_16x16x32_bf16 v[64:67], v[220:223], v[190:193], v[64:67]
	s_barrier
	s_setprio 0
	s_mov_b32 m0, s61
	v_lshl_add_u64 v[226:227], s[64:65], 0, v[160:161]
	ds_read_b128 v[144:147], v204 offset:16384
	ds_read_b128 v[148:151], v204 offset:17408
	ds_read_b128 v[152:155], v204 offset:18432
	ds_read_b128 v[156:159], v204 offset:19456
	ds_read_b128 v[178:181], v204 offset:20480
	ds_read_b128 v[182:185], v204 offset:21504
	ds_read_b128 v[186:189], v204 offset:22528
	ds_read_b128 v[190:193], v204 offset:23552
	global_load_lds_dwordx4 v[226:227], off
	v_lshl_add_u64 v[228:229], s[64:65], 0, v[164:165]
	s_mov_b32 m0, s63
	s_nop 0
	global_load_lds_dwordx4 v[228:229], off
	s_waitcnt vmcnt(10)
	s_waitcnt lgkmcnt(0)
	s_setprio 1
	s_barrier
	v_mfma_f32_16x16x32_bf16 v[60:63], v[128:131], v[144:147], v[60:63]
	v_mfma_f32_16x16x32_bf16 v[56:59], v[136:139], v[144:147], v[56:59]
	v_mfma_f32_16x16x32_bf16 v[48:51], v[128:131], v[152:155], v[48:51]
	v_mfma_f32_16x16x32_bf16 v[40:43], v[136:139], v[152:155], v[40:43]
	v_mfma_f32_16x16x32_bf16 v[28:31], v[128:131], v[178:181], v[28:31]
	v_mfma_f32_16x16x32_bf16 v[24:27], v[136:139], v[178:181], v[24:27]
	v_mfma_f32_16x16x32_bf16 v[12:15], v[128:131], v[186:189], v[12:15]
	v_mfma_f32_16x16x32_bf16 v[8:11], v[136:139], v[186:189], v[8:11]
	v_mfma_f32_16x16x32_bf16 v[60:63], v[132:135], v[148:151], v[60:63]
	v_mfma_f32_16x16x32_bf16 v[56:59], v[140:143], v[148:151], v[56:59]
	v_mfma_f32_16x16x32_bf16 v[48:51], v[132:135], v[156:159], v[48:51]
	v_mfma_f32_16x16x32_bf16 v[40:43], v[140:143], v[156:159], v[40:43]
	v_mfma_f32_16x16x32_bf16 v[28:31], v[132:135], v[182:185], v[28:31]
	v_mfma_f32_16x16x32_bf16 v[24:27], v[140:143], v[182:185], v[24:27]
	v_mfma_f32_16x16x32_bf16 v[12:15], v[132:135], v[190:193], v[12:15]
	v_mfma_f32_16x16x32_bf16 v[8:11], v[140:143], v[190:193], v[8:11]
	s_barrier
; #define PG8_STAGE(bufoff, gbase, voff) do { _Pragma("unroll") for (int _i = 0; _i < 2; ++_i) \
;     __builtin_amdgcn_global_load_lds((const unsigned*)((const char*)(gbase) + (voff)[_i]), (LAS unsigned*)(lds + (bufoff) + ldsw + _i * 8192), 16, 0, 0); } while (0)
; #define PG8_LDA(dst, b, h) do { _Pragma("unroll") for (int m = 0; m < 4; ++m) _Pragma("unroll") for (int k = 0; k < 2; ++k) dst[m][k] = *(const LAS bf16x8*)(lds + PG8_SA(b, h) + aoff + m * 2048 + k * 1024); } while (0)
; #define PG8_LDB(dst, b, h) do { _Pragma("unroll") for (int n = 0; n < 2; ++n) _Pragma("unroll") for (int k = 0; k < 2; ++k) dst[n][k] = *(const LAS bf16x8*)(lds + PG8_SB(b, h) + boff + n * 2048 + k * 1024); } while (0)
; #define PG8_MMA(ai, bj, At, Bt) do { __builtin_amdgcn_s_setprio(1); _Pragma("unroll") for (int m = 0; m < 4; ++m) _Pragma("unroll") for (int n = 0; n < 2; ++n) _Pragma("unroll") for (int k = 0; k < 2; ++k) \
;     acc[ai][bj][m][n] = __builtin_amdgcn_mfma_f32_16x16x32_bf16(Bt[n][k], At[m][k], acc[ai][bj][m][n], 0, 0, 0); __builtin_amdgcn_s_setprio(0); } while (0)
; #define PG8_WAIT_V(n) asm volatile("s_waitcnt vmcnt(" #n ")" ::: "memory")
; #define PG8_WAIT_L(n) asm volatile("s_waitcnt lgkmcnt(" #n ")" ::: "memory")
; #define PG8_BAR __builtin_amdgcn_s_barrier()
; #define PG8_SCHED __builtin_amdgcn_sched_barrier(0)
; template <class Epi, class Sched = StaticOrder>
; DI void gemm_phase(LAS unsigned char* lds, const Gemm g, const Sched& S, const Epi& E) {
;     ...
;       PG8_STAGE(PG8_SB(0, 1), b2 + hstep, voffB);
;       PG8_WAIT_V(6); PG8_BAR; PG8_MMA(1, 1, At, B1); PG8_BAR;
;       PG8_LDB(B0, 1, 0); PG8_SCHED; PG8_LDA(At, 1, 0); PG8_STAGE(PG8_SA(0, 1), a2 + hstep, voffA);
;       PG8_WAIT_L(8); PG8_BAR; PG8_WAIT_L(0); PG8_MMA(0, 0, At, B0); PG8_BAR; PG8_SCHED;
;       PG8_LDB(B1, 1, 1); PG8_STAGE(PG8_SB(1, 0), b3, voffB);
;       PG8_BAR; PG8_WAIT_L(0); PG8_MMA(0, 1, At, B1); PG8_BAR;
;       PG8_LDA(At, 1, 1); PG8_STAGE(PG8_SA(1, 0), a3, voffA);
;       PG8_BAR; PG8_WAIT_L(0); PG8_MMA(1, 0, At, B0); PG8_BAR; PG8_SCHED;
	s_setprio 0
	s_add_u32 s54, s12, 0x80000
	s_addc_u32 s55, s13, 0
	s_add_i32 s53, s81, s70
	v_lshl_add_u64 v[128:129], s[54:55], 0, v[162:163]
	s_mov_b32 m0, s53
	s_nop 0
	global_load_lds_dwordx4 v[128:129], off
	v_lshl_add_u64 v[128:129], s[54:55], 0, v[166:167]
	s_add_i32 m0, s53, 0x2000
	s_nop 0
	global_load_lds_dwordx4 v[128:129], off
	s_add_i32 s53, 0, 0x18000
	v_add_u32_e32 v140, s53, v199
	ds_read_b128 v[128:131], v140
	ds_read_b128 v[132:135], v140 offset:1024
	ds_read_b128 v[136:139], v140 offset:2048
	ds_read_b128 v[140:143], v140 offset:3072
	s_waitcnt vmcnt(6)
	s_setprio 1
	s_barrier
	v_mfma_f32_16x16x32_bf16 v[52:55], v[194:197], v[144:147], v[52:55]
	v_mfma_f32_16x16x32_bf16 v[44:47], v[216:219], v[144:147], v[44:47]
	v_mfma_f32_16x16x32_bf16 v[36:39], v[194:197], v[152:155], v[36:39]
	v_mfma_f32_16x16x32_bf16 v[32:35], v[216:219], v[152:155], v[32:35]
	v_mfma_f32_16x16x32_bf16 v[20:23], v[194:197], v[178:181], v[20:23]
	v_mfma_f32_16x16x32_bf16 v[16:19], v[216:219], v[178:181], v[16:19]
	v_mfma_f32_16x16x32_bf16 v[4:7], v[194:197], v[186:189], v[4:7]
	v_mfma_f32_16x16x32_bf16 v[0:3], v[216:219], v[186:189], v[0:3]
	v_mfma_f32_16x16x32_bf16 v[52:55], v[212:215], v[148:151], v[52:55]
	v_mfma_f32_16x16x32_bf16 v[44:47], v[220:223], v[148:151], v[44:47]
	v_mfma_f32_16x16x32_bf16 v[36:39], v[212:215], v[156:159], v[36:39]
	v_mfma_f32_16x16x32_bf16 v[32:35], v[220:223], v[156:159], v[32:35]
	v_mfma_f32_16x16x32_bf16 v[20:23], v[212:215], v[182:185], v[20:23]
	v_mfma_f32_16x16x32_bf16 v[16:19], v[220:223], v[182:185], v[16:19]
	v_mfma_f32_16x16x32_bf16 v[4:7], v[212:215], v[190:193], v[4:7]
	v_mfma_f32_16x16x32_bf16 v[0:3], v[220:223], v[190:193], v[0:3]
	s_barrier
	s_setprio 0
	s_add_u32 s54, s64, 0x80000
	s_addc_u32 s55, s65, 0
	s_mov_b32 m0, s71
	v_lshl_add_u64 v[194:195], s[54:55], 0, v[160:161]
	ds_read_b128 v[144:147], v204 offset:32768
	ds_read_b128 v[148:151], v204 offset:33792
	ds_read_b128 v[152:155], v204 offset:34816
	ds_read_b128 v[156:159], v204 offset:35840
	ds_read_b128 v[178:181], v204 offset:36864
	ds_read_b128 v[182:185], v204 offset:37888
	ds_read_b128 v[186:189], v204 offset:38912
	ds_read_b128 v[190:193], v204 offset:39936
	global_load_lds_dwordx4 v[194:195], off
	v_lshl_add_u64 v[194:195], s[54:55], 0, v[164:165]
	s_mov_b32 m0, s72
	s_nop 0
	global_load_lds_dwordx4 v[194:195], off
	s_waitcnt lgkmcnt(0)
	s_setprio 1
	s_barrier
	v_mfma_f32_16x16x32_bf16 v[124:127], v[128:131], v[144:147], v[124:127]
	v_mfma_f32_16x16x32_bf16 v[120:123], v[136:139], v[144:147], v[120:123]
	v_mfma_f32_16x16x32_bf16 v[116:119], v[128:131], v[152:155], v[116:119]
	v_mfma_f32_16x16x32_bf16 v[104:107], v[136:139], v[152:155], v[104:107]
	v_mfma_f32_16x16x32_bf16 v[92:95], v[128:131], v[178:181], v[92:95]
	v_mfma_f32_16x16x32_bf16 v[88:91], v[136:139], v[178:181], v[88:91]
	v_mfma_f32_16x16x32_bf16 v[84:87], v[128:131], v[186:189], v[84:87]
	v_mfma_f32_16x16x32_bf16 v[72:75], v[136:139], v[186:189], v[72:75]
	v_mfma_f32_16x16x32_bf16 v[124:127], v[132:135], v[148:151], v[124:127]
	v_mfma_f32_16x16x32_bf16 v[120:123], v[140:143], v[148:151], v[120:123]
	v_mfma_f32_16x16x32_bf16 v[116:119], v[132:135], v[156:159], v[116:119]
	v_mfma_f32_16x16x32_bf16 v[104:107], v[140:143], v[156:159], v[104:107]
	v_mfma_f32_16x16x32_bf16 v[92:95], v[132:135], v[182:185], v[92:95]
	v_mfma_f32_16x16x32_bf16 v[88:91], v[140:143], v[182:185], v[88:91]
	v_mfma_f32_16x16x32_bf16 v[84:87], v[132:135], v[190:193], v[84:87]
	v_mfma_f32_16x16x32_bf16 v[72:75], v[140:143], v[190:193], v[72:75]
	s_barrier
	s_setprio 0
	s_add_i32 s54, 0, 0x1c000
	s_add_i32 s53, s53, s70
	v_add_u32_e32 v168, s54, v199
	v_lshl_add_u64 v[208:209], v[208:209], 0, s[24:25]
	s_mov_b32 m0, s53
	ds_read_b128 v[194:197], v168
	ds_read_b128 v[212:215], v168 offset:1024
	ds_read_b128 v[216:219], v168 offset:2048
	ds_read_b128 v[220:223], v168 offset:3072
	global_load_lds_dwordx4 v[208:209], off
	v_lshl_add_u64 v[208:209], v[224:225], 0, s[24:25]
	s_add_i32 m0, s53, 0x2000
	s_nop 0
	global_load_lds_dwordx4 v[208:209], off
	s_waitcnt lgkmcnt(0)
	s_setprio 1
	s_barrier
	v_mfma_f32_16x16x32_bf16 v[112:115], v[194:197], v[144:147], v[112:115]
	v_mfma_f32_16x16x32_bf16 v[108:111], v[216:219], v[144:147], v[108:111]
	v_mfma_f32_16x16x32_bf16 v[100:103], v[194:197], v[152:155], v[100:103]
	v_mfma_f32_16x16x32_bf16 v[96:99], v[216:219], v[152:155], v[96:99]
	v_mfma_f32_16x16x32_bf16 v[80:83], v[194:197], v[178:181], v[80:83]
	v_mfma_f32_16x16x32_bf16 v[76:79], v[216:219], v[178:181], v[76:79]
	v_mfma_f32_16x16x32_bf16 v[68:71], v[194:197], v[186:189], v[68:71]
	v_mfma_f32_16x16x32_bf16 v[64:67], v[216:219], v[186:189], v[64:67]
	v_mfma_f32_16x16x32_bf16 v[112:115], v[212:215], v[148:151], v[112:115]
	v_mfma_f32_16x16x32_bf16 v[108:111], v[220:223], v[148:151], v[108:111]
	v_mfma_f32_16x16x32_bf16 v[100:103], v[212:215], v[156:159], v[100:103]
	v_mfma_f32_16x16x32_bf16 v[96:99], v[220:223], v[156:159], v[96:99]
	v_mfma_f32_16x16x32_bf16 v[80:83], v[212:215], v[182:185], v[80:83]
	v_mfma_f32_16x16x32_bf16 v[76:79], v[220:223], v[182:185], v[76:79]
	v_mfma_f32_16x16x32_bf16 v[68:71], v[212:215], v[190:193], v[68:71]
	v_mfma_f32_16x16x32_bf16 v[64:67], v[220:223], v[190:193], v[64:67]
	s_barrier
	s_setprio 0
	s_mov_b32 m0, s76
	v_lshl_add_u64 v[208:209], v[226:227], 0, s[24:25]
	ds_read_b128 v[144:147], v204 offset:49152
	ds_read_b128 v[148:151], v204 offset:50176
	ds_read_b128 v[152:155], v204 offset:51200
	ds_read_b128 v[156:159], v204 offset:52224
	ds_read_b128 v[178:181], v204 offset:53248
	ds_read_b128 v[182:185], v204 offset:54272
	ds_read_b128 v[186:189], v204 offset:55296
	ds_read_b128 v[190:193], v204 offset:56320
	global_load_lds_dwordx4 v[208:209], off
	v_lshl_add_u64 v[208:209], v[228:229], 0, s[24:25]
	s_mov_b32 m0, s77
	s_nop 0
	global_load_lds_dwordx4 v[208:209], off
	s_waitcnt vmcnt(10)
	s_waitcnt lgkmcnt(0)
	s_setprio 1
	s_barrier
; #define PG8_STAGE(bufoff, gbase, voff) do { _Pragma("unroll") for (int _i = 0; _i < 2; ++_i) \
;     __builtin_amdgcn_global_load_lds((const unsigned*)((const char*)(gbase) + (voff)[_i]), (LAS unsigned*)(lds + (bufoff) + ldsw + _i * 8192), 16, 0, 0); } while (0)
; #define PG8_MMA(ai, bj, At, Bt) do { __builtin_amdgcn_s_setprio(1); _Pragma("unroll") for (int m = 0; m < 4; ++m) _Pragma("unroll") for (int n = 0; n < 2; ++n) _Pragma("unroll") for (int k = 0; k < 2; ++k) \
;     acc[ai][bj][m][n] = __builtin_amdgcn_mfma_f32_16x16x32_bf16(Bt[n][k], At[m][k], acc[ai][bj][m][n], 0, 0, 0); __builtin_amdgcn_s_setprio(0); } while (0)
; #define PG8_WAIT_V(n) asm volatile("s_waitcnt vmcnt(" #n ")" ::: "memory")
; #define PG8_WAIT_L(n) asm volatile("s_waitcnt lgkmcnt(" #n ")" ::: "memory")
; #define PG8_BAR __builtin_amdgcn_s_barrier()
; #define PG8_SCHED __builtin_amdgcn_sched_barrier(0)
;   DI void operator()(const f32x4 (&acc)[2][2][4][2], const Unit& u, int wr, int wc, int fr, int fq) const {
;     ...
;     const int col = u.pn * 128 + wc * 32 + 8 * fq;
;     float w0[8], w1[8], w2[8];
; #pragma unroll
;     for (int e = 0; e < 8; ++e) { w0[e] = cw[col + e]; w1[e] = cw[2048 + col + e]; w2[e] = cw[4096 + col + e]; }
; #pragma unroll
;     for (int ai = 0; ai < 2; ++ai) {
;       const int row0 = u.pm * BM + ai * HALF + wr * 64, span = row0 >> 6;
;       float rsv[4];
; #pragma unroll
;       for (int m = 0; m < 4; ++m) rsv[m] = row_rstd(ssq, row0 + 16 * m + fr, fq);
; template <class Epi, class Sched = StaticOrder>
; DI void gemm_phase(LAS unsigned char* lds, const Gemm g, const Sched& S, const Epi& E) {
;     ...
;       PG8_BAR; PG8_WAIT_L(0); PG8_MMA(1, 0, At, B0); PG8_BAR; PG8_SCHED;
;       PG8_STAGE(PG8_SB(1, 1), b3 + hstep, voffB);
;       PG8_WAIT_V(6); PG8_BAR; PG8_MMA(1, 1, At, B1); PG8_BAR;
;     }
;     E(acc, cur, wr, wc, fr, fq);
	v_mfma_f32_16x16x32_bf16 v[60:63], v[128:131], v[144:147], v[60:63]
	v_mfma_f32_16x16x32_bf16 v[56:59], v[136:139], v[144:147], v[56:59]
	v_mfma_f32_16x16x32_bf16 v[48:51], v[128:131], v[152:155], v[48:51]
	v_mfma_f32_16x16x32_bf16 v[40:43], v[136:139], v[152:155], v[40:43]
	v_mfma_f32_16x16x32_bf16 v[28:31], v[128:131], v[178:181], v[28:31]
	v_mfma_f32_16x16x32_bf16 v[24:27], v[136:139], v[178:181], v[24:27]
	v_mfma_f32_16x16x32_bf16 v[12:15], v[128:131], v[186:189], v[12:15]
	v_mfma_f32_16x16x32_bf16 v[8:11], v[136:139], v[186:189], v[8:11]
	v_mfma_f32_16x16x32_bf16 v[60:63], v[132:135], v[148:151], v[60:63]
	v_mfma_f32_16x16x32_bf16 v[56:59], v[140:143], v[148:151], v[56:59]
	v_mfma_f32_16x16x32_bf16 v[48:51], v[132:135], v[156:159], v[48:51]
	v_mfma_f32_16x16x32_bf16 v[40:43], v[140:143], v[156:159], v[40:43]
	v_mfma_f32_16x16x32_bf16 v[28:31], v[132:135], v[182:185], v[28:31]
	v_mfma_f32_16x16x32_bf16 v[24:27], v[140:143], v[182:185], v[24:27]
	v_mfma_f32_16x16x32_bf16 v[12:15], v[132:135], v[190:193], v[12:15]
	v_mfma_f32_16x16x32_bf16 v[8:11], v[140:143], v[190:193], v[8:11]
	s_barrier
	s_setprio 0
	s_add_u32 s12, s12, 0x80080
	s_addc_u32 s13, s13, 0
	s_add_i32 s53, s54, s70
	v_lshl_add_u64 v[128:129], s[12:13], 0, v[162:163]
	s_mov_b32 m0, s53
	s_nop 0
	global_load_lds_dwordx4 v[128:129], off
	v_lshl_add_u64 v[128:129], s[12:13], 0, v[166:167]
	s_add_i32 m0, s53, 0x2000
	s_nop 0
	global_load_lds_dwordx4 v[128:129], off
	ds_read_b128 v[128:131], v203
	ds_read_b128 v[132:135], v203 offset:1024
	ds_read_b128 v[136:139], v203 offset:2048
	ds_read_b128 v[140:143], v203 offset:3072
	s_waitcnt vmcnt(6)
	s_setprio 1
	s_barrier
	v_mfma_f32_16x16x32_bf16 v[52:55], v[194:197], v[144:147], v[52:55]
	v_mfma_f32_16x16x32_bf16 v[44:47], v[216:219], v[144:147], v[44:47]
	v_mfma_f32_16x16x32_bf16 v[36:39], v[194:197], v[152:155], v[36:39]
	v_mfma_f32_16x16x32_bf16 v[32:35], v[216:219], v[152:155], v[32:35]
	v_mfma_f32_16x16x32_bf16 v[20:23], v[194:197], v[178:181], v[20:23]
	v_mfma_f32_16x16x32_bf16 v[16:19], v[216:219], v[178:181], v[16:19]
	v_mfma_f32_16x16x32_bf16 v[4:7], v[194:197], v[186:189], v[4:7]
	v_mfma_f32_16x16x32_bf16 v[0:3], v[216:219], v[186:189], v[0:3]
	v_mfma_f32_16x16x32_bf16 v[52:55], v[212:215], v[148:151], v[52:55]
	v_mfma_f32_16x16x32_bf16 v[44:47], v[220:223], v[148:151], v[44:47]
	v_mfma_f32_16x16x32_bf16 v[36:39], v[212:215], v[156:159], v[36:39]
	v_mfma_f32_16x16x32_bf16 v[32:35], v[220:223], v[156:159], v[32:35]
	v_mfma_f32_16x16x32_bf16 v[20:23], v[212:215], v[182:185], v[20:23]
	v_mfma_f32_16x16x32_bf16 v[16:19], v[220:223], v[182:185], v[16:19]
	v_mfma_f32_16x16x32_bf16 v[4:7], v[212:215], v[190:193], v[4:7]
	v_mfma_f32_16x16x32_bf16 v[0:3], v[220:223], v[190:193], v[0:3]
	s_add_i32 s52, s52, 2
	s_add_u32 s10, s10, 0x100
	s_addc_u32 s11, s11, 0
	s_add_u32 s45, s45, 0x100
	s_addc_u32 s49, s49, 0
	s_cmp_gt_u32 s52, 29
	s_barrier
	s_setprio 0
	s_cbranch_scc0 .LBB0_1052
	s_waitcnt lgkmcnt(0)
	s_cmp_lt_i32 s62, 16
	s_mov_b64 s[10:11], -1
	s_cbranch_scc0 .LBB0_1067
	s_lshl_b32 s41, s60, 8
	s_add_i32 s41, s41, s75
	v_or_b32_e32 v186, s41, v177
	v_ashrrev_i32_e32 v187, 31, v186
	v_lshlrev_b64 v[128:129], 7, v[186:187]
	v_or_b32_e32 v180, 16, v186
	v_lshl_add_u64 v[128:129], v[170:171], 0, v[128:129]
	v_ashrrev_i32_e32 v181, 31, v180
	global_load_dwordx4 v[152:155], v[128:129], off
	global_load_dwordx4 v[156:159], v[128:129], off offset:16
	v_lshlrev_b64 v[128:129], 7, v[180:181]
	v_lshl_add_u64 v[128:129], v[170:171], 0, v[128:129]
	global_load_dwordx4 v[188:191], v[128:129], off
	global_load_dwordx4 v[192:195], v[128:129], off offset:16
	v_or_b32_e32 v184, 32, v186
	v_ashrrev_i32_e32 v185, 31, v184
	v_lshlrev_b64 v[128:129], 7, v[184:185]
	v_or_b32_e32 v182, 48, v186
	v_lshl_add_u64 v[128:129], v[170:171], 0, v[128:129]
	v_ashrrev_i32_e32 v183, 31, v182
	global_load_dwordx4 v[212:215], v[128:129], off
	global_load_dwordx4 v[216:219], v[128:129], off offset:16
	v_lshlrev_b64 v[128:129], 7, v[182:183]
	v_lshl_add_u64 v[128:129], v[170:171], 0, v[128:129]
	global_load_dwordx4 v[220:223], v[128:129], off
	global_load_dwordx4 v[224:227], v[128:129], off offset:16
	v_and_b32_e32 v129, 64, v206
	v_lshl_or_b32 v178, s62, 7, v200
	v_xor_b32_e32 v128, 16, v206
	v_add_u32_e32 v129, 64, v129
	v_readlane_b32 s44, v243, 3
	v_xor_b32_e32 v130, 32, v206
	v_ashrrev_i32_e32 v179, 31, v178
	v_readlane_b32 s45, v243, 4
	v_cmp_lt_i32_e32 vcc, v128, v129
	s_movk_i32 s10, 0x2000
	v_lshl_add_u64 v[144:145], v[178:179], 2, s[44:45]
	v_cndmask_b32_e32 v134, v206, v128, vcc
	v_cmp_lt_i32_e32 vcc, v130, v129
	v_lshl_add_u64 v[132:133], v[144:145], 0, s[26:27]
	v_lshl_add_u64 v[136:137], v[144:145], 0, s[28:29]
	v_cndmask_b32_e32 v135, v206, v130, vcc
	v_add_co_u32_e32 v146, vcc, s10, v144
	global_load_dwordx4 v[128:131], v[144:145], off offset:16
	global_load_dwordx4 v[140:143], v[144:145], off
	v_addc_co_u32_e32 v147, vcc, 0, v145, vcc
	v_add_co_u32_e32 v148, vcc, s74, v144
	v_lshlrev_b32_e32 v196, 2, v134
	s_nop 0
	v_addc_co_u32_e32 v149, vcc, 0, v145, vcc
	v_lshlrev_b32_e32 v207, 2, v135
	global_load_dwordx4 v[132:135], v[132:133], off offset:16
	s_nop 0
	global_load_dwordx4 v[136:139], v[136:137], off offset:16
	s_nop 0
	global_load_dwordx4 v[144:147], v[146:147], off
	s_nop 0
	global_load_dwordx4 v[148:151], v[148:149], off
	v_mov_b32_e32 v197, 0
	v_mov_b32_e32 v211, 0
	v_readlane_b32 s46, v243, 5
	v_readlane_b32 s47, v243, 6
	v_readlane_b32 s48, v243, 7
	v_readlane_b32 s49, v243, 8
	v_readlane_b32 s50, v243, 9
	v_readlane_b32 s51, v243, 10
	v_readlane_b32 s52, v243, 11
	v_readlane_b32 s53, v243, 12
	v_readlane_b32 s54, v243, 13
	v_readlane_b32 s55, v243, 14
	v_readlane_b32 s56, v243, 15
	v_readlane_b32 s57, v243, 16
	v_readlane_b32 s58, v243, 17
	v_readlane_b32 s59, v243, 18
	s_waitcnt vmcnt(0)
; DI unsigned pack2(float lo, float hi) { f32x2 v = {lo, hi}; bf16v2 r = __builtin_convertvector(v, bf16v2); return __builtin_bit_cast(unsigned, r); }
; DI float dpp_ror1(float v) { return __int_as_float(__builtin_amdgcn_update_dpp(0, __float_as_int(v), 0x121, 0xf, 0xf, false)); }
; DI float dpp_ror2(float v) { return __int_as_float(__builtin_amdgcn_update_dpp(0, __float_as_int(v), 0x122, 0xf, 0xf, false)); }
; DI float row_rstd(const float* ssq, int row, int fq) {
;   const f32x4 a = *(const f32x4*)(ssq + (size_t)row * 32 + fq * 8), b = *(const f32x4*)(ssq + (size_t)row * 32 + fq * 8 + 4);
;   float sm = ((a[0] + a[1]) + (a[2] + a[3])) + ((b[0] + b[1]) + (b[2] + b[3]));
;   sm += __shfl_xor(sm, 16); sm += __shfl_xor(sm, 32);
;   return rsqrtf(sm * (1.0f / 2048.f) + 1e-6f);
;   DI void operator()(const f32x4 (&acc)[2][2][4][2], const Unit& u, int wr, int wc, int fr, int fq) const {
;     ...
;       const int row0 = u.pm * BM + ai * HALF + wr * 64, span = row0 >> 6;
;       float rsv[4];
; #pragma unroll
;       for (int m = 0; m < 4; ++m) rsv[m] = row_rstd(ssq, row0 + 16 * m + fr, fq);
;       float p1[8], p2[8];
; #pragma unroll
;       for (int e = 0; e < 8; ++e) { p1[e] = 0.f; p2[e] = 0.f; }
; #pragma unroll
;       for (int m = 0; m < 4; ++m) {
;         float g[8], a[8];
;         const float rs1 = rsv[m], rs2 = rs1 * rs1;
; #pragma unroll
;         for (int e = 0; e < 4; ++e) { g[e] = acc[ai][0][m][0][e] * acc[ai][1][m][0][e] * rs2; g[4 + e] = acc[ai][0][m][1][e] * acc[ai][1][m][1][e] * rs2; }
; #pragma unroll
;         for (int e = 0; e < 8; ++e) {
;           const float x1 = dpp_ror1(g[e]), x2 = dpp_ror2(g[e]);
;           const float pr1 = (fr == 0) ? p1[e] : x1, pr2 = (fr < 2) ? p2[e] : x2;
;           a[e] = w2[e] * g[e] + w1[e] * pr1 + w0[e] * pr2;
;           p1[e] = x1; p2[e] = x2;
;         }
;         if (m == 0 && fr < 2) {
;           float* hc = headC + (size_t)(span * 2 + fr) * 2048 + col;
;           *(f32x4*)hc = (f32x4){a[0], a[1], a[2], a[3]}; *(f32x4*)(hc + 4) = (f32x4){a[4], a[5], a[6], a[7]};
;         } else {
;           u32x4 w; w.x = pack2(a[0] * rs1, a[1] * rs1); w.y = pack2(a[2] * rs1, a[3] * rs1); w.z = pack2(a[4] * rs1, a[5] * rs1); w.w = pack2(a[6] * rs1, a[7] * rs1);
;           *(u32x4*)(C + (size_t)(row0 + 16 * m + fr) * 2048 + col) = w;
	v_mov_b32_e32 v208, v152
	v_mov_b32_e32 v209, v156
	v_mov_b32_e32 v156, v153
	v_mov_b32_e32 v152, v154
	v_mov_b32_e32 v153, v158
	v_mov_b32_e32 v158, v155
	v_pk_add_f32 v[154:155], v[208:209], v[156:157]
	v_pk_add_f32 v[152:153], v[152:153], v[158:159]
	v_mov_b32_e32 v156, v188
	v_mov_b32_e32 v157, v192
	v_mov_b32_e32 v192, v189
	v_mov_b32_e32 v158, v190
	v_mov_b32_e32 v159, v194
	v_mov_b32_e32 v194, v191
	v_pk_add_f32 v[152:153], v[154:155], v[152:153]
	v_pk_add_f32 v[154:155], v[156:157], v[192:193]
	v_pk_add_f32 v[156:157], v[158:159], v[194:195]
	v_mov_b32_e32 v188, v212
	v_pk_add_f32 v[154:155], v[154:155], v[156:157]
	v_mov_b32_e32 v157, v152
	v_mov_b32_e32 v156, v154
	v_mov_b32_e32 v152, v155
	v_pk_add_f32 v[152:153], v[156:157], v[152:153]
	ds_bpermute_b32 v155, v196, v153
	ds_bpermute_b32 v154, v196, v152
	v_mov_b32_e32 v189, v216
	v_mov_b32_e32 v216, v213
	v_mov_b32_e32 v190, v214
	v_mov_b32_e32 v191, v218
	s_waitcnt lgkmcnt(0)
	v_pk_add_f32 v[152:153], v[152:153], v[154:155]
	ds_bpermute_b32 v155, v207, v153
	ds_bpermute_b32 v154, v207, v152
	v_mov_b32_e32 v218, v215
	v_mov_b32_e32 v208, v220
	v_mov_b32_e32 v209, v224
	v_mov_b32_e32 v224, v221
	v_mov_b32_e32 v212, v222
	v_mov_b32_e32 v213, v226
	v_mov_b32_e32 v226, v223
	v_pk_add_f32 v[156:157], v[188:189], v[216:217]
	v_pk_add_f32 v[158:159], v[190:191], v[218:219]
	v_pk_add_f32 v[188:189], v[208:209], v[224:225]
	v_pk_add_f32 v[190:191], v[212:213], v[226:227]
	s_waitcnt lgkmcnt(0)
	v_pk_add_f32 v[152:153], v[152:153], v[154:155]
	v_pk_add_f32 v[156:157], v[156:157], v[158:159]
	v_pk_add_f32 v[158:159], v[188:189], v[190:191]
	v_pk_fma_f32 v[188:189], v[152:153], s[30:31], v[176:177] op_sel_hi:[1,0,0]
	v_mov_b32_e32 v153, v156
	v_mul_f32_e32 v152, 0x4b800000, v189
	v_cmp_gt_f32_e64 s[10:11], s84, v189
	v_mov_b32_e32 v156, v159
	v_mov_b32_e32 v194, v123
	v_cndmask_b32_e64 v152, v189, v152, s[10:11]
	v_rsq_f32_e32 v168, v152
	v_mov_b32_e32 v152, v158
	v_pk_add_f32 v[152:153], v[152:153], v[156:157]
	ds_bpermute_b32 v155, v196, v153
	ds_bpermute_b32 v154, v196, v152
	v_mul_f32_e32 v156, 0x45800000, v168
	v_cndmask_b32_e64 v195, v168, v156, s[10:11]
	v_mov_b32_e32 v217, 0
	v_mul_f32_e32 v156, v125, v113
	s_waitcnt lgkmcnt(0)
	v_pk_add_f32 v[190:191], v[152:153], v[154:155]
	v_mov_b32_e32 v152, v111
	v_mov_b32_e32 v153, v195
	v_mul_f32_e32 v154, v124, v112
	v_pk_mul_f32 v[152:153], v[194:195], v[152:153]
	v_mul_f32_e32 v155, v120, v108
	v_mul_f32_e32 v154, v154, v153
	v_pk_mul_f32 v[222:223], v[152:153], v[152:153] op_sel:[0,1] op_sel_hi:[1,0]
	v_mov_b32_e32 v213, 0
	v_mov_b32_dpp v217, v154 row_ror:1 row_mask:0xf bank_mask:0xf
	v_cndmask_b32_e64 v152, v217, 0, s[0:1]
	v_mul_f32_e32 v157, v121, v109
	v_mul_f32_e32 v158, v126, v114
	v_mul_f32_e32 v159, v122, v110
	v_mul_f32_e32 v168, v127, v115
	v_mul_f32_e32 v194, v155, v153
	v_mul_f32_e32 v155, v156, v153
	v_mov_b32_dpp v213, v154 row_ror:2 row_mask:0xf bank_mask:0xf
	v_mov_b32_e32 v221, 0
	v_mul_f32_e32 v152, v144, v152
	v_mul_f32_e32 v208, v157, v153
	v_mul_f32_e32 v156, v158, v153
	v_mul_f32_e32 v159, v159, v153
	v_mul_f32_e32 v157, v168, v153
	v_mov_b32_dpp v221, v155 row_ror:1 row_mask:0xf bank_mask:0xf
	v_cndmask_b32_e64 v153, v213, 0, s[8:9]
	v_fmac_f32_e32 v152, v148, v154
	v_mov_b32_e32 v219, 0
	v_fmac_f32_e32 v152, v140, v153
	v_cndmask_b32_e64 v153, v221, 0, s[0:1]
	v_mov_b32_dpp v219, v155 row_ror:2 row_mask:0xf bank_mask:0xf
	v_mul_f32_e32 v153, v145, v153
	v_mov_b32_e32 v216, 0
	v_cndmask_b32_e64 v154, v219, 0, s[8:9]
	v_fmac_f32_e32 v153, v149, v155
	v_mov_b32_dpp v216, v156 row_ror:1 row_mask:0xf bank_mask:0xf
	v_fmac_f32_e32 v153, v141, v154
	v_mov_b32_e32 v212, 0
	v_cndmask_b32_e64 v154, v216, 0, s[0:1]
	v_mov_b32_e32 v220, 0
	v_mov_b32_dpp v212, v156 row_ror:2 row_mask:0xf bank_mask:0xf
	v_mul_f32_e32 v154, v146, v154
	v_mov_b32_dpp v220, v157 row_ror:1 row_mask:0xf bank_mask:0xf
	v_cndmask_b32_e64 v155, v212, 0, s[8:9]
	v_fmac_f32_e32 v154, v150, v156
	v_mov_b32_e32 v218, 0
	v_fmac_f32_e32 v154, v142, v155
	v_cndmask_b32_e64 v155, v220, 0, s[0:1]
	v_mov_b32_dpp v218, v157 row_ror:2 row_mask:0xf bank_mask:0xf
	v_mul_f32_e32 v155, v147, v155
	v_cndmask_b32_e64 v156, v218, 0, s[8:9]
	v_fmac_f32_e32 v155, v151, v157
	v_mov_b32_dpp v197, v194 row_ror:1 row_mask:0xf bank_mask:0xf
	v_fmac_f32_e32 v155, v143, v156
	v_mov_b32_e32 v189, 0
	v_cndmask_b32_e64 v156, v197, 0, s[0:1]
	v_mov_b32_e32 v214, 0
	v_mov_b32_dpp v189, v194 row_ror:2 row_mask:0xf bank_mask:0xf
	v_mul_f32_e32 v156, v132, v156
	v_mov_b32_dpp v214, v208 row_ror:1 row_mask:0xf bank_mask:0xf
	v_cndmask_b32_e64 v157, v189, 0, s[8:9]
	v_fmac_f32_e32 v156, v136, v194
	v_fmac_f32_e32 v156, v128, v157
	v_cndmask_b32_e64 v157, v214, 0, s[0:1]
	v_mov_b32_e32 v209, 0
	v_mul_f32_e32 v157, v133, v157
	v_fmac_f32_e32 v157, v137, v208
	v_mov_b32_dpp v209, v208 row_ror:2 row_mask:0xf bank_mask:0xf
	v_mov_b32_e32 v208, 0
	v_cndmask_b32_e64 v158, v209, 0, s[8:9]
	v_fmac_f32_e32 v157, v129, v158
	v_mov_b32_dpp v208, v159 row_ror:1 row_mask:0xf bank_mask:0xf
	v_mov_b32_e32 v194, 0
	v_cndmask_b32_e64 v158, v208, 0, s[0:1]
	ds_bpermute_b32 v193, v207, v191
	ds_bpermute_b32 v192, v207, v190
	v_mov_b32_dpp v194, v159 row_ror:2 row_mask:0xf bank_mask:0xf
	v_mov_b32_e32 v215, 0
	v_mul_f32_e32 v158, v134, v158
	v_cndmask_b32_e64 v168, v194, 0, s[8:9]
	v_mov_b32_dpp v215, v222 row_ror:1 row_mask:0xf bank_mask:0xf
	v_fmac_f32_e32 v158, v138, v159
	v_mov_b32_dpp v211, v222 row_ror:2 row_mask:0xf bank_mask:0xf
	v_fmac_f32_e32 v158, v130, v168
	v_cndmask_b32_e64 v168, v215, 0, s[0:1]
	v_mul_f32_e32 v159, v139, v222
	v_cndmask_b32_e64 v223, v211, 0, s[8:9]
	v_fmac_f32_e32 v159, v135, v168
	v_cmp_gt_f32_e32 vcc, s84, v188
	v_fmac_f32_e32 v159, v131, v223
	s_and_saveexec_b64 s[10:11], s[4:5]
	s_xor_b64 s[10:11], exec, s[10:11]
	s_cbranch_execz .LBB0_1056
	v_mul_f32_e32 v152, v195, v152
	v_mul_f32_e32 v153, v195, v153
	v_cvt_pk_bf16_f32 v152, v152, v153
	v_mul_f32_e32 v153, v195, v154
	v_mul_f32_e32 v154, v195, v155
	v_cvt_pk_bf16_f32 v153, v153, v154
	v_mul_f32_e32 v154, v195, v156
	v_mul_f32_e32 v155, v195, v157
	v_cvt_pk_bf16_f32 v154, v154, v155
	v_mul_f32_e32 v155, v195, v158
	v_mul_f32_e32 v156, v195, v159
	v_cvt_pk_bf16_f32 v155, v155, v156
	v_lshlrev_b64 v[156:157], 12, v[186:187]
	v_lshl_add_u64 v[156:157], s[18:19], 0, v[156:157]
	v_lshl_add_u64 v[156:157], v[178:179], 1, v[156:157]
	global_store_dwordx4 v[156:157], v[152:155], off

; #define PG8_STAGE(bufoff, gbase, voff) do { _Pragma("unroll") for (int _i = 0; _i < 2; ++_i) \
;     __builtin_amdgcn_global_load_lds((const unsigned*)((const char*)(gbase) + (voff)[_i]), (LAS unsigned*)(lds + (bufoff) + ldsw + _i * 8192), 16, 0, 0); } while (0)
; #define PG8_LDA(dst, b, h) do { _Pragma("unroll") for (int m = 0; m < 4; ++m) _Pragma("unroll") for (int k = 0; k < 2; ++k) dst[m][k] = *(const LAS bf16x8*)(lds + PG8_SA(b, h) + aoff + m * 2048 + k * 1024); } while (0)
; #define PG8_LDB(dst, b, h) do { _Pragma("unroll") for (int n = 0; n < 2; ++n) _Pragma("unroll") for (int k = 0; k < 2; ++k) dst[n][k] = *(const LAS bf16x8*)(lds + PG8_SB(b, h) + boff + n * 2048 + k * 1024); } while (0)
; #define PG8_MMA(ai, bj, At, Bt) do { __builtin_amdgcn_s_setprio(1); _Pragma("unroll") for (int m = 0; m < 4; ++m) _Pragma("unroll") for (int n = 0; n < 2; ++n) _Pragma("unroll") for (int k = 0; k < 2; ++k) \
;     acc[ai][bj][m][n] = __builtin_amdgcn_mfma_f32_16x16x32_bf16(Bt[n][k], At[m][k], acc[ai][bj][m][n], 0, 0, 0); __builtin_amdgcn_s_setprio(0); } while (0)
; #define PG8_WAIT_L(n) asm volatile("s_waitcnt lgkmcnt(" #n ")" ::: "memory")
; #define PG8_BAR __builtin_amdgcn_s_barrier()
; #define PG8_SCHED __builtin_amdgcn_sched_barrier(0)
; template <class Epi, class Sched = StaticOrder>
; DI void gemm_phase(LAS unsigned char* lds, const Gemm g, const Sched& S, const Epi& E) {
;     ...
;     for (int t = 0; t < nt; t += 2) {
;       const bool last = (t == nt - 2);
;       const char* a1 = cA + (size_t)(t + 1) * kstep;
;       const char* a2 = last ? nA : cA + (size_t)(t + 2) * kstep; const char* b2 = last ? nB : cB + (size_t)(t + 2) * kstep;
;       const char* a3 = a2 + kstep; const char* b3 = b2 + kstep;
;       PG8_LDB(B0, 0, 0); PG8_SCHED; PG8_LDA(At, 0, 0); PG8_STAGE(PG8_SA(1, 1), a1 + hstep, voffA);
;       PG8_WAIT_L(8); PG8_BAR; PG8_WAIT_L(0); PG8_MMA(0, 0, At, B0); PG8_BAR; PG8_SCHED;
;       PG8_LDB(B1, 0, 1); PG8_STAGE(PG8_SB(0, 0), b2, voffB);
;       PG8_BAR; PG8_WAIT_L(0); PG8_MMA(0, 1, At, B1); PG8_BAR;
;       PG8_LDA(At, 0, 1); PG8_STAGE(PG8_SA(0, 0), a2, voffA);
;       PG8_BAR; PG8_WAIT_L(0); PG8_MMA(1, 0, At, B0); PG8_BAR; PG8_SCHED;
.LBB0_1194:
	s_add_u32 s24, s22, 0xfff80080
	s_addc_u32 s25, s23, -1
	s_cmp_eq_u32 s54, 28
	s_cselect_b32 s27, s17, s25
	s_cselect_b32 s26, s43, s24
	s_cselect_b32 s25, s15, s53
	s_cselect_b32 s24, s51, s52
	v_lshl_add_u64 v[192:193], s[22:23], 0, v[184:185]
	s_add_i32 m0, s37, 0xc000
	ds_read_b128 v[144:147], v215
	ds_read_b128 v[148:151], v215 offset:1024
	ds_read_b128 v[152:155], v215 offset:2048
	ds_read_b128 v[156:159], v215 offset:3072
	ds_read_b128 v[160:163], v215 offset:4096
	ds_read_b128 v[164:167], v215 offset:5120
	ds_read_b128 v[168:171], v215 offset:6144
	ds_read_b128 v[172:175], v215 offset:7168
	global_load_lds_dwordx4 v[192:193], off
	v_lshl_add_u64 v[192:193], s[22:23], 0, v[186:187]
	s_add_i32 m0, s37, 0xe000
	s_nop 0
	global_load_lds_dwordx4 v[192:193], off
	s_waitcnt lgkmcnt(0)
	s_setprio 1
	s_barrier
	v_mfma_f32_16x16x32_bf16 v[124:127], v[128:131], v[144:147], v[124:127]
	v_mfma_f32_16x16x32_bf16 v[120:123], v[136:139], v[144:147], v[120:123]
	v_mfma_f32_16x16x32_bf16 v[108:111], v[128:131], v[152:155], v[108:111]
	v_mfma_f32_16x16x32_bf16 v[104:107], v[136:139], v[152:155], v[104:107]
	v_mfma_f32_16x16x32_bf16 v[92:95], v[128:131], v[160:163], v[92:95]
	v_mfma_f32_16x16x32_bf16 v[88:91], v[136:139], v[160:163], v[88:91]
	v_mfma_f32_16x16x32_bf16 v[76:79], v[128:131], v[168:171], v[76:79]
	v_mfma_f32_16x16x32_bf16 v[72:75], v[136:139], v[168:171], v[72:75]
	v_mfma_f32_16x16x32_bf16 v[124:127], v[132:135], v[148:151], v[124:127]
	v_mfma_f32_16x16x32_bf16 v[120:123], v[140:143], v[148:151], v[120:123]
	v_mfma_f32_16x16x32_bf16 v[108:111], v[132:135], v[156:159], v[108:111]
	v_mfma_f32_16x16x32_bf16 v[104:107], v[140:143], v[156:159], v[104:107]
	v_mfma_f32_16x16x32_bf16 v[92:95], v[132:135], v[164:167], v[92:95]
	v_mfma_f32_16x16x32_bf16 v[88:91], v[140:143], v[164:167], v[88:91]
	v_mfma_f32_16x16x32_bf16 v[76:79], v[132:135], v[172:175], v[76:79]
	v_mfma_f32_16x16x32_bf16 v[72:75], v[140:143], v[172:175], v[72:75]
	s_barrier
	s_setprio 0
	s_add_i32 s55, s48, s35
	v_lshl_add_u64 v[208:209], s[24:25], 0, v[180:181]
	s_mov_b32 m0, s55
	ds_read_b128 v[192:195], v216
	ds_read_b128 v[196:199], v216 offset:1024
	ds_read_b128 v[200:203], v216 offset:2048
	ds_read_b128 v[204:207], v216 offset:3072
	global_load_lds_dwordx4 v[208:209], off
	v_lshl_add_u64 v[218:219], s[24:25], 0, v[176:177]
	s_add_i32 m0, s55, 0x2000
	s_nop 0
	global_load_lds_dwordx4 v[218:219], off
	s_waitcnt lgkmcnt(0)
	s_setprio 1
	s_barrier
	v_mfma_f32_16x16x32_bf16 v[116:119], v[192:195], v[144:147], v[116:119]
	v_mfma_f32_16x16x32_bf16 v[112:115], v[200:203], v[144:147], v[112:115]
	v_mfma_f32_16x16x32_bf16 v[100:103], v[192:195], v[152:155], v[100:103]
	v_mfma_f32_16x16x32_bf16 v[96:99], v[200:203], v[152:155], v[96:99]
	v_mfma_f32_16x16x32_bf16 v[84:87], v[192:195], v[160:163], v[84:87]
	v_mfma_f32_16x16x32_bf16 v[80:83], v[200:203], v[160:163], v[80:83]
	v_mfma_f32_16x16x32_bf16 v[68:71], v[192:195], v[168:171], v[68:71]
	v_mfma_f32_16x16x32_bf16 v[64:67], v[200:203], v[168:171], v[64:67]
	v_mfma_f32_16x16x32_bf16 v[116:119], v[196:199], v[148:151], v[116:119]
	v_mfma_f32_16x16x32_bf16 v[112:115], v[204:207], v[148:151], v[112:115]
	v_mfma_f32_16x16x32_bf16 v[100:103], v[196:199], v[156:159], v[100:103]
	v_mfma_f32_16x16x32_bf16 v[96:99], v[204:207], v[156:159], v[96:99]
	v_mfma_f32_16x16x32_bf16 v[84:87], v[196:199], v[164:167], v[84:87]
	v_mfma_f32_16x16x32_bf16 v[80:83], v[204:207], v[164:167], v[80:83]
	v_mfma_f32_16x16x32_bf16 v[68:71], v[196:199], v[172:175], v[68:71]
	v_mfma_f32_16x16x32_bf16 v[64:67], v[204:207], v[172:175], v[64:67]
	s_barrier
	s_setprio 0
	s_mov_b32 m0, s37
	v_lshl_add_u64 v[220:221], s[26:27], 0, v[182:183]
	ds_read_b128 v[144:147], v215 offset:16384
	ds_read_b128 v[148:151], v215 offset:17408
	ds_read_b128 v[152:155], v215 offset:18432
	ds_read_b128 v[156:159], v215 offset:19456
	ds_read_b128 v[160:163], v215 offset:20480
	ds_read_b128 v[164:167], v215 offset:21504
	ds_read_b128 v[168:171], v215 offset:22528
	ds_read_b128 v[172:175], v215 offset:23552
	global_load_lds_dwordx4 v[220:221], off
	v_lshl_add_u64 v[222:223], s[26:27], 0, v[178:179]
	s_mov_b32 m0, s38
	s_nop 0
	global_load_lds_dwordx4 v[222:223], off
	s_waitcnt vmcnt(10)
	s_waitcnt lgkmcnt(0)
	s_setprio 1
	s_barrier
	v_mfma_f32_16x16x32_bf16 v[60:63], v[128:131], v[144:147], v[60:63]
	v_mfma_f32_16x16x32_bf16 v[56:59], v[136:139], v[144:147], v[56:59]
	v_mfma_f32_16x16x32_bf16 v[44:47], v[128:131], v[152:155], v[44:47]
	v_mfma_f32_16x16x32_bf16 v[40:43], v[136:139], v[152:155], v[40:43]
	v_mfma_f32_16x16x32_bf16 v[28:31], v[128:131], v[160:163], v[28:31]
	v_mfma_f32_16x16x32_bf16 v[24:27], v[136:139], v[160:163], v[24:27]
	v_mfma_f32_16x16x32_bf16 v[12:15], v[128:131], v[168:171], v[12:15]
	v_mfma_f32_16x16x32_bf16 v[8:11], v[136:139], v[168:171], v[8:11]
	v_mfma_f32_16x16x32_bf16 v[60:63], v[132:135], v[148:151], v[60:63]
	v_mfma_f32_16x16x32_bf16 v[56:59], v[140:143], v[148:151], v[56:59]
	v_mfma_f32_16x16x32_bf16 v[44:47], v[132:135], v[156:159], v[44:47]
	v_mfma_f32_16x16x32_bf16 v[40:43], v[140:143], v[156:159], v[40:43]
	v_mfma_f32_16x16x32_bf16 v[28:31], v[132:135], v[164:167], v[28:31]
	v_mfma_f32_16x16x32_bf16 v[24:27], v[140:143], v[164:167], v[24:27]
	v_mfma_f32_16x16x32_bf16 v[12:15], v[132:135], v[172:175], v[12:15]
	v_mfma_f32_16x16x32_bf16 v[8:11], v[140:143], v[172:175], v[8:11]
	s_barrier
; #define PG8_STAGE(bufoff, gbase, voff) do { _Pragma("unroll") for (int _i = 0; _i < 2; ++_i) \
;     __builtin_amdgcn_global_load_lds((const unsigned*)((const char*)(gbase) + (voff)[_i]), (LAS unsigned*)(lds + (bufoff) + ldsw + _i * 8192), 16, 0, 0); } while (0)
; #define PG8_LDA(dst, b, h) do { _Pragma("unroll") for (int m = 0; m < 4; ++m) _Pragma("unroll") for (int k = 0; k < 2; ++k) dst[m][k] = *(const LAS bf16x8*)(lds + PG8_SA(b, h) + aoff + m * 2048 + k * 1024); } while (0)
; #define PG8_LDB(dst, b, h) do { _Pragma("unroll") for (int n = 0; n < 2; ++n) _Pragma("unroll") for (int k = 0; k < 2; ++k) dst[n][k] = *(const LAS bf16x8*)(lds + PG8_SB(b, h) + boff + n * 2048 + k * 1024); } while (0)
; #define PG8_MMA(ai, bj, At, Bt) do { __builtin_amdgcn_s_setprio(1); _Pragma("unroll") for (int m = 0; m < 4; ++m) _Pragma("unroll") for (int n = 0; n < 2; ++n) _Pragma("unroll") for (int k = 0; k < 2; ++k) \
;     acc[ai][bj][m][n] = __builtin_amdgcn_mfma_f32_16x16x32_bf16(Bt[n][k], At[m][k], acc[ai][bj][m][n], 0, 0, 0); __builtin_amdgcn_s_setprio(0); } while (0)
; #define PG8_WAIT_V(n) asm volatile("s_waitcnt vmcnt(" #n ")" ::: "memory")
; #define PG8_WAIT_L(n) asm volatile("s_waitcnt lgkmcnt(" #n ")" ::: "memory")
; #define PG8_BAR __builtin_amdgcn_s_barrier()
; #define PG8_SCHED __builtin_amdgcn_sched_barrier(0)
; template <class Epi, class Sched = StaticOrder>
; DI void gemm_phase(LAS unsigned char* lds, const Gemm g, const Sched& S, const Epi& E) {
;     ...
;       PG8_STAGE(PG8_SB(0, 1), b2 + hstep, voffB);
;       PG8_WAIT_V(6); PG8_BAR; PG8_MMA(1, 1, At, B1); PG8_BAR;
;       PG8_LDB(B0, 1, 0); PG8_SCHED; PG8_LDA(At, 1, 0); PG8_STAGE(PG8_SA(0, 1), a2 + hstep, voffA);
;       PG8_WAIT_L(8); PG8_BAR; PG8_WAIT_L(0); PG8_MMA(0, 0, At, B0); PG8_BAR; PG8_SCHED;
;       PG8_LDB(B1, 1, 1); PG8_STAGE(PG8_SB(1, 0), b3, voffB);
;       PG8_BAR; PG8_WAIT_L(0); PG8_MMA(0, 1, At, B1); PG8_BAR;
;       PG8_LDA(At, 1, 1); PG8_STAGE(PG8_SA(1, 0), a3, voffA);
;       PG8_BAR; PG8_WAIT_L(0); PG8_MMA(1, 0, At, B0); PG8_BAR; PG8_SCHED;
	s_setprio 0
	s_add_u32 s56, s24, 0x80000
	s_addc_u32 s57, s25, 0
	s_add_i32 s55, s49, s35
	v_lshl_add_u64 v[128:129], s[56:57], 0, v[180:181]
	s_mov_b32 m0, s55
	s_nop 0
	global_load_lds_dwordx4 v[128:129], off
	v_lshl_add_u64 v[128:129], s[56:57], 0, v[176:177]
	s_add_i32 m0, s55, 0x2000
	s_nop 0
	global_load_lds_dwordx4 v[128:129], off
	s_add_i32 s55, 0, 0x18000
	v_add_u32_e32 v140, s55, v212
	ds_read_b128 v[128:131], v140
	ds_read_b128 v[132:135], v140 offset:1024
	ds_read_b128 v[136:139], v140 offset:2048
	ds_read_b128 v[140:143], v140 offset:3072
	s_waitcnt vmcnt(6)
	s_setprio 1
	s_barrier
	v_mfma_f32_16x16x32_bf16 v[52:55], v[192:195], v[144:147], v[52:55]
	v_mfma_f32_16x16x32_bf16 v[48:51], v[200:203], v[144:147], v[48:51]
	v_mfma_f32_16x16x32_bf16 v[36:39], v[192:195], v[152:155], v[36:39]
	v_mfma_f32_16x16x32_bf16 v[32:35], v[200:203], v[152:155], v[32:35]
	v_mfma_f32_16x16x32_bf16 v[20:23], v[192:195], v[160:163], v[20:23]
	v_mfma_f32_16x16x32_bf16 v[16:19], v[200:203], v[160:163], v[16:19]
	v_mfma_f32_16x16x32_bf16 v[4:7], v[192:195], v[168:171], v[4:7]
	v_mfma_f32_16x16x32_bf16 v[0:3], v[200:203], v[168:171], v[0:3]
	v_mfma_f32_16x16x32_bf16 v[52:55], v[196:199], v[148:151], v[52:55]
	v_mfma_f32_16x16x32_bf16 v[48:51], v[204:207], v[148:151], v[48:51]
	v_mfma_f32_16x16x32_bf16 v[36:39], v[196:199], v[156:159], v[36:39]
	v_mfma_f32_16x16x32_bf16 v[32:35], v[204:207], v[156:159], v[32:35]
	v_mfma_f32_16x16x32_bf16 v[20:23], v[196:199], v[164:167], v[20:23]
	v_mfma_f32_16x16x32_bf16 v[16:19], v[204:207], v[164:167], v[16:19]
	v_mfma_f32_16x16x32_bf16 v[4:7], v[196:199], v[172:175], v[4:7]
	v_mfma_f32_16x16x32_bf16 v[0:3], v[204:207], v[172:175], v[0:3]
	s_barrier
	s_setprio 0
	s_add_u32 s26, s26, 0x80000
	s_addc_u32 s27, s27, 0
	s_mov_b32 m0, s39
	v_lshl_add_u64 v[192:193], s[26:27], 0, v[182:183]
	ds_read_b128 v[144:147], v215 offset:32768
	ds_read_b128 v[148:151], v215 offset:33792
	ds_read_b128 v[152:155], v215 offset:34816
	ds_read_b128 v[156:159], v215 offset:35840
	ds_read_b128 v[160:163], v215 offset:36864
	ds_read_b128 v[164:167], v215 offset:37888
	ds_read_b128 v[168:171], v215 offset:38912
	ds_read_b128 v[172:175], v215 offset:39936
	global_load_lds_dwordx4 v[192:193], off
	v_lshl_add_u64 v[192:193], s[26:27], 0, v[178:179]
	s_mov_b32 m0, s40
	s_nop 0
	global_load_lds_dwordx4 v[192:193], off
	s_waitcnt lgkmcnt(0)
	s_setprio 1
	s_barrier
	v_mfma_f32_16x16x32_bf16 v[124:127], v[128:131], v[144:147], v[124:127]
	v_mfma_f32_16x16x32_bf16 v[120:123], v[136:139], v[144:147], v[120:123]
	v_mfma_f32_16x16x32_bf16 v[108:111], v[128:131], v[152:155], v[108:111]
	v_mfma_f32_16x16x32_bf16 v[104:107], v[136:139], v[152:155], v[104:107]
	v_mfma_f32_16x16x32_bf16 v[92:95], v[128:131], v[160:163], v[92:95]
	v_mfma_f32_16x16x32_bf16 v[88:91], v[136:139], v[160:163], v[88:91]
	v_mfma_f32_16x16x32_bf16 v[76:79], v[128:131], v[168:171], v[76:79]
	v_mfma_f32_16x16x32_bf16 v[72:75], v[136:139], v[168:171], v[72:75]
	v_mfma_f32_16x16x32_bf16 v[124:127], v[132:135], v[148:151], v[124:127]
	v_mfma_f32_16x16x32_bf16 v[120:123], v[140:143], v[148:151], v[120:123]
	v_mfma_f32_16x16x32_bf16 v[108:111], v[132:135], v[156:159], v[108:111]
	v_mfma_f32_16x16x32_bf16 v[104:107], v[140:143], v[156:159], v[104:107]
	v_mfma_f32_16x16x32_bf16 v[92:95], v[132:135], v[164:167], v[92:95]
	v_mfma_f32_16x16x32_bf16 v[88:91], v[140:143], v[164:167], v[88:91]
	v_mfma_f32_16x16x32_bf16 v[76:79], v[132:135], v[172:175], v[76:79]
	v_mfma_f32_16x16x32_bf16 v[72:75], v[140:143], v[172:175], v[72:75]
	s_barrier
	s_setprio 0
	s_add_i32 s26, 0, 0x1c000
	s_add_i32 s27, s55, s35
	v_add_u32_e32 v204, s26, v212
	v_lshl_add_u64 v[208:209], v[208:209], 0, s[10:11]
	s_mov_b32 m0, s27
	ds_read_b128 v[192:195], v204
	ds_read_b128 v[196:199], v204 offset:1024
	ds_read_b128 v[200:203], v204 offset:2048
	ds_read_b128 v[204:207], v204 offset:3072
	global_load_lds_dwordx4 v[208:209], off
	v_lshl_add_u64 v[208:209], v[218:219], 0, s[10:11]
	s_add_i32 m0, s27, 0x2000
	s_nop 0
	global_load_lds_dwordx4 v[208:209], off
	s_waitcnt lgkmcnt(0)
	s_setprio 1
	s_barrier
	v_mfma_f32_16x16x32_bf16 v[116:119], v[192:195], v[144:147], v[116:119]
	v_mfma_f32_16x16x32_bf16 v[112:115], v[200:203], v[144:147], v[112:115]
	v_mfma_f32_16x16x32_bf16 v[100:103], v[192:195], v[152:155], v[100:103]
	v_mfma_f32_16x16x32_bf16 v[96:99], v[200:203], v[152:155], v[96:99]
	v_mfma_f32_16x16x32_bf16 v[84:87], v[192:195], v[160:163], v[84:87]
	v_mfma_f32_16x16x32_bf16 v[80:83], v[200:203], v[160:163], v[80:83]
	v_mfma_f32_16x16x32_bf16 v[68:71], v[192:195], v[168:171], v[68:71]
	v_mfma_f32_16x16x32_bf16 v[64:67], v[200:203], v[168:171], v[64:67]
	v_mfma_f32_16x16x32_bf16 v[116:119], v[196:199], v[148:151], v[116:119]
	v_mfma_f32_16x16x32_bf16 v[112:115], v[204:207], v[148:151], v[112:115]
	v_mfma_f32_16x16x32_bf16 v[100:103], v[196:199], v[156:159], v[100:103]
	v_mfma_f32_16x16x32_bf16 v[96:99], v[204:207], v[156:159], v[96:99]
	v_mfma_f32_16x16x32_bf16 v[84:87], v[196:199], v[164:167], v[84:87]
	v_mfma_f32_16x16x32_bf16 v[80:83], v[204:207], v[164:167], v[80:83]
	v_mfma_f32_16x16x32_bf16 v[68:71], v[196:199], v[172:175], v[68:71]
	v_mfma_f32_16x16x32_bf16 v[64:67], v[204:207], v[172:175], v[64:67]
	s_barrier
	s_setprio 0
	s_mov_b32 m0, s44
	v_lshl_add_u64 v[208:209], v[220:221], 0, s[10:11]
	ds_read_b128 v[144:147], v215 offset:49152
	ds_read_b128 v[148:151], v215 offset:50176
	ds_read_b128 v[152:155], v215 offset:51200
	ds_read_b128 v[156:159], v215 offset:52224
	ds_read_b128 v[160:163], v215 offset:53248
	ds_read_b128 v[164:167], v215 offset:54272
	ds_read_b128 v[168:171], v215 offset:55296
	ds_read_b128 v[172:175], v215 offset:56320
	global_load_lds_dwordx4 v[208:209], off
	v_lshl_add_u64 v[208:209], v[222:223], 0, s[10:11]
	s_mov_b32 m0, s45
	s_nop 0
	global_load_lds_dwordx4 v[208:209], off
	s_waitcnt vmcnt(10)
	s_waitcnt lgkmcnt(0)
	s_setprio 1
	s_barrier
; #define PG8_STAGE(bufoff, gbase, voff) do { _Pragma("unroll") for (int _i = 0; _i < 2; ++_i) \
;     __builtin_amdgcn_global_load_lds((const unsigned*)((const char*)(gbase) + (voff)[_i]), (LAS unsigned*)(lds + (bufoff) + ldsw + _i * 8192), 16, 0, 0); } while (0)
; #define PG8_MMA(ai, bj, At, Bt) do { __builtin_amdgcn_s_setprio(1); _Pragma("unroll") for (int m = 0; m < 4; ++m) _Pragma("unroll") for (int n = 0; n < 2; ++n) _Pragma("unroll") for (int k = 0; k < 2; ++k) \
;     acc[ai][bj][m][n] = __builtin_amdgcn_mfma_f32_16x16x32_bf16(Bt[n][k], At[m][k], acc[ai][bj][m][n], 0, 0, 0); __builtin_amdgcn_s_setprio(0); } while (0)
; #define PG8_WAIT_V(n) asm volatile("s_waitcnt vmcnt(" #n ")" ::: "memory")
; #define PG8_WAIT_L(n) asm volatile("s_waitcnt lgkmcnt(" #n ")" ::: "memory")
; #define PG8_BAR __builtin_amdgcn_s_barrier()
; #define PG8_SCHED __builtin_amdgcn_sched_barrier(0)
; template <class Epi, class Sched = StaticOrder>
; DI void gemm_phase(LAS unsigned char* lds, const Gemm g, const Sched& S, const Epi& E) {
;     ...
;       PG8_BAR; PG8_WAIT_L(0); PG8_MMA(1, 0, At, B0); PG8_BAR; PG8_SCHED;
;       PG8_STAGE(PG8_SB(1, 1), b3 + hstep, voffB);
;       PG8_WAIT_V(6); PG8_BAR; PG8_MMA(1, 1, At, B1); PG8_BAR;
;     }
	v_mfma_f32_16x16x32_bf16 v[60:63], v[128:131], v[144:147], v[60:63]
	v_mfma_f32_16x16x32_bf16 v[56:59], v[136:139], v[144:147], v[56:59]
	v_mfma_f32_16x16x32_bf16 v[44:47], v[128:131], v[152:155], v[44:47]
	v_mfma_f32_16x16x32_bf16 v[40:43], v[136:139], v[152:155], v[40:43]
	v_mfma_f32_16x16x32_bf16 v[28:31], v[128:131], v[160:163], v[28:31]
	v_mfma_f32_16x16x32_bf16 v[24:27], v[136:139], v[160:163], v[24:27]
	v_mfma_f32_16x16x32_bf16 v[12:15], v[128:131], v[168:171], v[12:15]
	v_mfma_f32_16x16x32_bf16 v[8:11], v[136:139], v[168:171], v[8:11]
	v_mfma_f32_16x16x32_bf16 v[60:63], v[132:135], v[148:151], v[60:63]
	v_mfma_f32_16x16x32_bf16 v[56:59], v[140:143], v[148:151], v[56:59]
	v_mfma_f32_16x16x32_bf16 v[44:47], v[132:135], v[156:159], v[44:47]
	v_mfma_f32_16x16x32_bf16 v[40:43], v[140:143], v[156:159], v[40:43]
	v_mfma_f32_16x16x32_bf16 v[28:31], v[132:135], v[164:167], v[28:31]
	v_mfma_f32_16x16x32_bf16 v[24:27], v[140:143], v[164:167], v[24:27]
	v_mfma_f32_16x16x32_bf16 v[12:15], v[132:135], v[172:175], v[12:15]
	v_mfma_f32_16x16x32_bf16 v[8:11], v[140:143], v[172:175], v[8:11]
	s_barrier
	s_setprio 0
	s_add_u32 s24, s24, 0x80080
	s_addc_u32 s25, s25, 0
	s_add_i32 s26, s26, s35
	v_lshl_add_u64 v[128:129], s[24:25], 0, v[180:181]
	s_mov_b32 m0, s26
	s_nop 0
	global_load_lds_dwordx4 v[128:129], off
	v_lshl_add_u64 v[128:129], s[24:25], 0, v[176:177]
	s_add_i32 m0, s26, 0x2000
	s_nop 0
	global_load_lds_dwordx4 v[128:129], off
	ds_read_b128 v[128:131], v214
	ds_read_b128 v[132:135], v214 offset:1024
	ds_read_b128 v[136:139], v214 offset:2048
	ds_read_b128 v[140:143], v214 offset:3072
	s_waitcnt vmcnt(6)
	s_setprio 1
	s_barrier
	v_mfma_f32_16x16x32_bf16 v[52:55], v[192:195], v[144:147], v[52:55]
	v_mfma_f32_16x16x32_bf16 v[48:51], v[200:203], v[144:147], v[48:51]
	v_mfma_f32_16x16x32_bf16 v[36:39], v[192:195], v[152:155], v[36:39]
	v_mfma_f32_16x16x32_bf16 v[32:35], v[200:203], v[152:155], v[32:35]
	v_mfma_f32_16x16x32_bf16 v[20:23], v[192:195], v[160:163], v[20:23]
	v_mfma_f32_16x16x32_bf16 v[16:19], v[200:203], v[160:163], v[16:19]
	v_mfma_f32_16x16x32_bf16 v[4:7], v[192:195], v[168:171], v[4:7]
	v_mfma_f32_16x16x32_bf16 v[0:3], v[200:203], v[168:171], v[0:3]
	v_mfma_f32_16x16x32_bf16 v[52:55], v[196:199], v[148:151], v[52:55]
	v_mfma_f32_16x16x32_bf16 v[48:51], v[204:207], v[148:151], v[48:51]
	v_mfma_f32_16x16x32_bf16 v[36:39], v[196:199], v[156:159], v[36:39]
	v_mfma_f32_16x16x32_bf16 v[32:35], v[204:207], v[156:159], v[32:35]
	v_mfma_f32_16x16x32_bf16 v[20:23], v[196:199], v[164:167], v[20:23]
	v_mfma_f32_16x16x32_bf16 v[16:19], v[204:207], v[164:167], v[16:19]
	v_mfma_f32_16x16x32_bf16 v[4:7], v[196:199], v[172:175], v[4:7]
	v_mfma_f32_16x16x32_bf16 v[0:3], v[204:207], v[172:175], v[0:3]
	s_add_i32 s54, s54, 2
	s_add_u32 s22, s22, 0x100
	s_addc_u32 s23, s23, 0
	s_add_u32 s52, s52, 0x100
	s_addc_u32 s53, s53, 0
	s_cmp_gt_u32 s54, 29
	s_barrier
	s_setprio 0
	s_cbranch_scc0 .LBB0_1194
; DI unsigned pack2(float lo, float hi) { f32x2 v = {lo, hi}; bf16v2 r = __builtin_convertvector(v, bf16v2); return __builtin_bit_cast(unsigned, r); }
;   DI void operator()(const f32x4 (&acc)[2][2][4][2], const Unit& u, int wr, int wc, int fr, int fq) const {
;     const int row0 = u.pm * BM + wr * 64 + fr, col0 = u.pn * BM + wc * 32 + 8 * fq;
; #pragma unroll
;     for (int ai = 0; ai < 2; ++ai) {
;       f32x4 bv[4][2][2];
; #pragma unroll
;       for (int m = 0; m < 4; ++m)
; #pragma unroll
;         for (int bj = 0; bj < 2; ++bj) {
;           const float* bp = base + (size_t)(row0 + ai * HALF + m * 16) * 2048 + col0 + bj * HALF;
;           bv[m][bj][0] = *(const f32x4*)bp; bv[m][bj][1] = *(const f32x4*)(bp + 4);
;         }
; #pragma unroll
;       for (int m = 0; m < 4; ++m) {
;         const int row = row0 + ai * HALF + m * 16;
;         const size_t off = (size_t)row * 2048 + col0;
;         float ss = 0.f;
; #pragma unroll
;         for (int bj = 0; bj < 2; ++bj) {
;           const f32x4 v0 = acc[ai][bj][m][0] + bv[m][bj][0], v1 = acc[ai][bj][m][1] + bv[m][bj][1];
;           *(f32x4*)(C + off + bj * HALF) = v0; *(f32x4*)(C + off + bj * HALF + 4) = v1;
;           if (xb) {
;             u32x4 w; w.x = pack2(v0[0], v0[1]); w.y = pack2(v0[2], v0[3]); w.z = pack2(v1[0], v1[1]); w.w = pack2(v1[2], v1[3]);
;             *(u32x4*)(xb + off + bj * HALF) = w;
;             ss += v0[0] * v0[0] + v0[1] * v0[1] + v0[2] * v0[2] + v0[3] * v0[3] + v1[0] * v1[0] + v1[1] * v1[1] + v1[2] * v1[2] + v1[3] * v1[3];
;           }
;         }
;         if (xb) {
;           ss += __shfl_xor(ss, 16); ss += __shfl_xor(ss, 32);
;           if (fq == 0) ssq[(size_t)row * 32 + u.pn * 4 + wc] = ss;
;         }
	s_waitcnt lgkmcnt(0)
	v_lshl_add_u32 v194, s12, 8, v211
	v_lshl_or_b32 v192, s42, 8, v213
	v_readlane_b32 s52, v243, 3
	v_ashrrev_i32_e32 v193, 31, v192
	v_readlane_b32 s66, v243, 17
	v_readlane_b32 s67, v243, 18
	v_ashrrev_i32_e32 v195, 31, v194
	v_lshlrev_b64 v[128:129], 13, v[194:195]
	v_lshl_add_u64 v[196:197], v[192:193], 2, s[66:67]
	v_lshl_add_u64 v[236:237], v[196:197], 0, v[128:129]
	global_load_dwordx4 v[220:223], v[236:237], off
	global_load_dwordx4 v[224:227], v[236:237], off offset:16
	global_load_dwordx4 v[228:231], v[236:237], off offset:512
	global_load_dwordx4 v[232:235], v[236:237], off offset:528
	v_or_b32_e32 v206, 16, v194
	v_or_b32_e32 v202, 32, v194
	v_or_b32_e32 v198, 48, v194
	v_ashrrev_i32_e32 v207, 31, v206
	v_ashrrev_i32_e32 v203, 31, v202
	v_ashrrev_i32_e32 v199, 31, v198
	v_lshlrev_b64 v[128:129], 13, v[206:207]
	v_lshlrev_b64 v[130:131], 13, v[202:203]
	v_lshlrev_b64 v[132:133], 13, v[198:199]
	v_lshl_add_u64 v[208:209], v[196:197], 0, v[128:129]
	v_lshl_add_u64 v[204:205], v[196:197], 0, v[130:131]
	v_lshl_add_u64 v[200:201], v[196:197], 0, v[132:133]
	global_load_dwordx4 v[168:171], v[208:209], off offset:16
	global_load_dwordx4 v[172:175], v[208:209], off
	global_load_dwordx4 v[160:163], v[208:209], off offset:528
	global_load_dwordx4 v[164:167], v[208:209], off offset:512
	global_load_dwordx4 v[152:155], v[204:205], off offset:16
	global_load_dwordx4 v[156:159], v[204:205], off
	global_load_dwordx4 v[144:147], v[204:205], off offset:528
	global_load_dwordx4 v[148:151], v[204:205], off offset:512
	global_load_dwordx4 v[136:139], v[200:201], off offset:16
	global_load_dwordx4 v[140:143], v[200:201], off
	global_load_dwordx4 v[128:131], v[200:201], off offset:528
	global_load_dwordx4 v[132:135], v[200:201], off offset:512
	v_and_b32_e32 v218, 64, v217
	v_xor_b32_e32 v238, 16, v217
	v_add_u32_e32 v240, 64, v218
	v_xor_b32_e32 v239, 32, v217
	v_cmp_lt_i32_e32 vcc, v238, v240
	v_lshlrev_b64 v[218:219], 11, v[194:195]
	s_lshl_b32 s22, s42, 2
	v_cndmask_b32_e32 v241, v217, v238, vcc
	v_cmp_lt_i32_e32 vcc, v239, v240
	s_ashr_i32 s23, s22, 31
	v_readlane_b32 s53, v243, 4
	v_cndmask_b32_e32 v240, v217, v239, vcc
	v_lshl_add_u64 v[238:239], v[218:219], 0, v[192:193]
	v_lshlrev_b32_e32 v218, 2, v241
	v_lshl_add_u64 v[238:239], v[238:239], 1, s[2:3]
	v_readlane_b32 s54, v243, 5
	v_readlane_b32 s55, v243, 6
	v_readlane_b32 s56, v243, 7
	v_readlane_b32 s57, v243, 8
	v_readlane_b32 s58, v243, 9
	v_readlane_b32 s59, v243, 10
	v_readlane_b32 s60, v243, 11
	v_readlane_b32 s61, v243, 12
	v_readlane_b32 s62, v243, 13
	v_readlane_b32 s63, v243, 14
	v_readlane_b32 s64, v243, 15
	v_readlane_b32 s65, v243, 16
	s_waitcnt vmcnt(0)
	v_pk_add_f32 v[126:127], v[126:127], v[222:223]
	v_pk_add_f32 v[124:125], v[124:125], v[220:221]
	v_pk_add_f32 v[116:117], v[116:117], v[228:229]
	v_pk_add_f32 v[122:123], v[122:123], v[226:227]
	v_pk_add_f32 v[120:121], v[120:121], v[224:225]
	v_pk_add_f32 v[220:221], v[112:113], v[232:233]
	global_store_dwordx4 v[236:237], v[124:127], off
	global_store_dwordx4 v[236:237], v[120:123], off offset:16
	v_cvt_pk_bf16_f32 v112, v124, v125
	v_mul_f32_e32 v125, v125, v125
	v_mul_f32_e32 v219, v117, v117
	v_pk_add_f32 v[118:119], v[118:119], v[230:231]
	v_fmac_f32_e32 v125, v124, v124
	v_fmac_f32_e32 v219, v116, v116
	v_fmac_f32_e32 v125, v126, v126
	v_fmac_f32_e32 v219, v118, v118
	v_fmac_f32_e32 v125, v127, v127
	v_fmac_f32_e32 v219, v119, v119
	v_fmac_f32_e32 v125, v120, v120
	v_fmac_f32_e32 v219, v220, v220
	v_pk_add_f32 v[222:223], v[114:115], v[234:235]
	v_fmac_f32_e32 v125, v121, v121
	v_fmac_f32_e32 v219, v221, v221
	v_fmac_f32_e32 v125, v122, v122
	v_fmac_f32_e32 v219, v222, v222
	v_fmac_f32_e32 v125, v123, v123
	v_fmac_f32_e32 v219, v223, v223
	v_cvt_pk_bf16_f32 v114, v120, v121
	v_add_f32_e32 v121, v125, v219
	v_cvt_pk_bf16_f32 v115, v122, v123
	ds_bpermute_b32 v122, v218, v121
	v_cvt_pk_bf16_f32 v113, v126, v127
	global_store_dwordx4 v[238:239], v[112:115], off
	global_store_dwordx4 v[236:237], v[116:119], off offset:512
	global_store_dwordx4 v[236:237], v[220:223], off offset:528
	v_lshlrev_b32_e32 v126, 2, v240
	v_cvt_pk_bf16_f32 v120, v116, v117
	s_waitcnt lgkmcnt(0)
	v_add_f32_e32 v112, v121, v122
	ds_bpermute_b32 v113, v126, v112
	v_cvt_pk_bf16_f32 v121, v118, v119
	v_cvt_pk_bf16_f32 v122, v220, v221
	v_cvt_pk_bf16_f32 v123, v222, v223
	global_store_dwordx4 v[238:239], v[120:123], off offset:256
	s_and_saveexec_b64 s[24:25], s[0:1]
	s_cbranch_execz .LBB0_1197
	s_waitcnt lgkmcnt(0)
	v_add_f32_e32 v114, v112, v113
	v_lshlrev_b64 v[112:113], 7, v[194:195]
	v_lshl_add_u64 v[112:113], s[8:9], 0, v[112:113]
	v_lshl_add_u64 v[112:113], s[22:23], 2, v[112:113]
	s_lshl_b32 s12, s41, 2
	v_lshl_add_u64 v[112:113], v[112:113], 0, s[12:13]
	global_store_dword v[112:113], v114, off

; #define PG8_STAGE(bufoff, gbase, voff) do { _Pragma("unroll") for (int _i = 0; _i < 2; ++_i) \
;     __builtin_amdgcn_global_load_lds((const unsigned*)((const char*)(gbase) + (voff)[_i]), (LAS unsigned*)(lds + (bufoff) + ldsw + _i * 8192), 16, 0, 0); } while (0)
; #define PG8_LDA(dst, b, h) do { _Pragma("unroll") for (int m = 0; m < 4; ++m) _Pragma("unroll") for (int k = 0; k < 2; ++k) dst[m][k] = *(const LAS bf16x8*)(lds + PG8_SA(b, h) + aoff + m * 2048 + k * 1024); } while (0)
; #define PG8_LDB(dst, b, h) do { _Pragma("unroll") for (int n = 0; n < 2; ++n) _Pragma("unroll") for (int k = 0; k < 2; ++k) dst[n][k] = *(const LAS bf16x8*)(lds + PG8_SB(b, h) + boff + n * 2048 + k * 1024); } while (0)
; #define PG8_MMA(ai, bj, At, Bt) do { __builtin_amdgcn_s_setprio(1); _Pragma("unroll") for (int m = 0; m < 4; ++m) _Pragma("unroll") for (int n = 0; n < 2; ++n) _Pragma("unroll") for (int k = 0; k < 2; ++k) \
;     acc[ai][bj][m][n] = __builtin_amdgcn_mfma_f32_16x16x32_bf16(Bt[n][k], At[m][k], acc[ai][bj][m][n], 0, 0, 0); __builtin_amdgcn_s_setprio(0); } while (0)
; #define PG8_WAIT_V(n) asm volatile("s_waitcnt vmcnt(" #n ")" ::: "memory")
; #define PG8_WAIT_L(n) asm volatile("s_waitcnt lgkmcnt(" #n ")" ::: "memory")
; #define PG8_BAR __builtin_amdgcn_s_barrier()
; #define PG8_SCHED __builtin_amdgcn_sched_barrier(0)
; template <class Epi, class Sched = StaticOrder>
; DI void gemm_phase(LAS unsigned char* lds, const Gemm g, const Sched& S, const Epi& E) {
;     ...
;     for (int t = 0; t < nt; t += 2) {
;       const bool last = (t == nt - 2);
;       const char* a1 = cA + (size_t)(t + 1) * kstep;
;       const char* a2 = last ? nA : cA + (size_t)(t + 2) * kstep; const char* b2 = last ? nB : cB + (size_t)(t + 2) * kstep;
;       const char* a3 = a2 + kstep; const char* b3 = b2 + kstep;
;       PG8_LDB(B0, 0, 0); PG8_SCHED; PG8_LDA(At, 0, 0); PG8_STAGE(PG8_SA(1, 1), a1 + hstep, voffA);
;       PG8_WAIT_L(8); PG8_BAR; PG8_WAIT_L(0); PG8_MMA(0, 0, At, B0); PG8_BAR; PG8_SCHED;
;       PG8_LDB(B1, 0, 1); PG8_STAGE(PG8_SB(0, 0), b2, voffB);
;       PG8_BAR; PG8_WAIT_L(0); PG8_MMA(0, 1, At, B1); PG8_BAR;
;       PG8_LDA(At, 0, 1); PG8_STAGE(PG8_SA(0, 0), a2, voffA);
;       PG8_BAR; PG8_WAIT_L(0); PG8_MMA(1, 0, At, B0); PG8_BAR; PG8_SCHED;
;       PG8_STAGE(PG8_SB(0, 1), b2 + hstep, voffB);
;       PG8_WAIT_V(6); PG8_BAR; PG8_MMA(1, 1, At, B1); PG8_BAR;
.LBB0_1277:
	s_add_u32 s48, s14, 0xfff80080
	s_addc_u32 s49, s15, -1
	s_cmp_eq_u32 s58, 28
	s_cselect_b32 s51, s41, s49
	s_cselect_b32 s50, s42, s48
	s_cselect_b32 s49, s39, s53
	s_cselect_b32 s48, s43, s52
	v_lshl_add_u64 v[196:197], s[14:15], 0, v[170:171]
	s_add_i32 m0, s64, 0xc000
	ds_read_b128 v[80:83], v202
	ds_read_b128 v[84:87], v202 offset:1024
	ds_read_b128 v[88:91], v202 offset:2048
	ds_read_b128 v[92:95], v202 offset:3072
	ds_read_b128 v[180:183], v202 offset:4096
	ds_read_b128 v[184:187], v202 offset:5120
	ds_read_b128 v[188:191], v202 offset:6144
	ds_read_b128 v[192:195], v202 offset:7168
	global_load_lds_dwordx4 v[196:197], off
	v_lshl_add_u64 v[196:197], s[14:15], 0, v[172:173]
	s_add_i32 m0, s64, 0xe000
	s_nop 0
	global_load_lds_dwordx4 v[196:197], off
	s_waitcnt lgkmcnt(0)
	s_setprio 1
	s_barrier
	v_mfma_f32_16x16x32_bf16 v[156:159], v[64:67], v[80:83], v[156:159]
	v_mfma_f32_16x16x32_bf16 v[144:147], v[72:75], v[80:83], v[144:147]
	v_mfma_f32_16x16x32_bf16 v[140:143], v[64:67], v[88:91], v[140:143]
	v_mfma_f32_16x16x32_bf16 v[132:135], v[72:75], v[88:91], v[132:135]
	v_mfma_f32_16x16x32_bf16 v[124:127], v[64:67], v[180:183], v[124:127]
	v_mfma_f32_16x16x32_bf16 v[116:119], v[72:75], v[180:183], v[116:119]
	v_mfma_f32_16x16x32_bf16 v[112:115], v[64:67], v[188:191], v[112:115]
	v_mfma_f32_16x16x32_bf16 v[108:111], v[72:75], v[188:191], v[108:111]
	v_mfma_f32_16x16x32_bf16 v[156:159], v[68:71], v[84:87], v[156:159]
	v_mfma_f32_16x16x32_bf16 v[144:147], v[76:79], v[84:87], v[144:147]
	v_mfma_f32_16x16x32_bf16 v[140:143], v[68:71], v[92:95], v[140:143]
	v_mfma_f32_16x16x32_bf16 v[132:135], v[76:79], v[92:95], v[132:135]
	v_mfma_f32_16x16x32_bf16 v[124:127], v[68:71], v[184:187], v[124:127]
	v_mfma_f32_16x16x32_bf16 v[116:119], v[76:79], v[184:187], v[116:119]
	v_mfma_f32_16x16x32_bf16 v[112:115], v[68:71], v[192:195], v[112:115]
	v_mfma_f32_16x16x32_bf16 v[108:111], v[76:79], v[192:195], v[108:111]
	s_barrier
	s_setprio 0
	s_add_i32 s59, s72, s62
	v_lshl_add_u64 v[196:197], s[48:49], 0, v[164:165]
	s_mov_b32 m0, s59
	ds_read_b128 v[206:209], v203
	ds_read_b128 v[212:215], v203 offset:1024
	ds_read_b128 v[216:219], v203 offset:2048
	ds_read_b128 v[220:223], v203 offset:3072
	global_load_lds_dwordx4 v[196:197], off
	v_lshl_add_u64 v[232:233], s[48:49], 0, v[160:161]
	s_add_i32 m0, s59, 0x2000
	s_nop 0
	global_load_lds_dwordx4 v[232:233], off
	s_waitcnt lgkmcnt(0)
	s_setprio 1
	s_barrier
	v_mfma_f32_16x16x32_bf16 v[152:155], v[206:209], v[80:83], v[152:155]
	v_mfma_f32_16x16x32_bf16 v[80:83], v[216:219], v[80:83], v[148:151]
	v_mfma_f32_16x16x32_bf16 v[152:155], v[212:215], v[84:87], v[152:155]
	v_mfma_f32_16x16x32_bf16 v[80:83], v[220:223], v[84:87], v[80:83]
	v_mfma_f32_16x16x32_bf16 v[84:87], v[206:209], v[88:91], v[136:139]
	v_mfma_f32_16x16x32_bf16 v[88:91], v[216:219], v[88:91], v[128:131]
	v_mfma_f32_16x16x32_bf16 v[104:107], v[216:219], v[180:183], v[104:107]
	v_mfma_f32_16x16x32_bf16 v[100:103], v[206:209], v[188:191], v[100:103]
	v_mfma_f32_16x16x32_bf16 v[96:99], v[216:219], v[188:191], v[96:99]
	v_mfma_f32_16x16x32_bf16 v[84:87], v[212:215], v[92:95], v[84:87]
	v_mfma_f32_16x16x32_bf16 v[88:91], v[220:223], v[92:95], v[88:91]
	v_mfma_f32_16x16x32_bf16 v[92:95], v[206:209], v[180:183], v[120:123]
	v_mfma_f32_16x16x32_bf16 v[104:107], v[220:223], v[184:187], v[104:107]
	v_mfma_f32_16x16x32_bf16 v[100:103], v[212:215], v[192:195], v[100:103]
	v_mfma_f32_16x16x32_bf16 v[96:99], v[220:223], v[192:195], v[96:99]
	v_mfma_f32_16x16x32_bf16 v[92:95], v[212:215], v[184:187], v[92:95]
	s_barrier
	s_setprio 0
	s_mov_b32 m0, s64
	v_lshl_add_u64 v[234:235], s[50:51], 0, v[166:167]
	ds_read_b128 v[120:123], v202 offset:16384
	ds_read_b128 v[128:131], v202 offset:17408
	ds_read_b128 v[136:139], v202 offset:18432
	ds_read_b128 v[148:151], v202 offset:19456
	ds_read_b128 v[180:183], v202 offset:20480
	ds_read_b128 v[184:187], v202 offset:21504
	ds_read_b128 v[188:191], v202 offset:22528
	ds_read_b128 v[192:195], v202 offset:23552
	global_load_lds_dwordx4 v[234:235], off
	v_lshl_add_u64 v[236:237], s[50:51], 0, v[162:163]
	s_mov_b32 m0, s65
	s_nop 0
	global_load_lds_dwordx4 v[236:237], off
	s_waitcnt vmcnt(10)
	s_waitcnt lgkmcnt(0)
	s_setprio 1
	s_barrier
	v_mfma_f32_16x16x32_bf16 v[60:63], v[64:67], v[120:123], v[60:63]
	v_mfma_f32_16x16x32_bf16 v[48:51], v[72:75], v[120:123], v[48:51]
	v_mfma_f32_16x16x32_bf16 v[44:47], v[64:67], v[136:139], v[44:47]
	v_mfma_f32_16x16x32_bf16 v[36:39], v[72:75], v[136:139], v[36:39]
	v_mfma_f32_16x16x32_bf16 v[28:31], v[64:67], v[180:183], v[28:31]
	v_mfma_f32_16x16x32_bf16 v[20:23], v[72:75], v[180:183], v[20:23]
	v_mfma_f32_16x16x32_bf16 v[16:19], v[64:67], v[188:191], v[16:19]
	v_mfma_f32_16x16x32_bf16 v[12:15], v[72:75], v[188:191], v[12:15]
	v_mfma_f32_16x16x32_bf16 v[60:63], v[68:71], v[128:131], v[60:63]
	v_mfma_f32_16x16x32_bf16 v[48:51], v[76:79], v[128:131], v[48:51]
	v_mfma_f32_16x16x32_bf16 v[44:47], v[68:71], v[148:151], v[44:47]
	v_mfma_f32_16x16x32_bf16 v[36:39], v[76:79], v[148:151], v[36:39]
	v_mfma_f32_16x16x32_bf16 v[28:31], v[68:71], v[184:187], v[28:31]
	v_mfma_f32_16x16x32_bf16 v[20:23], v[76:79], v[184:187], v[20:23]
	v_mfma_f32_16x16x32_bf16 v[16:19], v[68:71], v[192:195], v[16:19]
	v_mfma_f32_16x16x32_bf16 v[12:15], v[76:79], v[192:195], v[12:15]
	s_barrier
	s_setprio 0
	s_add_u32 s78, s48, 0x80000
	s_addc_u32 s79, s49, 0
	s_add_i32 s59, s73, s62
	v_lshl_add_u64 v[64:65], s[78:79], 0, v[164:165]
	s_mov_b32 m0, s59
	s_nop 0
	global_load_lds_dwordx4 v[64:65], off
	v_lshl_add_u64 v[64:65], s[78:79], 0, v[160:161]
	s_add_i32 m0, s59, 0x2000
	s_nop 0
	global_load_lds_dwordx4 v[64:65], off
	s_add_i32 s59, 0, 0x18000
	v_add_u32_e32 v76, s59, v198
	ds_read_b128 v[64:67], v76
	ds_read_b128 v[68:71], v76 offset:1024
	ds_read_b128 v[72:75], v76 offset:2048
	ds_read_b128 v[76:79], v76 offset:3072
	s_waitcnt vmcnt(6)
	s_setprio 1
	s_barrier
; #define PG8_STAGE(bufoff, gbase, voff) do { _Pragma("unroll") for (int _i = 0; _i < 2; ++_i) \
;     __builtin_amdgcn_global_load_lds((const unsigned*)((const char*)(gbase) + (voff)[_i]), (LAS unsigned*)(lds + (bufoff) + ldsw + _i * 8192), 16, 0, 0); } while (0)
; #define PG8_LDA(dst, b, h) do { _Pragma("unroll") for (int m = 0; m < 4; ++m) _Pragma("unroll") for (int k = 0; k < 2; ++k) dst[m][k] = *(const LAS bf16x8*)(lds + PG8_SA(b, h) + aoff + m * 2048 + k * 1024); } while (0)
; #define PG8_LDB(dst, b, h) do { _Pragma("unroll") for (int n = 0; n < 2; ++n) _Pragma("unroll") for (int k = 0; k < 2; ++k) dst[n][k] = *(const LAS bf16x8*)(lds + PG8_SB(b, h) + boff + n * 2048 + k * 1024); } while (0)
; #define PG8_MMA(ai, bj, At, Bt) do { __builtin_amdgcn_s_setprio(1); _Pragma("unroll") for (int m = 0; m < 4; ++m) _Pragma("unroll") for (int n = 0; n < 2; ++n) _Pragma("unroll") for (int k = 0; k < 2; ++k) \
;     acc[ai][bj][m][n] = __builtin_amdgcn_mfma_f32_16x16x32_bf16(Bt[n][k], At[m][k], acc[ai][bj][m][n], 0, 0, 0); __builtin_amdgcn_s_setprio(0); } while (0)
; #define PG8_WAIT_V(n) asm volatile("s_waitcnt vmcnt(" #n ")" ::: "memory")
; #define PG8_WAIT_L(n) asm volatile("s_waitcnt lgkmcnt(" #n ")" ::: "memory")
; #define PG8_BAR __builtin_amdgcn_s_barrier()
; #define PG8_SCHED __builtin_amdgcn_sched_barrier(0)
; template <class Epi, class Sched = StaticOrder>
; DI void gemm_phase(LAS unsigned char* lds, const Gemm g, const Sched& S, const Epi& E) {
;     ...
;       PG8_WAIT_V(6); PG8_BAR; PG8_MMA(1, 1, At, B1); PG8_BAR;
;       PG8_LDB(B0, 1, 0); PG8_SCHED; PG8_LDA(At, 1, 0); PG8_STAGE(PG8_SA(0, 1), a2 + hstep, voffA);
;       PG8_WAIT_L(8); PG8_BAR; PG8_WAIT_L(0); PG8_MMA(0, 0, At, B0); PG8_BAR; PG8_SCHED;
;       PG8_LDB(B1, 1, 1); PG8_STAGE(PG8_SB(1, 0), b3, voffB);
;       PG8_BAR; PG8_WAIT_L(0); PG8_MMA(0, 1, At, B1); PG8_BAR;
;       PG8_LDA(At, 1, 1); PG8_STAGE(PG8_SA(1, 0), a3, voffA);
;       PG8_BAR; PG8_WAIT_L(0); PG8_MMA(1, 0, At, B0); PG8_BAR; PG8_SCHED;
	v_mfma_f32_16x16x32_bf16 v[56:59], v[206:209], v[120:123], v[56:59]
	v_mfma_f32_16x16x32_bf16 v[52:55], v[216:219], v[120:123], v[52:55]
	v_mfma_f32_16x16x32_bf16 v[40:43], v[206:209], v[136:139], v[40:43]
	v_mfma_f32_16x16x32_bf16 v[32:35], v[216:219], v[136:139], v[32:35]
	v_mfma_f32_16x16x32_bf16 v[24:27], v[206:209], v[180:183], v[24:27]
	v_mfma_f32_16x16x32_bf16 v[8:11], v[216:219], v[180:183], v[8:11]
	v_mfma_f32_16x16x32_bf16 v[4:7], v[206:209], v[188:191], v[4:7]
	v_mfma_f32_16x16x32_bf16 v[0:3], v[216:219], v[188:191], v[0:3]
	v_mfma_f32_16x16x32_bf16 v[56:59], v[212:215], v[128:131], v[56:59]
	v_mfma_f32_16x16x32_bf16 v[52:55], v[220:223], v[128:131], v[52:55]
	v_mfma_f32_16x16x32_bf16 v[40:43], v[212:215], v[148:151], v[40:43]
	v_mfma_f32_16x16x32_bf16 v[32:35], v[220:223], v[148:151], v[32:35]
	v_mfma_f32_16x16x32_bf16 v[24:27], v[212:215], v[184:187], v[24:27]
	v_mfma_f32_16x16x32_bf16 v[8:11], v[220:223], v[184:187], v[8:11]
	v_mfma_f32_16x16x32_bf16 v[4:7], v[212:215], v[192:195], v[4:7]
	v_mfma_f32_16x16x32_bf16 v[0:3], v[220:223], v[192:195], v[0:3]
	s_barrier
	s_setprio 0
	s_add_u32 s50, s50, 0x80000
	s_addc_u32 s51, s51, 0
	s_mov_b32 m0, s66
	v_lshl_add_u64 v[136:137], s[50:51], 0, v[166:167]
	ds_read_b128 v[120:123], v202 offset:32768
	ds_read_b128 v[128:131], v202 offset:33792
	ds_read_b128 v[180:183], v202 offset:34816
	ds_read_b128 v[184:187], v202 offset:35840
	ds_read_b128 v[188:191], v202 offset:36864
	ds_read_b128 v[192:195], v202 offset:37888
	ds_read_b128 v[206:209], v202 offset:38912
	ds_read_b128 v[212:215], v202 offset:39936
	global_load_lds_dwordx4 v[136:137], off
	v_lshl_add_u64 v[136:137], s[50:51], 0, v[162:163]
	s_mov_b32 m0, s67
	s_nop 0
	global_load_lds_dwordx4 v[136:137], off
	s_waitcnt lgkmcnt(0)
	s_setprio 1
	s_barrier
	v_mfma_f32_16x16x32_bf16 v[136:139], v[64:67], v[120:123], v[156:159]
	v_mfma_f32_16x16x32_bf16 v[156:159], v[68:71], v[128:131], v[136:139]
	v_mfma_f32_16x16x32_bf16 v[136:139], v[72:75], v[120:123], v[144:147]
	v_mfma_f32_16x16x32_bf16 v[144:147], v[76:79], v[128:131], v[136:139]
	v_mfma_f32_16x16x32_bf16 v[136:139], v[64:67], v[180:183], v[140:143]
	v_mfma_f32_16x16x32_bf16 v[132:135], v[72:75], v[180:183], v[132:135]
	v_mfma_f32_16x16x32_bf16 v[124:127], v[64:67], v[188:191], v[124:127]
	v_mfma_f32_16x16x32_bf16 v[116:119], v[72:75], v[188:191], v[116:119]
	v_mfma_f32_16x16x32_bf16 v[112:115], v[64:67], v[206:209], v[112:115]
	v_mfma_f32_16x16x32_bf16 v[108:111], v[72:75], v[206:209], v[108:111]
	v_mfma_f32_16x16x32_bf16 v[140:143], v[68:71], v[184:187], v[136:139]
	v_mfma_f32_16x16x32_bf16 v[132:135], v[76:79], v[184:187], v[132:135]
	v_mfma_f32_16x16x32_bf16 v[124:127], v[68:71], v[192:195], v[124:127]
	v_mfma_f32_16x16x32_bf16 v[116:119], v[76:79], v[192:195], v[116:119]
	v_mfma_f32_16x16x32_bf16 v[112:115], v[68:71], v[212:215], v[112:115]
	v_mfma_f32_16x16x32_bf16 v[108:111], v[76:79], v[212:215], v[108:111]
	s_barrier
	s_setprio 0
	s_add_i32 s50, 0, 0x1c000
	v_add_u32_e32 v136, s50, v198
	s_add_i32 s51, s59, s62
	ds_read_b128 v[216:219], v136
	ds_read_b128 v[220:223], v136 offset:1024
	ds_read_b128 v[224:227], v136 offset:2048
	ds_read_b128 v[228:231], v136 offset:3072
	v_lshl_add_u64 v[136:137], v[196:197], 0, s[28:29]
	s_mov_b32 m0, s51
	s_nop 0
	global_load_lds_dwordx4 v[136:137], off
	v_lshl_add_u64 v[136:137], v[232:233], 0, s[28:29]
	s_add_i32 m0, s51, 0x2000
	s_nop 0
	global_load_lds_dwordx4 v[136:137], off
	s_waitcnt lgkmcnt(0)
	s_setprio 1
	s_barrier
	v_mfma_f32_16x16x32_bf16 v[80:83], v[224:227], v[120:123], v[80:83]
	v_mfma_f32_16x16x32_bf16 v[136:139], v[216:219], v[120:123], v[152:155]
	v_mfma_f32_16x16x32_bf16 v[148:151], v[228:231], v[128:131], v[80:83]
	v_mfma_f32_16x16x32_bf16 v[80:83], v[216:219], v[180:183], v[84:87]
	v_mfma_f32_16x16x32_bf16 v[152:155], v[220:223], v[128:131], v[136:139]
	v_mfma_f32_16x16x32_bf16 v[136:139], v[220:223], v[184:187], v[80:83]
	v_mfma_f32_16x16x32_bf16 v[80:83], v[224:227], v[180:183], v[88:91]
	v_mfma_f32_16x16x32_bf16 v[128:131], v[228:231], v[184:187], v[80:83]
	v_mfma_f32_16x16x32_bf16 v[80:83], v[216:219], v[188:191], v[92:95]
	v_mfma_f32_16x16x32_bf16 v[120:123], v[220:223], v[192:195], v[80:83]
	v_mfma_f32_16x16x32_bf16 v[80:83], v[224:227], v[188:191], v[104:107]
	v_mfma_f32_16x16x32_bf16 v[104:107], v[228:231], v[192:195], v[80:83]
	v_mfma_f32_16x16x32_bf16 v[80:83], v[216:219], v[206:209], v[100:103]
	v_mfma_f32_16x16x32_bf16 v[100:103], v[220:223], v[212:215], v[80:83]
	v_mfma_f32_16x16x32_bf16 v[80:83], v[224:227], v[206:209], v[96:99]
	v_mfma_f32_16x16x32_bf16 v[96:99], v[228:231], v[212:215], v[80:83]
	s_barrier
	s_setprio 0
	s_mov_b32 m0, s55
	v_lshl_add_u64 v[196:197], v[234:235], 0, s[28:29]
	s_nop 2
	ds_read_b128 v[80:83], v202 offset:49152
	ds_read_b128 v[84:87], v202 offset:50176
	ds_read_b128 v[88:91], v202 offset:51200
	ds_read_b128 v[92:95], v202 offset:52224
	ds_read_b128 v[180:183], v202 offset:53248
	ds_read_b128 v[184:187], v202 offset:54272
	ds_read_b128 v[188:191], v202 offset:55296
	ds_read_b128 v[192:195], v202 offset:56320
	global_load_lds_dwordx4 v[196:197], off
	v_lshl_add_u64 v[196:197], v[236:237], 0, s[28:29]
	s_mov_b32 m0, s68
	s_nop 0
	global_load_lds_dwordx4 v[196:197], off
	s_waitcnt vmcnt(10)
	s_waitcnt lgkmcnt(0)
	s_setprio 1
	s_barrier
; #define PG8_STAGE(bufoff, gbase, voff) do { _Pragma("unroll") for (int _i = 0; _i < 2; ++_i) \
;     __builtin_amdgcn_global_load_lds((const unsigned*)((const char*)(gbase) + (voff)[_i]), (LAS unsigned*)(lds + (bufoff) + ldsw + _i * 8192), 16, 0, 0); } while (0)
; #define PG8_MMA(ai, bj, At, Bt) do { __builtin_amdgcn_s_setprio(1); _Pragma("unroll") for (int m = 0; m < 4; ++m) _Pragma("unroll") for (int n = 0; n < 2; ++n) _Pragma("unroll") for (int k = 0; k < 2; ++k) \
;     acc[ai][bj][m][n] = __builtin_amdgcn_mfma_f32_16x16x32_bf16(Bt[n][k], At[m][k], acc[ai][bj][m][n], 0, 0, 0); __builtin_amdgcn_s_setprio(0); } while (0)
; #define PG8_WAIT_V(n) asm volatile("s_waitcnt vmcnt(" #n ")" ::: "memory")
; #define PG8_WAIT_L(n) asm volatile("s_waitcnt lgkmcnt(" #n ")" ::: "memory")
; #define PG8_BAR __builtin_amdgcn_s_barrier()
; #define PG8_SCHED __builtin_amdgcn_sched_barrier(0)
;   DI void operator()(const f32x4 (&acc)[2][2][4][2], const Unit& u, int wr, int wc, int fr, int fq) const {
;     const int col = u.pn * 128 + wc * 32 + 8 * fq;
;     float w0[8], w1[8], w2[8], bb[8];
; #pragma unroll
;     for (int e = 0; e < 8; ++e) { w0[e] = cw[col + e]; w1[e] = cw[5632 + col + e]; w2[e] = cw[2 * 5632 + col + e]; bb[e] = cb[col + e]; }
; #pragma unroll
;     for (int ai = 0; ai < 2; ++ai) {
;       const int row0 = u.pm * BM + ai * HALF + wr * 64, span = row0 >> 6;
;       float rsv[4];
; #pragma unroll
;       for (int m = 0; m < 4; ++m) rsv[m] = row_rstd(ssq, row0 + 16 * m + fr, fq);
; template <class Epi, class Sched = StaticOrder>
; DI void gemm_phase(LAS unsigned char* lds, const Gemm g, const Sched& S, const Epi& E) {
;     ...
;       PG8_BAR; PG8_WAIT_L(0); PG8_MMA(1, 0, At, B0); PG8_BAR; PG8_SCHED;
;       PG8_STAGE(PG8_SB(1, 1), b3 + hstep, voffB);
;       PG8_WAIT_V(6); PG8_BAR; PG8_MMA(1, 1, At, B1); PG8_BAR;
;     }
	v_mfma_f32_16x16x32_bf16 v[60:63], v[64:67], v[80:83], v[60:63]
	v_mfma_f32_16x16x32_bf16 v[48:51], v[72:75], v[80:83], v[48:51]
	v_mfma_f32_16x16x32_bf16 v[44:47], v[64:67], v[88:91], v[44:47]
	v_mfma_f32_16x16x32_bf16 v[36:39], v[72:75], v[88:91], v[36:39]
	v_mfma_f32_16x16x32_bf16 v[28:31], v[64:67], v[180:183], v[28:31]
	v_mfma_f32_16x16x32_bf16 v[20:23], v[72:75], v[180:183], v[20:23]
	v_mfma_f32_16x16x32_bf16 v[16:19], v[64:67], v[188:191], v[16:19]
	v_mfma_f32_16x16x32_bf16 v[12:15], v[72:75], v[188:191], v[12:15]
	v_mfma_f32_16x16x32_bf16 v[60:63], v[68:71], v[84:87], v[60:63]
	v_mfma_f32_16x16x32_bf16 v[48:51], v[76:79], v[84:87], v[48:51]
	v_mfma_f32_16x16x32_bf16 v[44:47], v[68:71], v[92:95], v[44:47]
	v_mfma_f32_16x16x32_bf16 v[36:39], v[76:79], v[92:95], v[36:39]
	v_mfma_f32_16x16x32_bf16 v[28:31], v[68:71], v[184:187], v[28:31]
	v_mfma_f32_16x16x32_bf16 v[20:23], v[76:79], v[184:187], v[20:23]
	v_mfma_f32_16x16x32_bf16 v[16:19], v[68:71], v[192:195], v[16:19]
	v_mfma_f32_16x16x32_bf16 v[12:15], v[76:79], v[192:195], v[12:15]
	s_barrier
	s_setprio 0
	s_add_u32 s48, s48, 0x80080
	s_addc_u32 s49, s49, 0
	s_add_i32 s50, s50, s62
	v_lshl_add_u64 v[64:65], s[48:49], 0, v[164:165]
	s_mov_b32 m0, s50
	s_nop 0
	global_load_lds_dwordx4 v[64:65], off
	v_lshl_add_u64 v[64:65], s[48:49], 0, v[160:161]
	s_add_i32 m0, s50, 0x2000
	s_nop 0
	global_load_lds_dwordx4 v[64:65], off
	ds_read_b128 v[64:67], v201
	ds_read_b128 v[68:71], v201 offset:1024
	ds_read_b128 v[72:75], v201 offset:2048
	ds_read_b128 v[76:79], v201 offset:3072
	s_waitcnt vmcnt(6)
	s_setprio 1
	s_barrier
	v_mfma_f32_16x16x32_bf16 v[56:59], v[216:219], v[80:83], v[56:59]
	v_mfma_f32_16x16x32_bf16 v[52:55], v[224:227], v[80:83], v[52:55]
	v_mfma_f32_16x16x32_bf16 v[40:43], v[216:219], v[88:91], v[40:43]
	v_mfma_f32_16x16x32_bf16 v[32:35], v[224:227], v[88:91], v[32:35]
	v_mfma_f32_16x16x32_bf16 v[24:27], v[216:219], v[180:183], v[24:27]
	v_mfma_f32_16x16x32_bf16 v[8:11], v[224:227], v[180:183], v[8:11]
	v_mfma_f32_16x16x32_bf16 v[4:7], v[216:219], v[188:191], v[4:7]
	v_mfma_f32_16x16x32_bf16 v[0:3], v[224:227], v[188:191], v[0:3]
	v_mfma_f32_16x16x32_bf16 v[56:59], v[220:223], v[84:87], v[56:59]
	v_mfma_f32_16x16x32_bf16 v[52:55], v[228:231], v[84:87], v[52:55]
	v_mfma_f32_16x16x32_bf16 v[40:43], v[220:223], v[92:95], v[40:43]
	v_mfma_f32_16x16x32_bf16 v[32:35], v[228:231], v[92:95], v[32:35]
	v_mfma_f32_16x16x32_bf16 v[24:27], v[220:223], v[184:187], v[24:27]
	v_mfma_f32_16x16x32_bf16 v[8:11], v[228:231], v[184:187], v[8:11]
	v_mfma_f32_16x16x32_bf16 v[4:7], v[220:223], v[192:195], v[4:7]
	v_mfma_f32_16x16x32_bf16 v[0:3], v[228:231], v[192:195], v[0:3]
	s_add_i32 s58, s58, 2
	s_add_u32 s14, s14, 0x100
	s_addc_u32 s15, s15, 0
	s_add_u32 s52, s52, 0x100
	s_addc_u32 s53, s53, 0
	s_cmp_gt_u32 s58, 29
	s_barrier
	s_setprio 0
	s_cbranch_scc0 .LBB0_1277
	s_waitcnt lgkmcnt(0)
	s_lshl_b32 s39, s12, 8
	s_add_i32 s39, s39, s54
	v_or_b32_e32 v190, s39, v179
	v_ashrrev_i32_e32 v191, 31, v190
	v_lshlrev_b64 v[64:65], 7, v[190:191]
	v_or_b32_e32 v188, 16, v190
	v_lshl_add_u64 v[64:65], v[168:169], 0, v[64:65]
	v_ashrrev_i32_e32 v189, 31, v188
	global_load_dwordx4 v[192:195], v[64:65], off
	global_load_dwordx4 v[206:209], v[64:65], off offset:16
	v_lshlrev_b64 v[64:65], 7, v[188:189]
	v_lshl_add_u64 v[64:65], v[168:169], 0, v[64:65]
	global_load_dwordx4 v[212:215], v[64:65], off
	global_load_dwordx4 v[216:219], v[64:65], off offset:16
	v_or_b32_e32 v186, 32, v190
	v_ashrrev_i32_e32 v187, 31, v186
	v_lshlrev_b64 v[64:65], 7, v[186:187]
	v_or_b32_e32 v184, 48, v190
	v_lshl_add_u64 v[64:65], v[168:169], 0, v[64:65]
	v_ashrrev_i32_e32 v185, 31, v184
	global_load_dwordx4 v[220:223], v[64:65], off
	global_load_dwordx4 v[224:227], v[64:65], off offset:16
	v_lshlrev_b64 v[64:65], 7, v[184:185]
	v_lshl_add_u64 v[64:65], v[168:169], 0, v[64:65]
	global_load_dwordx4 v[228:231], v[64:65], off
	global_load_dwordx4 v[232:235], v[64:65], off offset:16
	v_lshl_or_b32 v180, s13, 7, v200
	v_and_b32_e32 v65, 64, v204
	v_xor_b32_e32 v64, 16, v204
	v_ashrrev_i32_e32 v181, 31, v180
	v_add_u32_e32 v65, 64, v65
	v_xor_b32_e32 v66, 32, v204
	v_lshlrev_b64 v[182:183], 2, v[180:181]
	v_cmp_lt_i32_e32 vcc, v64, v65
	v_lshl_add_u64 v[88:89], s[16:17], 0, v[182:183]
	v_lshl_add_u64 v[72:73], s[18:19], 0, v[182:183]
	v_cndmask_b32_e32 v64, v204, v64, vcc
	v_cmp_lt_i32_e32 vcc, v66, v65
	v_lshl_add_u64 v[74:75], v[88:89], 0, s[30:31]
	v_lshl_add_u64 v[76:77], v[88:89], 0, s[34:35]
	v_cndmask_b32_e32 v65, v204, v66, vcc
	v_add_co_u32_e32 v90, vcc, 0x5000, v88
	v_lshlrev_b32_e32 v187, 2, v64
	s_nop 0
	v_addc_co_u32_e32 v91, vcc, 0, v89, vcc
	v_add_co_u32_e32 v92, vcc, 0xb000, v88
	v_lshlrev_b32_e32 v185, 2, v65
	s_nop 0
	v_addc_co_u32_e32 v93, vcc, 0, v89, vcc
	global_load_dwordx4 v[64:67], v[88:89], off offset:16
	global_load_dwordx4 v[80:83], v[88:89], off
	global_load_dwordx4 v[68:71], v[72:73], off offset:16
	global_load_dwordx4 v[84:87], v[72:73], off
	s_nop 0
	global_load_dwordx4 v[72:75], v[74:75], off offset:16
	s_nop 0
	global_load_dwordx4 v[76:79], v[76:77], off offset:16
	s_nop 0
	global_load_dwordx4 v[88:91], v[90:91], off offset:2048
	s_nop 0
	global_load_dwordx4 v[92:95], v[92:93], off
	v_mov_b32_e32 v211, 0
	v_mov_b32_e32 v205, 0
	s_waitcnt vmcnt(0)
; DI float dpp_ror1(float v) { return __int_as_float(__builtin_amdgcn_update_dpp(0, __float_as_int(v), 0x121, 0xf, 0xf, false)); }
; DI float dpp_ror2(float v) { return __int_as_float(__builtin_amdgcn_update_dpp(0, __float_as_int(v), 0x122, 0xf, 0xf, false)); }
;   DI void operator()(const f32x4 (&acc)[2][2][4][2], const Unit& u, int wr, int wc, int fr, int fq) const {
;     const int col = u.pn * 128 + wc * 32 + 8 * fq;
;     float w0[8], w1[8], w2[8], bb[8];
; #pragma unroll
;     for (int e = 0; e < 8; ++e) { w0[e] = cw[col + e]; w1[e] = cw[5632 + col + e]; w2[e] = cw[2 * 5632 + col + e]; bb[e] = cb[col + e]; }
; #pragma unroll
;     for (int ai = 0; ai < 2; ++ai) {
;       const int row0 = u.pm * BM + ai * HALF + wr * 64, span = row0 >> 6;
;       float rsv[4];
; #pragma unroll
;       for (int m = 0; m < 4; ++m) rsv[m] = row_rstd(ssq, row0 + 16 * m + fr, fq);
;       float p1[8], p2[8];
; #pragma unroll
;       for (int e = 0; e < 8; ++e) { p1[e] = 0.f; p2[e] = 0.f; }
; #pragma unroll
;       for (int m = 0; m < 4; ++m) {
;         float g[8], uu[8], a[8];
;         const float rs = rsv[m];
; #pragma unroll
;         for (int e = 0; e < 4; ++e) { g[e] = acc[ai][0][m][0][e] * rs; g[4 + e] = acc[ai][0][m][1][e] * rs; uu[e] = acc[ai][1][m][0][e] * rs; uu[4 + e] = acc[ai][1][m][1][e] * rs; }
; #pragma unroll
;         for (int e = 0; e < 8; ++e) {
;           const float x1 = dpp_ror1(g[e]), x2 = dpp_ror2(g[e]);
;           const float pr1 = (fr == 0) ? p1[e] : x1, pr2 = (fr < 2) ? p2[e] : x2;
;           a[e] = w2[e] * g[e] + w1[e] * pr1 + w0[e] * pr2 + bb[e];
;           p1[e] = x1; p2[e] = x2;
;         }
	v_mov_b32_e32 v196, v192
	v_mov_b32_e32 v197, v206
	v_mov_b32_e32 v206, v193
	v_mov_b32_e32 v192, v194
	v_mov_b32_e32 v193, v208
	v_mov_b32_e32 v208, v195
	v_pk_add_f32 v[194:195], v[196:197], v[206:207]
	v_pk_add_f32 v[192:193], v[192:193], v[208:209]
	v_mov_b32_e32 v196, v212
	v_mov_b32_e32 v197, v216
	v_mov_b32_e32 v216, v213
	v_mov_b32_e32 v206, v214
	v_mov_b32_e32 v207, v218
	v_mov_b32_e32 v218, v215
	v_pk_add_f32 v[192:193], v[194:195], v[192:193]
	v_pk_add_f32 v[194:195], v[196:197], v[216:217]
	v_pk_add_f32 v[196:197], v[206:207], v[218:219]
	v_mov_b32_e32 v208, v220
	v_pk_add_f32 v[194:195], v[194:195], v[196:197]
	v_mov_b32_e32 v197, v192
	v_mov_b32_e32 v196, v194
	v_mov_b32_e32 v192, v195
	v_pk_add_f32 v[192:193], v[196:197], v[192:193]
	ds_bpermute_b32 v195, v187, v193
	ds_bpermute_b32 v194, v187, v192
	v_mov_b32_e32 v209, v224
	v_mov_b32_e32 v224, v221
	v_mov_b32_e32 v212, v222
	v_mov_b32_e32 v213, v226
	s_waitcnt lgkmcnt(0)
	v_pk_add_f32 v[192:193], v[192:193], v[194:195]
	ds_bpermute_b32 v195, v185, v193
	ds_bpermute_b32 v194, v185, v192
	v_mov_b32_e32 v226, v223
	v_mov_b32_e32 v196, v228
	v_mov_b32_e32 v197, v232
	v_mov_b32_e32 v232, v229
	s_waitcnt lgkmcnt(0)
	v_pk_add_f32 v[192:193], v[192:193], v[194:195]
	v_mov_b32_e32 v206, v230
	v_pk_fma_f32 v[192:193], v[192:193], s[36:37], v[178:179] op_sel_hi:[1,0,0]
	v_mov_b32_e32 v207, v234
	v_mul_f32_e32 v189, 0x4b800000, v193
	v_cmp_gt_f32_e64 s[12:13], s74, v193
	v_mov_b32_e32 v234, v231
	v_pk_add_f32 v[208:209], v[208:209], v[224:225]
	v_cndmask_b32_e64 v189, v193, v189, s[12:13]
	v_rsq_f32_e32 v189, v189
	v_pk_add_f32 v[212:213], v[212:213], v[226:227]
	v_pk_add_f32 v[196:197], v[196:197], v[232:233]
	v_pk_add_f32 v[194:195], v[206:207], v[234:235]
	v_mul_f32_e32 v191, 0x45800000, v189
	v_cndmask_b32_e64 v220, v189, v191, s[12:13]
	v_pk_add_f32 v[208:209], v[208:209], v[212:213]
	v_pk_add_f32 v[194:195], v[196:197], v[194:195]
	v_pk_mul_f32 v[156:157], v[156:157], v[220:221] op_sel_hi:[1,0]
	v_mov_b32_e32 v216, 0
	v_mov_b32_e32 v218, 0
	v_mov_b32_e32 v196, v194
	v_mov_b32_e32 v197, v208
	v_mov_b32_e32 v208, v195
	v_mov_b32_dpp v216, v156 row_ror:1 row_mask:0xf bank_mask:0xf
	v_mov_b32_dpp v218, v157 row_ror:1 row_mask:0xf bank_mask:0xf
	v_pk_add_f32 v[194:195], v[196:197], v[208:209]
	v_cndmask_b32_e64 v207, v218, 0, s[0:1]
	v_cndmask_b32_e64 v206, v216, 0, s[0:1]
	v_pk_mul_f32 v[158:159], v[158:159], v[220:221] op_sel_hi:[1,0]
	v_mov_b32_e32 v212, 0
	v_mov_b32_e32 v214, 0
	ds_bpermute_b32 v197, v187, v195
	ds_bpermute_b32 v196, v187, v194
	v_mov_b32_e32 v215, 0
	v_mov_b32_e32 v217, 0
	v_pk_mul_f32 v[206:207], v[88:89], v[206:207]
	v_mov_b32_dpp v212, v158 row_ror:1 row_mask:0xf bank_mask:0xf
	v_mov_b32_dpp v214, v159 row_ror:1 row_mask:0xf bank_mask:0xf
	v_mov_b32_dpp v215, v156 row_ror:2 row_mask:0xf bank_mask:0xf
	v_mov_b32_dpp v217, v157 row_ror:2 row_mask:0xf bank_mask:0xf
	v_pk_fma_f32 v[156:157], v[92:93], v[156:157], v[206:207]
	v_mov_b32_e32 v213, 0
	v_cndmask_b32_e64 v207, v214, 0, s[0:1]
	v_cndmask_b32_e64 v206, v212, 0, s[0:1]
	v_cndmask_b32_e64 v209, v217, 0, s[4:5]
	v_cndmask_b32_e64 v208, v215, 0, s[4:5]
	v_mov_b32_dpp v211, v158 row_ror:2 row_mask:0xf bank_mask:0xf
	v_mov_b32_dpp v213, v159 row_ror:2 row_mask:0xf bank_mask:0xf
	v_pk_mul_f32 v[206:207], v[90:91], v[206:207]
	v_pk_fma_f32 v[156:157], v[80:81], v[208:209], v[156:157]
	v_cndmask_b32_e64 v209, v213, 0, s[4:5]
	v_cndmask_b32_e64 v208, v211, 0, s[4:5]
	v_pk_fma_f32 v[158:159], v[94:95], v[158:159], v[206:207]
	v_pk_mul_f32 v[144:145], v[144:145], v[220:221] op_sel_hi:[1,0]
	v_pk_fma_f32 v[158:159], v[82:83], v[208:209], v[158:159]
	v_mov_b32_e32 v207, 0
	v_mov_b32_e32 v209, 0
	v_pk_mul_f32 v[146:147], v[146:147], v[220:221] op_sel_hi:[1,0]
	v_mov_b32_e32 v191, 0
	s_waitcnt lgkmcnt(0)
	v_pk_add_f32 v[194:195], v[194:195], v[196:197]
	v_mov_b32_dpp v207, v144 row_ror:1 row_mask:0xf bank_mask:0xf
	v_mov_b32_dpp v209, v145 row_ror:1 row_mask:0xf bank_mask:0xf
	v_mov_b32_dpp v191, v146 row_ror:1 row_mask:0xf bank_mask:0xf
	v_mov_b32_dpp v205, v147 row_ror:1 row_mask:0xf bank_mask:0xf
	ds_bpermute_b32 v197, v185, v195
	ds_bpermute_b32 v196, v185, v194
	v_pk_mul_f32 v[152:153], v[152:153], v[220:221] op_sel_hi:[1,0]
	v_pk_mul_f32 v[148:149], v[148:149], v[220:221] op_sel_hi:[1,0]
	v_pk_mul_f32 v[154:155], v[154:155], v[220:221] op_sel_hi:[1,0]
	v_pk_mul_f32 v[150:151], v[150:151], v[220:221] op_sel_hi:[1,0]
	v_mov_b32_e32 v206, 0
	v_mov_b32_e32 v208, 0
	v_cndmask_b32_e64 v223, v209, 0, s[0:1]
	v_cndmask_b32_e64 v222, v207, 0, s[0:1]
	v_mov_b32_e32 v189, 0
	v_mov_b32_e32 v193, 0
	v_cndmask_b32_e64 v221, v205, 0, s[0:1]
	v_cndmask_b32_e64 v220, v191, 0, s[0:1]
	v_mov_b32_dpp v206, v144 row_ror:2 row_mask:0xf bank_mask:0xf
	v_mov_b32_dpp v208, v145 row_ror:2 row_mask:0xf bank_mask:0xf
	v_pk_mul_f32 v[222:223], v[72:73], v[222:223]
	v_mov_b32_dpp v189, v146 row_ror:2 row_mask:0xf bank_mask:0xf
	v_mov_b32_dpp v193, v147 row_ror:2 row_mask:0xf bank_mask:0xf
	v_pk_mul_f32 v[220:221], v[74:75], v[220:221]
	v_cndmask_b32_e64 v225, v208, 0, s[4:5]
	v_cndmask_b32_e64 v224, v206, 0, s[4:5]
	v_pk_fma_f32 v[144:145], v[76:77], v[144:145], v[222:223]
	v_cndmask_b32_e64 v223, v193, 0, s[4:5]
	v_cndmask_b32_e64 v222, v189, 0, s[4:5]
	v_pk_fma_f32 v[146:147], v[78:79], v[146:147], v[220:221]
	v_pk_fma_f32 v[144:145], v[64:65], v[224:225], v[144:145]
	v_pk_fma_f32 v[146:147], v[66:67], v[222:223], v[146:147]
	v_cmp_gt_f32_e32 vcc, s74, v192
	v_pk_add_f32 v[156:157], v[84:85], v[156:157]
	v_pk_add_f32 v[158:159], v[86:87], v[158:159]
	v_pk_add_f32 v[144:145], v[68:69], v[144:145]
	v_pk_add_f32 v[146:147], v[70:71], v[146:147]
	s_and_saveexec_b64 s[12:13], s[10:11]
	s_xor_b64 s[12:13], exec, s[12:13]
	s_cbranch_execz .LBB0_1280
; DI unsigned pack2(float lo, float hi) { f32x2 v = {lo, hi}; bf16v2 r = __builtin_convertvector(v, bf16v2); return __builtin_bit_cast(unsigned, r); }
; DI float silu_f(float x) { return x * sigmoid_f(x); }
;   DI void operator()(const f32x4 (&acc)[2][2][4][2], const Unit& u, int wr, int wc, int fr, int fq) const {
;     ...
;         } else {
;           u32x4 w;
;           w.x = pack2(silu_f(a[0]) * uu[0], silu_f(a[1]) * uu[1]);
;           w.y = pack2(silu_f(a[2]) * uu[2], silu_f(a[3]) * uu[3]);
;           w.z = pack2(silu_f(a[4]) * uu[4], silu_f(a[5]) * uu[5]);
;           w.w = pack2(silu_f(a[6]) * uu[6], silu_f(a[7]) * uu[7]);
;           *(u32x4*)(H + (size_t)(row0 + 16 * m + fr) * 5632 + col) = w;
;         }
	v_mul_f32_e32 v219, 0xbfb8aa3b, v156
	v_exp_f32_e32 v219, v219
	v_mul_f32_e32 v220, 0xbfb8aa3b, v157
	v_exp_f32_e32 v220, v220
	v_mul_f32_e32 v222, 0xbfb8aa3b, v159
	v_add_f32_e32 v219, 1.0, v219
	v_exp_f32_e32 v223, v222
	v_add_f32_e32 v221, 1.0, v220
	v_rcp_f32_e32 v220, v219
	v_mul_f32_e32 v219, 0xbfb8aa3b, v158
	v_exp_f32_e32 v219, v219
	v_rcp_f32_e32 v221, v221
	v_add_f32_e32 v219, 1.0, v219
	v_rcp_f32_e32 v222, v219
	v_add_f32_e32 v219, 1.0, v223
	v_rcp_f32_e32 v223, v219
	v_pk_mul_f32 v[156:157], v[156:157], v[220:221]
	s_nop 0
	v_pk_mul_f32 v[152:153], v[152:153], v[156:157]
	v_pk_mul_f32 v[156:157], v[158:159], v[222:223]
	v_cvt_pk_bf16_f32 v152, v152, v153
	v_mul_f32_e32 v153, 0xbfb8aa3b, v144
	v_pk_mul_f32 v[154:155], v[154:155], v[156:157]
	v_exp_f32_e32 v156, v153
	v_mul_f32_e32 v153, 0xbfb8aa3b, v145
	v_exp_f32_e32 v157, v153
	v_cvt_pk_bf16_f32 v153, v154, v155
	v_add_f32_e32 v154, 1.0, v156
	v_mul_f32_e32 v156, 0xbfb8aa3b, v146
	v_add_f32_e32 v155, 1.0, v157
	v_mul_f32_e32 v157, 0xbfb8aa3b, v147
	v_exp_f32_e32 v156, v156
	v_exp_f32_e32 v157, v157
	v_rcp_f32_e32 v154, v154
	v_rcp_f32_e32 v155, v155
	v_add_f32_e32 v156, 1.0, v156
	v_add_f32_e32 v157, 1.0, v157
	v_rcp_f32_e32 v156, v156
	v_rcp_f32_e32 v157, v157
	v_pk_mul_f32 v[144:145], v[144:145], v[154:155]
	s_nop 0
	v_pk_mul_f32 v[144:145], v[148:149], v[144:145]
	s_nop 0
	v_cvt_pk_bf16_f32 v154, v144, v145
	v_pk_mul_f32 v[144:145], v[146:147], v[156:157]
	s_nop 0
	v_pk_mul_f32 v[144:145], v[150:151], v[144:145]
	s_nop 0
	v_cvt_pk_bf16_f32 v155, v144, v145
	v_mov_b64_e32 v[144:145], s[20:21]
	v_mad_i64_i32 v[144:145], s[14:15], v190, s75, v[144:145]
	v_lshl_add_u64 v[144:145], v[180:181], 1, v[144:145]
	global_store_dwordx4 v[144:145], v[152:155], off

; #define PG8_STAGE(bufoff, gbase, voff) do { _Pragma("unroll") for (int _i = 0; _i < 2; ++_i) \
;     __builtin_amdgcn_global_load_lds((const unsigned*)((const char*)(gbase) + (voff)[_i]), (LAS unsigned*)(lds + (bufoff) + ldsw + _i * 8192), 16, 0, 0); } while (0)
; #define PG8_LDA(dst, b, h) do { _Pragma("unroll") for (int m = 0; m < 4; ++m) _Pragma("unroll") for (int k = 0; k < 2; ++k) dst[m][k] = *(const LAS bf16x8*)(lds + PG8_SA(b, h) + aoff + m * 2048 + k * 1024); } while (0)
; #define PG8_LDB(dst, b, h) do { _Pragma("unroll") for (int n = 0; n < 2; ++n) _Pragma("unroll") for (int k = 0; k < 2; ++k) dst[n][k] = *(const LAS bf16x8*)(lds + PG8_SB(b, h) + boff + n * 2048 + k * 1024); } while (0)
; #define PG8_MMA(ai, bj, At, Bt) do { __builtin_amdgcn_s_setprio(1); _Pragma("unroll") for (int m = 0; m < 4; ++m) _Pragma("unroll") for (int n = 0; n < 2; ++n) _Pragma("unroll") for (int k = 0; k < 2; ++k) \
;     acc[ai][bj][m][n] = __builtin_amdgcn_mfma_f32_16x16x32_bf16(Bt[n][k], At[m][k], acc[ai][bj][m][n], 0, 0, 0); __builtin_amdgcn_s_setprio(0); } while (0)
; #define PG8_WAIT_L(n) asm volatile("s_waitcnt lgkmcnt(" #n ")" ::: "memory")
; #define PG8_BAR __builtin_amdgcn_s_barrier()
; #define PG8_SCHED __builtin_amdgcn_sched_barrier(0)
; template <class Epi, class Sched = StaticOrder>
; DI void gemm_phase(LAS unsigned char* lds, const Gemm g, const Sched& S, const Epi& E) {
;     ...
;     for (int t = 0; t < nt; t += 2) {
;       const bool last = (t == nt - 2);
;       const char* a1 = cA + (size_t)(t + 1) * kstep;
;       const char* a2 = last ? nA : cA + (size_t)(t + 2) * kstep; const char* b2 = last ? nB : cB + (size_t)(t + 2) * kstep;
;       const char* a3 = a2 + kstep; const char* b3 = b2 + kstep;
;       PG8_LDB(B0, 0, 0); PG8_SCHED; PG8_LDA(At, 0, 0); PG8_STAGE(PG8_SA(1, 1), a1 + hstep, voffA);
;       PG8_WAIT_L(8); PG8_BAR; PG8_WAIT_L(0); PG8_MMA(0, 0, At, B0); PG8_BAR; PG8_SCHED;
;       PG8_LDB(B1, 0, 1); PG8_STAGE(PG8_SB(0, 0), b2, voffB);
;       PG8_BAR; PG8_WAIT_L(0); PG8_MMA(0, 1, At, B1); PG8_BAR;
;       PG8_LDA(At, 0, 1); PG8_STAGE(PG8_SA(0, 0), a2, voffA);
;       PG8_BAR; PG8_WAIT_L(0); PG8_MMA(1, 0, At, B0); PG8_BAR; PG8_SCHED;
.LBB0_1424:
	s_add_u32 s18, s16, 0xffea0080
	s_addc_u32 s19, s17, -1
	s_cmpk_eq_i32 s47, 0x54
	s_cselect_b32 s21, s3, s19
	s_cselect_b32 s20, s2, s18
	s_cselect_b32 s19, s5, s46
	s_cselect_b32 s18, s4, s45
	v_lshl_add_u64 v[198:199], s[16:17], 0, v[136:137]
	s_add_i32 m0, s30, 0xc000
	ds_read_b128 v[166:169], v160
	ds_read_b128 v[170:173], v160 offset:1024
	ds_read_b128 v[174:177], v160 offset:2048
	ds_read_b128 v[178:181], v160 offset:3072
	ds_read_b128 v[182:185], v160 offset:4096
	ds_read_b128 v[186:189], v160 offset:5120
	ds_read_b128 v[190:193], v160 offset:6144
	ds_read_b128 v[194:197], v160 offset:7168
	global_load_lds_dwordx4 v[198:199], off
	v_lshl_add_u64 v[198:199], s[16:17], 0, v[138:139]
	s_add_i32 m0, s30, 0xe000
	s_nop 0
	global_load_lds_dwordx4 v[198:199], off
	s_waitcnt lgkmcnt(0)
	s_setprio 1
	s_barrier
	v_mfma_f32_16x16x32_bf16 v[124:127], v[144:147], v[166:169], v[124:127]
	v_mfma_f32_16x16x32_bf16 v[120:123], v[152:155], v[166:169], v[120:123]
	v_mfma_f32_16x16x32_bf16 v[116:119], v[144:147], v[174:177], v[116:119]
	v_mfma_f32_16x16x32_bf16 v[112:115], v[152:155], v[174:177], v[112:115]
	v_mfma_f32_16x16x32_bf16 v[104:107], v[144:147], v[182:185], v[104:107]
	v_mfma_f32_16x16x32_bf16 v[96:99], v[152:155], v[182:185], v[96:99]
	v_mfma_f32_16x16x32_bf16 v[88:91], v[144:147], v[190:193], v[88:91]
	v_mfma_f32_16x16x32_bf16 v[80:83], v[152:155], v[190:193], v[80:83]
	v_mfma_f32_16x16x32_bf16 v[124:127], v[148:151], v[170:173], v[124:127]
	v_mfma_f32_16x16x32_bf16 v[120:123], v[162:165], v[170:173], v[120:123]
	v_mfma_f32_16x16x32_bf16 v[116:119], v[148:151], v[178:181], v[116:119]
	v_mfma_f32_16x16x32_bf16 v[112:115], v[162:165], v[178:181], v[112:115]
	v_mfma_f32_16x16x32_bf16 v[104:107], v[148:151], v[186:189], v[104:107]
	v_mfma_f32_16x16x32_bf16 v[96:99], v[162:165], v[186:189], v[96:99]
	v_mfma_f32_16x16x32_bf16 v[88:91], v[148:151], v[194:197], v[88:91]
	v_mfma_f32_16x16x32_bf16 v[80:83], v[162:165], v[194:197], v[80:83]
	s_barrier
	s_setprio 0
	s_add_i32 s48, s39, s28
	v_lshl_add_u64 v[214:215], s[18:19], 0, v[132:133]
	s_mov_b32 m0, s48
	ds_read_b128 v[198:201], v161
	ds_read_b128 v[202:205], v161 offset:1024
	ds_read_b128 v[206:209], v161 offset:2048
	ds_read_b128 v[210:213], v161 offset:3072
	global_load_lds_dwordx4 v[214:215], off
	v_lshl_add_u64 v[216:217], s[18:19], 0, v[128:129]
	s_add_i32 m0, s48, 0x2000
	s_nop 0
	global_load_lds_dwordx4 v[216:217], off
	s_waitcnt lgkmcnt(0)
	s_setprio 1
	s_barrier
	v_mfma_f32_16x16x32_bf16 v[108:111], v[198:201], v[166:169], v[108:111]
	v_mfma_f32_16x16x32_bf16 v[100:103], v[206:209], v[166:169], v[100:103]
	v_mfma_f32_16x16x32_bf16 v[92:95], v[198:201], v[174:177], v[92:95]
	v_mfma_f32_16x16x32_bf16 v[84:87], v[206:209], v[174:177], v[84:87]
	v_mfma_f32_16x16x32_bf16 v[76:79], v[198:201], v[182:185], v[76:79]
	v_mfma_f32_16x16x32_bf16 v[72:75], v[206:209], v[182:185], v[72:75]
	v_mfma_f32_16x16x32_bf16 v[68:71], v[198:201], v[190:193], v[68:71]
	v_mfma_f32_16x16x32_bf16 v[64:67], v[206:209], v[190:193], v[64:67]
	v_mfma_f32_16x16x32_bf16 v[108:111], v[202:205], v[170:173], v[108:111]
	v_mfma_f32_16x16x32_bf16 v[100:103], v[210:213], v[170:173], v[100:103]
	v_mfma_f32_16x16x32_bf16 v[92:95], v[202:205], v[178:181], v[92:95]
	v_mfma_f32_16x16x32_bf16 v[84:87], v[210:213], v[178:181], v[84:87]
	v_mfma_f32_16x16x32_bf16 v[76:79], v[202:205], v[186:189], v[76:79]
	v_mfma_f32_16x16x32_bf16 v[72:75], v[210:213], v[186:189], v[72:75]
	v_mfma_f32_16x16x32_bf16 v[68:71], v[202:205], v[194:197], v[68:71]
	v_mfma_f32_16x16x32_bf16 v[64:67], v[210:213], v[194:197], v[64:67]
	s_barrier
	s_setprio 0
	s_mov_b32 m0, s30
	v_lshl_add_u64 v[218:219], s[20:21], 0, v[134:135]
	ds_read_b128 v[166:169], v160 offset:16384
	ds_read_b128 v[170:173], v160 offset:17408
	ds_read_b128 v[174:177], v160 offset:18432
	ds_read_b128 v[178:181], v160 offset:19456
	ds_read_b128 v[182:185], v160 offset:20480
	ds_read_b128 v[186:189], v160 offset:21504
	ds_read_b128 v[190:193], v160 offset:22528
	ds_read_b128 v[194:197], v160 offset:23552
	global_load_lds_dwordx4 v[218:219], off
	v_lshl_add_u64 v[220:221], s[20:21], 0, v[130:131]
	s_mov_b32 m0, s31
	s_nop 0
	global_load_lds_dwordx4 v[220:221], off
	s_waitcnt vmcnt(10)
	s_waitcnt lgkmcnt(0)
	s_setprio 1
	s_barrier
	v_mfma_f32_16x16x32_bf16 v[60:63], v[144:147], v[166:169], v[60:63]
	v_mfma_f32_16x16x32_bf16 v[56:59], v[152:155], v[166:169], v[56:59]
	v_mfma_f32_16x16x32_bf16 v[52:55], v[144:147], v[174:177], v[52:55]
	v_mfma_f32_16x16x32_bf16 v[44:47], v[152:155], v[174:177], v[44:47]
	v_mfma_f32_16x16x32_bf16 v[36:39], v[144:147], v[182:185], v[36:39]
	v_mfma_f32_16x16x32_bf16 v[28:31], v[152:155], v[182:185], v[28:31]
	v_mfma_f32_16x16x32_bf16 v[20:23], v[144:147], v[190:193], v[20:23]
	v_mfma_f32_16x16x32_bf16 v[12:15], v[152:155], v[190:193], v[12:15]
	v_mfma_f32_16x16x32_bf16 v[60:63], v[148:151], v[170:173], v[60:63]
	v_mfma_f32_16x16x32_bf16 v[56:59], v[162:165], v[170:173], v[56:59]
	v_mfma_f32_16x16x32_bf16 v[52:55], v[148:151], v[178:181], v[52:55]
	v_mfma_f32_16x16x32_bf16 v[44:47], v[162:165], v[178:181], v[44:47]
	v_mfma_f32_16x16x32_bf16 v[36:39], v[148:151], v[186:189], v[36:39]
	v_mfma_f32_16x16x32_bf16 v[28:31], v[162:165], v[186:189], v[28:31]
	v_mfma_f32_16x16x32_bf16 v[20:23], v[148:151], v[194:197], v[20:23]
	v_mfma_f32_16x16x32_bf16 v[12:15], v[162:165], v[194:197], v[12:15]
	s_barrier
; #define PG8_STAGE(bufoff, gbase, voff) do { _Pragma("unroll") for (int _i = 0; _i < 2; ++_i) \
;     __builtin_amdgcn_global_load_lds((const unsigned*)((const char*)(gbase) + (voff)[_i]), (LAS unsigned*)(lds + (bufoff) + ldsw + _i * 8192), 16, 0, 0); } while (0)
; #define PG8_LDA(dst, b, h) do { _Pragma("unroll") for (int m = 0; m < 4; ++m) _Pragma("unroll") for (int k = 0; k < 2; ++k) dst[m][k] = *(const LAS bf16x8*)(lds + PG8_SA(b, h) + aoff + m * 2048 + k * 1024); } while (0)
; #define PG8_LDB(dst, b, h) do { _Pragma("unroll") for (int n = 0; n < 2; ++n) _Pragma("unroll") for (int k = 0; k < 2; ++k) dst[n][k] = *(const LAS bf16x8*)(lds + PG8_SB(b, h) + boff + n * 2048 + k * 1024); } while (0)
; #define PG8_MMA(ai, bj, At, Bt) do { __builtin_amdgcn_s_setprio(1); _Pragma("unroll") for (int m = 0; m < 4; ++m) _Pragma("unroll") for (int n = 0; n < 2; ++n) _Pragma("unroll") for (int k = 0; k < 2; ++k) \
;     acc[ai][bj][m][n] = __builtin_amdgcn_mfma_f32_16x16x32_bf16(Bt[n][k], At[m][k], acc[ai][bj][m][n], 0, 0, 0); __builtin_amdgcn_s_setprio(0); } while (0)
; #define PG8_WAIT_V(n) asm volatile("s_waitcnt vmcnt(" #n ")" ::: "memory")
; #define PG8_WAIT_L(n) asm volatile("s_waitcnt lgkmcnt(" #n ")" ::: "memory")
; #define PG8_BAR __builtin_amdgcn_s_barrier()
; #define PG8_SCHED __builtin_amdgcn_sched_barrier(0)
; template <class Epi, class Sched = StaticOrder>
; DI void gemm_phase(LAS unsigned char* lds, const Gemm g, const Sched& S, const Epi& E) {
;     ...
;       PG8_STAGE(PG8_SB(0, 1), b2 + hstep, voffB);
;       PG8_WAIT_V(6); PG8_BAR; PG8_MMA(1, 1, At, B1); PG8_BAR;
;       PG8_LDB(B0, 1, 0); PG8_SCHED; PG8_LDA(At, 1, 0); PG8_STAGE(PG8_SA(0, 1), a2 + hstep, voffA);
;       PG8_WAIT_L(8); PG8_BAR; PG8_WAIT_L(0); PG8_MMA(0, 0, At, B0); PG8_BAR; PG8_SCHED;
;       PG8_LDB(B1, 1, 1); PG8_STAGE(PG8_SB(1, 0), b3, voffB);
;       PG8_BAR; PG8_WAIT_L(0); PG8_MMA(0, 1, At, B1); PG8_BAR;
;       PG8_LDA(At, 1, 1); PG8_STAGE(PG8_SA(1, 0), a3, voffA);
;       PG8_BAR; PG8_WAIT_L(0); PG8_MMA(1, 0, At, B0); PG8_BAR; PG8_SCHED;
	s_setprio 0
	s_add_u32 s48, s18, 0x160000
	s_addc_u32 s49, s19, 0
	s_add_i32 s50, s40, s28
	v_lshl_add_u64 v[144:145], s[48:49], 0, v[132:133]
	s_mov_b32 m0, s50
	s_nop 0
	global_load_lds_dwordx4 v[144:145], off
	v_lshl_add_u64 v[144:145], s[48:49], 0, v[128:129]
	s_add_i32 m0, s50, 0x2000
	s_nop 0
	global_load_lds_dwordx4 v[144:145], off
	s_add_i32 s48, 0, 0x18000
	v_add_u32_e32 v162, s48, v157
	ds_read_b128 v[144:147], v162
	ds_read_b128 v[148:151], v162 offset:1024
	ds_read_b128 v[152:155], v162 offset:2048
	ds_read_b128 v[162:165], v162 offset:3072
	s_waitcnt vmcnt(6)
	s_setprio 1
	s_barrier
	v_mfma_f32_16x16x32_bf16 v[48:51], v[198:201], v[166:169], v[48:51]
	v_mfma_f32_16x16x32_bf16 v[40:43], v[206:209], v[166:169], v[40:43]
	v_mfma_f32_16x16x32_bf16 v[32:35], v[198:201], v[174:177], v[32:35]
	v_mfma_f32_16x16x32_bf16 v[24:27], v[206:209], v[174:177], v[24:27]
	v_mfma_f32_16x16x32_bf16 v[16:19], v[198:201], v[182:185], v[16:19]
	v_mfma_f32_16x16x32_bf16 v[8:11], v[206:209], v[182:185], v[8:11]
	v_mfma_f32_16x16x32_bf16 v[4:7], v[198:201], v[190:193], v[4:7]
	v_mfma_f32_16x16x32_bf16 v[0:3], v[206:209], v[190:193], v[0:3]
	v_mfma_f32_16x16x32_bf16 v[48:51], v[202:205], v[170:173], v[48:51]
	v_mfma_f32_16x16x32_bf16 v[40:43], v[210:213], v[170:173], v[40:43]
	v_mfma_f32_16x16x32_bf16 v[32:35], v[202:205], v[178:181], v[32:35]
	v_mfma_f32_16x16x32_bf16 v[24:27], v[210:213], v[178:181], v[24:27]
	v_mfma_f32_16x16x32_bf16 v[16:19], v[202:205], v[186:189], v[16:19]
	v_mfma_f32_16x16x32_bf16 v[8:11], v[210:213], v[186:189], v[8:11]
	v_mfma_f32_16x16x32_bf16 v[4:7], v[202:205], v[194:197], v[4:7]
	v_mfma_f32_16x16x32_bf16 v[0:3], v[210:213], v[194:197], v[0:3]
	s_barrier
	s_setprio 0
	s_add_u32 s20, s20, 0x160000
	s_addc_u32 s21, s21, 0
	s_mov_b32 m0, s33
	v_lshl_add_u64 v[198:199], s[20:21], 0, v[134:135]
	ds_read_b128 v[166:169], v160 offset:32768
	ds_read_b128 v[170:173], v160 offset:33792
	ds_read_b128 v[174:177], v160 offset:34816
	ds_read_b128 v[178:181], v160 offset:35840
	ds_read_b128 v[182:185], v160 offset:36864
	ds_read_b128 v[186:189], v160 offset:37888
	ds_read_b128 v[190:193], v160 offset:38912
	ds_read_b128 v[194:197], v160 offset:39936
	global_load_lds_dwordx4 v[198:199], off
	v_lshl_add_u64 v[198:199], s[20:21], 0, v[130:131]
	s_mov_b32 m0, s34
	s_nop 0
	global_load_lds_dwordx4 v[198:199], off
	s_waitcnt lgkmcnt(0)
	s_setprio 1
	s_barrier
	v_mfma_f32_16x16x32_bf16 v[124:127], v[144:147], v[166:169], v[124:127]
	v_mfma_f32_16x16x32_bf16 v[120:123], v[152:155], v[166:169], v[120:123]
	v_mfma_f32_16x16x32_bf16 v[116:119], v[144:147], v[174:177], v[116:119]
	v_mfma_f32_16x16x32_bf16 v[112:115], v[152:155], v[174:177], v[112:115]
	v_mfma_f32_16x16x32_bf16 v[104:107], v[144:147], v[182:185], v[104:107]
	v_mfma_f32_16x16x32_bf16 v[96:99], v[152:155], v[182:185], v[96:99]
	v_mfma_f32_16x16x32_bf16 v[88:91], v[144:147], v[190:193], v[88:91]
	v_mfma_f32_16x16x32_bf16 v[80:83], v[152:155], v[190:193], v[80:83]
	v_mfma_f32_16x16x32_bf16 v[124:127], v[148:151], v[170:173], v[124:127]
	v_mfma_f32_16x16x32_bf16 v[120:123], v[162:165], v[170:173], v[120:123]
	v_mfma_f32_16x16x32_bf16 v[116:119], v[148:151], v[178:181], v[116:119]
	v_mfma_f32_16x16x32_bf16 v[112:115], v[162:165], v[178:181], v[112:115]
	v_mfma_f32_16x16x32_bf16 v[104:107], v[148:151], v[186:189], v[104:107]
	v_mfma_f32_16x16x32_bf16 v[96:99], v[162:165], v[186:189], v[96:99]
	v_mfma_f32_16x16x32_bf16 v[88:91], v[148:151], v[194:197], v[88:91]
	v_mfma_f32_16x16x32_bf16 v[80:83], v[162:165], v[194:197], v[80:83]
	s_barrier
	s_setprio 0
	s_add_i32 s20, 0, 0x1c000
	s_add_i32 s21, s48, s28
	v_add_u32_e32 v210, s20, v157
	v_lshl_add_u64 v[214:215], v[214:215], 0, s[8:9]
	s_mov_b32 m0, s21
	ds_read_b128 v[198:201], v210
	ds_read_b128 v[202:205], v210 offset:1024
	ds_read_b128 v[206:209], v210 offset:2048
	ds_read_b128 v[210:213], v210 offset:3072
	global_load_lds_dwordx4 v[214:215], off
	v_lshl_add_u64 v[214:215], v[216:217], 0, s[8:9]
	s_add_i32 m0, s21, 0x2000
	s_nop 0
	global_load_lds_dwordx4 v[214:215], off
	s_waitcnt lgkmcnt(0)
	s_setprio 1
	s_barrier
	v_mfma_f32_16x16x32_bf16 v[108:111], v[198:201], v[166:169], v[108:111]
	v_mfma_f32_16x16x32_bf16 v[100:103], v[206:209], v[166:169], v[100:103]
	v_mfma_f32_16x16x32_bf16 v[92:95], v[198:201], v[174:177], v[92:95]
	v_mfma_f32_16x16x32_bf16 v[84:87], v[206:209], v[174:177], v[84:87]
	v_mfma_f32_16x16x32_bf16 v[76:79], v[198:201], v[182:185], v[76:79]
	v_mfma_f32_16x16x32_bf16 v[72:75], v[206:209], v[182:185], v[72:75]
	v_mfma_f32_16x16x32_bf16 v[68:71], v[198:201], v[190:193], v[68:71]
	v_mfma_f32_16x16x32_bf16 v[64:67], v[206:209], v[190:193], v[64:67]
	v_mfma_f32_16x16x32_bf16 v[108:111], v[202:205], v[170:173], v[108:111]
	v_mfma_f32_16x16x32_bf16 v[100:103], v[210:213], v[170:173], v[100:103]
	v_mfma_f32_16x16x32_bf16 v[92:95], v[202:205], v[178:181], v[92:95]
	v_mfma_f32_16x16x32_bf16 v[84:87], v[210:213], v[178:181], v[84:87]
	v_mfma_f32_16x16x32_bf16 v[76:79], v[202:205], v[186:189], v[76:79]
	v_mfma_f32_16x16x32_bf16 v[72:75], v[210:213], v[186:189], v[72:75]
	v_mfma_f32_16x16x32_bf16 v[68:71], v[202:205], v[194:197], v[68:71]
	v_mfma_f32_16x16x32_bf16 v[64:67], v[210:213], v[194:197], v[64:67]
	s_barrier
	s_setprio 0
	s_mov_b32 m0, s35
	v_lshl_add_u64 v[214:215], v[218:219], 0, s[8:9]
	ds_read_b128 v[166:169], v160 offset:49152
	ds_read_b128 v[170:173], v160 offset:50176
	ds_read_b128 v[174:177], v160 offset:51200
	ds_read_b128 v[178:181], v160 offset:52224
	ds_read_b128 v[182:185], v160 offset:53248
	ds_read_b128 v[186:189], v160 offset:54272
	ds_read_b128 v[190:193], v160 offset:55296
	ds_read_b128 v[194:197], v160 offset:56320
	global_load_lds_dwordx4 v[214:215], off
	v_lshl_add_u64 v[214:215], v[220:221], 0, s[8:9]
	s_mov_b32 m0, s36
	s_nop 0
	global_load_lds_dwordx4 v[214:215], off
	s_waitcnt vmcnt(10)
	s_waitcnt lgkmcnt(0)
	s_setprio 1
	s_barrier
; #define PG8_STAGE(bufoff, gbase, voff) do { _Pragma("unroll") for (int _i = 0; _i < 2; ++_i) \
;     __builtin_amdgcn_global_load_lds((const unsigned*)((const char*)(gbase) + (voff)[_i]), (LAS unsigned*)(lds + (bufoff) + ldsw + _i * 8192), 16, 0, 0); } while (0)
; #define PG8_MMA(ai, bj, At, Bt) do { __builtin_amdgcn_s_setprio(1); _Pragma("unroll") for (int m = 0; m < 4; ++m) _Pragma("unroll") for (int n = 0; n < 2; ++n) _Pragma("unroll") for (int k = 0; k < 2; ++k) \
;     acc[ai][bj][m][n] = __builtin_amdgcn_mfma_f32_16x16x32_bf16(Bt[n][k], At[m][k], acc[ai][bj][m][n], 0, 0, 0); __builtin_amdgcn_s_setprio(0); } while (0)
; #define PG8_WAIT_V(n) asm volatile("s_waitcnt vmcnt(" #n ")" ::: "memory")
; #define PG8_WAIT_L(n) asm volatile("s_waitcnt lgkmcnt(" #n ")" ::: "memory")
; #define PG8_BAR __builtin_amdgcn_s_barrier()
; #define PG8_SCHED __builtin_amdgcn_sched_barrier(0)
;   DI void operator()(const f32x4 (&acc)[2][2][4][2], const Unit& u, int wr, int wc, int fr, int fq) const {
;     const int row0 = u.pm * BM + wr * 64 + fr, col0 = u.pn * BM + wc * 32 + 8 * fq;
; #pragma unroll
;     for (int ai = 0; ai < 2; ++ai) {
;       f32x4 bv[4][2][2];
; #pragma unroll
;       for (int m = 0; m < 4; ++m)
; #pragma unroll
;         for (int bj = 0; bj < 2; ++bj) {
;           const float* bp = base + (size_t)(row0 + ai * HALF + m * 16) * 2048 + col0 + bj * HALF;
;           bv[m][bj][0] = *(const f32x4*)bp; bv[m][bj][1] = *(const f32x4*)(bp + 4);
;         }
; template <class Epi, class Sched = StaticOrder>
; DI void gemm_phase(LAS unsigned char* lds, const Gemm g, const Sched& S, const Epi& E) {
;     ...
;       PG8_BAR; PG8_WAIT_L(0); PG8_MMA(1, 0, At, B0); PG8_BAR; PG8_SCHED;
;       PG8_STAGE(PG8_SB(1, 1), b3 + hstep, voffB);
;       PG8_WAIT_V(6); PG8_BAR; PG8_MMA(1, 1, At, B1); PG8_BAR;
;     }
	v_mfma_f32_16x16x32_bf16 v[60:63], v[144:147], v[166:169], v[60:63]
	v_mfma_f32_16x16x32_bf16 v[56:59], v[152:155], v[166:169], v[56:59]
	v_mfma_f32_16x16x32_bf16 v[52:55], v[144:147], v[174:177], v[52:55]
	v_mfma_f32_16x16x32_bf16 v[44:47], v[152:155], v[174:177], v[44:47]
	v_mfma_f32_16x16x32_bf16 v[36:39], v[144:147], v[182:185], v[36:39]
	v_mfma_f32_16x16x32_bf16 v[28:31], v[152:155], v[182:185], v[28:31]
	v_mfma_f32_16x16x32_bf16 v[20:23], v[144:147], v[190:193], v[20:23]
	v_mfma_f32_16x16x32_bf16 v[12:15], v[152:155], v[190:193], v[12:15]
	v_mfma_f32_16x16x32_bf16 v[60:63], v[148:151], v[170:173], v[60:63]
	v_mfma_f32_16x16x32_bf16 v[56:59], v[162:165], v[170:173], v[56:59]
	v_mfma_f32_16x16x32_bf16 v[52:55], v[148:151], v[178:181], v[52:55]
	v_mfma_f32_16x16x32_bf16 v[44:47], v[162:165], v[178:181], v[44:47]
	v_mfma_f32_16x16x32_bf16 v[36:39], v[148:151], v[186:189], v[36:39]
	v_mfma_f32_16x16x32_bf16 v[28:31], v[162:165], v[186:189], v[28:31]
	v_mfma_f32_16x16x32_bf16 v[20:23], v[148:151], v[194:197], v[20:23]
	v_mfma_f32_16x16x32_bf16 v[12:15], v[162:165], v[194:197], v[12:15]
	s_barrier
	s_setprio 0
	s_add_u32 s18, s18, 0x160080
	s_addc_u32 s19, s19, 0
	s_add_i32 s20, s20, s28
	v_lshl_add_u64 v[144:145], s[18:19], 0, v[132:133]
	s_mov_b32 m0, s20
	s_nop 0
	global_load_lds_dwordx4 v[144:145], off
	v_lshl_add_u64 v[144:145], s[18:19], 0, v[128:129]
	s_add_i32 m0, s20, 0x2000
	s_nop 0
	global_load_lds_dwordx4 v[144:145], off
	ds_read_b128 v[144:147], v159
	ds_read_b128 v[148:151], v159 offset:1024
	ds_read_b128 v[152:155], v159 offset:2048
	ds_read_b128 v[162:165], v159 offset:3072
	s_waitcnt vmcnt(6)
	s_setprio 1
	s_barrier
	v_mfma_f32_16x16x32_bf16 v[48:51], v[198:201], v[166:169], v[48:51]
	v_mfma_f32_16x16x32_bf16 v[40:43], v[206:209], v[166:169], v[40:43]
	v_mfma_f32_16x16x32_bf16 v[32:35], v[198:201], v[174:177], v[32:35]
	v_mfma_f32_16x16x32_bf16 v[24:27], v[206:209], v[174:177], v[24:27]
	v_mfma_f32_16x16x32_bf16 v[16:19], v[198:201], v[182:185], v[16:19]
	v_mfma_f32_16x16x32_bf16 v[8:11], v[206:209], v[182:185], v[8:11]
	v_mfma_f32_16x16x32_bf16 v[4:7], v[198:201], v[190:193], v[4:7]
	v_mfma_f32_16x16x32_bf16 v[0:3], v[206:209], v[190:193], v[0:3]
	v_mfma_f32_16x16x32_bf16 v[48:51], v[202:205], v[170:173], v[48:51]
	v_mfma_f32_16x16x32_bf16 v[40:43], v[210:213], v[170:173], v[40:43]
	v_mfma_f32_16x16x32_bf16 v[32:35], v[202:205], v[178:181], v[32:35]
	v_mfma_f32_16x16x32_bf16 v[24:27], v[210:213], v[178:181], v[24:27]
	v_mfma_f32_16x16x32_bf16 v[16:19], v[202:205], v[186:189], v[16:19]
	v_mfma_f32_16x16x32_bf16 v[8:11], v[210:213], v[186:189], v[8:11]
	v_mfma_f32_16x16x32_bf16 v[4:7], v[202:205], v[194:197], v[4:7]
	v_mfma_f32_16x16x32_bf16 v[0:3], v[210:213], v[194:197], v[0:3]
	s_add_i32 s47, s47, 2
	s_add_u32 s16, s16, 0x100
	s_addc_u32 s17, s17, 0
	s_add_u32 s45, s45, 0x100
	s_addc_u32 s46, s46, 0
	s_cmpk_gt_u32 s47, 0x55
	s_barrier
	s_setprio 0
	s_cbranch_scc0 .LBB0_1424
	s_waitcnt lgkmcnt(0)
	v_lshl_or_b32 v144, s44, 8, v158
	v_lshl_add_u32 v154, s43, 8, v156
	v_ashrrev_i32_e32 v145, 31, v144
	v_lshlrev_b64 v[144:145], 2, v[144:145]
	v_ashrrev_i32_e32 v155, 31, v154
	v_lshl_add_u64 v[146:147], s[54:55], 0, v[144:145]
	v_lshlrev_b64 v[148:149], 13, v[154:155]
	v_or_b32_e32 v174, 16, v154
	v_lshl_add_u64 v[170:171], v[146:147], 0, v[148:149]
	v_ashrrev_i32_e32 v175, 31, v174
	global_load_dwordx4 v[150:153], v[170:171], off offset:16
	global_load_dwordx4 v[162:165], v[170:171], off
	global_load_dwordx4 v[166:169], v[170:171], off offset:528
	s_nop 0
	global_load_dwordx4 v[170:173], v[170:171], off offset:512
	v_lshlrev_b64 v[222:223], 13, v[174:175]
	v_or_b32_e32 v190, 32, v154
	v_lshl_add_u64 v[186:187], v[146:147], 0, v[222:223]
	v_ashrrev_i32_e32 v191, 31, v190
	global_load_dwordx4 v[174:177], v[186:187], off offset:16
	global_load_dwordx4 v[178:181], v[186:187], off
	global_load_dwordx4 v[182:185], v[186:187], off offset:528
	s_nop 0
	global_load_dwordx4 v[186:189], v[186:187], off offset:512
	v_lshlrev_b64 v[224:225], 13, v[190:191]
	v_or_b32_e32 v154, 48, v154
	v_lshl_add_u64 v[202:203], v[146:147], 0, v[224:225]
	v_ashrrev_i32_e32 v155, 31, v154
	global_load_dwordx4 v[190:193], v[202:203], off offset:16
	global_load_dwordx4 v[194:197], v[202:203], off
	global_load_dwordx4 v[198:201], v[202:203], off offset:528
	s_nop 0
	global_load_dwordx4 v[202:205], v[202:203], off offset:512
	v_lshlrev_b64 v[154:155], 13, v[154:155]
	v_lshl_add_u64 v[218:219], v[146:147], 0, v[154:155]
	global_load_dwordx4 v[206:209], v[218:219], off offset:16
	global_load_dwordx4 v[210:213], v[218:219], off
	global_load_dwordx4 v[214:217], v[218:219], off offset:528
	s_nop 0
	global_load_dwordx4 v[218:221], v[218:219], off offset:512
	s_and_b64 vcc, exec, s[0:1]
	s_mov_b32 s44, s41
	s_mov_b32 s43, s42
	s_mov_b64 s[18:19], s[4:5]
	s_mov_b64 s[16:17], s[2:3]
	s_waitcnt vmcnt(0)
; #define PG8_WAIT_V(n) asm volatile("s_waitcnt vmcnt(" #n ")" ::: "memory")
; #define PG8_BAR __builtin_amdgcn_s_barrier()
;   DI void operator()(const f32x4 (&acc)[2][2][4][2], const Unit& u, int wr, int wc, int fr, int fq) const {
;     const int row0 = u.pm * BM + wr * 64 + fr, col0 = u.pn * BM + wc * 32 + 8 * fq;
; #pragma unroll
;     for (int ai = 0; ai < 2; ++ai) {
;       f32x4 bv[4][2][2];
; #pragma unroll
;       for (int m = 0; m < 4; ++m)
; #pragma unroll
;         for (int bj = 0; bj < 2; ++bj) {
;           const float* bp = base + (size_t)(row0 + ai * HALF + m * 16) * 2048 + col0 + bj * HALF;
;           bv[m][bj][0] = *(const f32x4*)bp; bv[m][bj][1] = *(const f32x4*)(bp + 4);
;         }
; #pragma unroll
;       for (int m = 0; m < 4; ++m) {
;         const int row = row0 + ai * HALF + m * 16;
;         const size_t off = (size_t)row * 2048 + col0;
;         float ss = 0.f;
; #pragma unroll
;         for (int bj = 0; bj < 2; ++bj) {
;           const f32x4 v0 = acc[ai][bj][m][0] + bv[m][bj][0], v1 = acc[ai][bj][m][1] + bv[m][bj][1];
;           *(f32x4*)(C + off + bj * HALF) = v0; *(f32x4*)(C + off + bj * HALF + 4) = v1;
; template <class Epi, class Sched = StaticOrder>
; DI void gemm_phase(LAS unsigned char* lds, const Gemm g, const Sched& S, const Epi& E) {
;     ...
;     E(acc, cur, wr, wc, fr, fq);
;     if (!has_next) break;
; #pragma unroll
;     for (int a = 0; a < 2; ++a)
; #pragma unroll
;       for (int b = 0; b < 2; ++b)
; #pragma unroll
;         for (int m = 0; m < 4; ++m)
; #pragma unroll
;           for (int n = 0; n < 2; ++n) acc[a][b][m][n] = (f32x4){0.f, 0.f, 0.f, 0.f};
;     cur = nxt; cA = nA; cB = nB; ++ui;
;   }
;   PG8_WAIT_V(0);
;   if (wr == 0) PG8_BAR;
;   PG8_BAR;
	v_pk_add_f32 v[120:121], v[120:121], v[150:151]
	v_lshl_add_u64 v[150:151], s[54:55], 0, v[148:149]
	v_pk_add_f32 v[126:127], v[126:127], v[164:165]
	v_pk_add_f32 v[124:125], v[124:125], v[162:163]
	v_lshl_add_u64 v[150:151], v[150:151], 0, v[144:145]
	v_pk_add_f32 v[110:111], v[110:111], v[172:173]
	v_pk_add_f32 v[108:109], v[108:109], v[170:171]
	v_pk_add_f32 v[122:123], v[122:123], v[152:153]
	global_store_dwordx4 v[150:151], v[124:127], off
	global_store_dwordx4 v[150:151], v[120:123], off offset:16
	v_pk_add_f32 v[102:103], v[102:103], v[168:169]
	v_pk_add_f32 v[100:101], v[100:101], v[166:167]
	global_store_dwordx4 v[150:151], v[108:111], off offset:512
	global_store_dwordx4 v[150:151], v[100:103], off offset:528
	v_pk_add_f32 v[94:95], v[94:95], v[188:189]
	v_pk_add_f32 v[108:109], v[112:113], v[174:175]
	v_lshl_add_u64 v[112:113], s[54:55], 0, v[222:223]
	v_pk_add_f32 v[102:103], v[118:119], v[180:181]
	v_pk_add_f32 v[100:101], v[116:117], v[178:179]
	v_lshl_add_u64 v[112:113], v[112:113], 0, v[144:145]
	v_pk_add_f32 v[92:93], v[92:93], v[186:187]
	v_pk_add_f32 v[110:111], v[114:115], v[176:177]
	global_store_dwordx4 v[112:113], v[100:103], off
	global_store_dwordx4 v[112:113], v[108:111], off offset:16
	v_pk_add_f32 v[86:87], v[86:87], v[184:185]
	v_pk_add_f32 v[84:85], v[84:85], v[182:183]
	global_store_dwordx4 v[112:113], v[92:95], off offset:512
	global_store_dwordx4 v[112:113], v[84:87], off offset:528
	v_pk_add_f32 v[78:79], v[78:79], v[204:205]
	v_pk_add_f32 v[92:93], v[96:97], v[190:191]
	v_lshl_add_u64 v[96:97], s[54:55], 0, v[224:225]
	v_pk_add_f32 v[86:87], v[106:107], v[196:197]
	v_pk_add_f32 v[84:85], v[104:105], v[194:195]
	v_lshl_add_u64 v[96:97], v[96:97], 0, v[144:145]
	v_pk_add_f32 v[76:77], v[76:77], v[202:203]
	v_pk_add_f32 v[94:95], v[98:99], v[192:193]
	global_store_dwordx4 v[96:97], v[84:87], off
	global_store_dwordx4 v[96:97], v[92:95], off offset:16
	v_pk_add_f32 v[74:75], v[74:75], v[200:201]
	v_pk_add_f32 v[72:73], v[72:73], v[198:199]
	global_store_dwordx4 v[96:97], v[76:79], off offset:512
	global_store_dwordx4 v[96:97], v[72:75], off offset:528
	v_pk_add_f32 v[70:71], v[70:71], v[220:221]
	v_pk_add_f32 v[76:77], v[80:81], v[206:207]
	v_lshl_add_u64 v[80:81], s[54:55], 0, v[154:155]
	v_pk_add_f32 v[74:75], v[90:91], v[212:213]
	v_pk_add_f32 v[72:73], v[88:89], v[210:211]
	v_lshl_add_u64 v[80:81], v[80:81], 0, v[144:145]
	v_pk_add_f32 v[68:69], v[68:69], v[218:219]
	v_pk_add_f32 v[64:65], v[64:65], v[214:215]
	v_lshl_add_u64 v[154:155], v[148:149], 0, s[10:11]
	v_pk_add_f32 v[78:79], v[82:83], v[208:209]
	global_store_dwordx4 v[80:81], v[72:75], off
	global_store_dwordx4 v[80:81], v[76:79], off offset:16
	v_pk_add_f32 v[66:67], v[66:67], v[216:217]
	global_store_dwordx4 v[80:81], v[68:71], off offset:512
	global_store_dwordx4 v[80:81], v[64:67], off offset:528
	v_lshl_add_u64 v[152:153], v[148:149], 0, s[12:13]
	v_lshl_add_u64 v[150:151], v[148:149], 0, s[14:15]
	v_lshl_add_u64 v[64:65], v[146:147], 0, v[154:155]
	global_load_dwordx4 v[108:111], v[64:65], off offset:16
	global_load_dwordx4 v[120:123], v[64:65], off
	global_load_dwordx4 v[92:95], v[64:65], off offset:528
	global_load_dwordx4 v[100:103], v[64:65], off offset:512
	v_lshl_add_u64 v[64:65], v[146:147], 0, v[152:153]
	global_load_dwordx4 v[88:91], v[64:65], off offset:16
	global_load_dwordx4 v[96:99], v[64:65], off
	global_load_dwordx4 v[76:79], v[64:65], off offset:528
	global_load_dwordx4 v[84:87], v[64:65], off offset:512
	v_lshl_add_u64 v[68:69], v[146:147], 0, v[150:151]
	global_load_dwordx4 v[72:75], v[68:69], off offset:16
	global_load_dwordx4 v[80:83], v[68:69], off
	global_load_dwordx4 v[64:67], v[68:69], off offset:528
	s_nop 0
	global_load_dwordx4 v[68:71], v[68:69], off offset:512
	v_lshl_add_u64 v[148:149], v[148:149], 0, s[6:7]
	v_lshl_add_u64 v[112:113], v[146:147], 0, v[148:149]
	global_load_dwordx4 v[116:119], v[112:113], off offset:16
	global_load_dwordx4 v[124:127], v[112:113], off
	global_load_dwordx4 v[104:107], v[112:113], off offset:528
	s_nop 0
	global_load_dwordx4 v[112:115], v[112:113], off offset:512
	s_waitcnt vmcnt(0)
	v_pk_add_f32 v[56:57], v[56:57], v[108:109]
	v_lshl_add_u64 v[108:109], s[54:55], 0, v[154:155]
	v_pk_add_f32 v[62:63], v[62:63], v[122:123]
	v_pk_add_f32 v[60:61], v[60:61], v[120:121]
	v_lshl_add_u64 v[108:109], v[108:109], 0, v[144:145]
	v_pk_add_f32 v[50:51], v[50:51], v[102:103]
	v_pk_add_f32 v[48:49], v[48:49], v[100:101]
	v_pk_add_f32 v[58:59], v[58:59], v[110:111]
	global_store_dwordx4 v[108:109], v[60:63], off
	global_store_dwordx4 v[108:109], v[56:59], off offset:16
	v_pk_add_f32 v[42:43], v[42:43], v[94:95]
	v_pk_add_f32 v[40:41], v[40:41], v[92:93]
	global_store_dwordx4 v[108:109], v[48:51], off offset:512
	global_store_dwordx4 v[108:109], v[40:43], off offset:528
	v_pk_add_f32 v[34:35], v[34:35], v[86:87]
	v_lshl_add_u64 v[48:49], s[54:55], 0, v[152:153]
	v_pk_add_f32 v[42:43], v[54:55], v[98:99]
	v_pk_add_f32 v[40:41], v[52:53], v[96:97]
	v_lshl_add_u64 v[48:49], v[48:49], 0, v[144:145]
	v_pk_add_f32 v[32:33], v[32:33], v[84:85]
	v_pk_add_f32 v[46:47], v[46:47], v[90:91]
	v_pk_add_f32 v[44:45], v[44:45], v[88:89]
	global_store_dwordx4 v[48:49], v[40:43], off
	global_store_dwordx4 v[48:49], v[44:47], off offset:16
	v_pk_add_f32 v[26:27], v[26:27], v[78:79]
	v_pk_add_f32 v[24:25], v[24:25], v[76:77]
	global_store_dwordx4 v[48:49], v[32:35], off offset:512
	global_store_dwordx4 v[48:49], v[24:27], off offset:528
	v_pk_add_f32 v[18:19], v[18:19], v[70:71]
	v_lshl_add_u64 v[32:33], s[54:55], 0, v[150:151]
	v_pk_add_f32 v[26:27], v[38:39], v[82:83]
	v_pk_add_f32 v[24:25], v[36:37], v[80:81]
	v_lshl_add_u64 v[32:33], v[32:33], 0, v[144:145]
	v_pk_add_f32 v[16:17], v[16:17], v[68:69]
	v_pk_add_f32 v[30:31], v[30:31], v[74:75]
	v_pk_add_f32 v[28:29], v[28:29], v[72:73]
	global_store_dwordx4 v[32:33], v[24:27], off
	global_store_dwordx4 v[32:33], v[28:31], off offset:16
	v_pk_add_f32 v[10:11], v[10:11], v[66:67]
	v_pk_add_f32 v[8:9], v[8:9], v[64:65]
	global_store_dwordx4 v[32:33], v[16:19], off offset:512
	global_store_dwordx4 v[32:33], v[8:11], off offset:528
	v_pk_add_f32 v[6:7], v[6:7], v[114:115]
	v_lshl_add_u64 v[16:17], s[54:55], 0, v[148:149]
	v_pk_add_f32 v[10:11], v[22:23], v[126:127]
	v_pk_add_f32 v[8:9], v[20:21], v[124:125]
	v_lshl_add_u64 v[16:17], v[16:17], 0, v[144:145]
	v_pk_add_f32 v[4:5], v[4:5], v[112:113]
	v_pk_add_f32 v[14:15], v[14:15], v[118:119]
	v_pk_add_f32 v[12:13], v[12:13], v[116:117]
	global_store_dwordx4 v[16:17], v[8:11], off
	global_store_dwordx4 v[16:17], v[12:15], off offset:16
	v_pk_add_f32 v[2:3], v[2:3], v[106:107]
	v_pk_add_f32 v[0:1], v[0:1], v[104:105]
	global_store_dwordx4 v[16:17], v[4:7], off offset:512
	global_store_dwordx4 v[16:17], v[0:3], off offset:528
	s_cbranch_vccz .LBB0_1417
	s_waitcnt vmcnt(0)
	s_cmpk_gt_u32 s23, 0xff
	s_cbranch_scc1 .LBB0_1428
	s_barrier
